# same 16-byte store pairing also in the k_nope tile epilogues (O3a/O3b); scratch registers found by liveness in the straight-line tile code
# speedup vs baseline: 1.0195x; 1.0070x over previous
; template <int N> DI void wait_vm() { asm volatile("s_waitcnt vmcnt(%0)" ::"n"(N) : "memory"); }
; template <int BM, class Epi>
; DI void gemm_dma(const u16* __restrict__ X, long ldx, const u16* __restrict__ W, long ldw, int K, char* smem,
;                  int m0, int n0, const Epi& epi) {
;     ...
;   do {
;     if (kt + D - 2 < nk) wait_vm<PW * (D - 2)>(); else wait_vm<0>();
;     __syncthreads();
;     if (kt + D - 1 < nk) GD_ISSUE(nxt)
;     nxt = (nxt + 1 == D) ? 0 : nxt + 1;
;     const char* base = smem + cur * STG;
;     cur = (cur + 1 == D) ? 0 : cur + 1;
;     bf16x8 xf[MT];
; #pragma unroll
;     for (int i = 0; i < MT; ++i) xf[i] = *(const bf16x8*)(base + (xrow0 + i * 16) * 64 + rd);
; #pragma unroll
;     for (int nh = 0; nh < NT / 4; ++nh) {
;       bf16x8 wf[4];
; #pragma unroll
;       for (int i = 0; i < 4; ++i) wf[i] = *(const bf16x8*)(base + BM * 64 + (wrow0 + (nh * 4 + i) * 16) * 64 + rd);
; #pragma unroll
;       for (int i = 0; i < 4; ++i)
; #pragma unroll
;         for (int mt = 0; mt < MT; ++mt)
;           acc[nh * 4 + i][mt] = __builtin_amdgcn_mfma_f32_16x16x32_bf16(wf[i], xf[mt], acc[nh * 4 + i][mt], 0, 0, 0);
;     }
;   } while (++kt < nk);
;     ...
;   epi.run(acc, m0 + xrow0 + lr, n0 + wrow0 + 4 * g);
.LBB0_32:
	s_mul_i32 s12, s10, 0x6000
	v_lshl_add_u64 v[196:197], v[130:131], 0, s[40:41]
	s_waitcnt vmcnt(6)
	s_barrier
	s_mul_i32 s98, s11, 0x6000
	v_or_b32_e32 v137, s98, v134
	v_add_u32_e32 v150, v137, v136
	ds_read_b128 v[138:141], v150
	ds_read_b128 v[142:145], v150 offset:1024
	ds_read_b128 v[146:149], v150 offset:2048
	ds_read_b128 v[150:153], v150 offset:3072
	ds_read_b128 v[154:157], v137 offset:16384
	ds_read_b128 v[158:161], v137 offset:17408
	ds_read_b128 v[162:165], v137 offset:18432
	ds_read_b128 v[166:169], v137 offset:19456
	ds_read_b128 v[226:229], v137 offset:20480
	ds_read_b128 v[230:233], v137 offset:21504
	ds_read_b128 v[234:237], v137 offset:22528
	ds_read_b128 v[238:241], v137 offset:23552
	s_add_i32 s13, s12, s8
	s_mov_b32 m0, s13
	s_nop 0
	global_load_lds_dwordx4 v[196:197], off
	v_lshl_add_u64 v[224:225], v[196:197], 0, s[16:17]
	s_add_i32 s14, s13, 0x400
	s_mov_b32 m0, s14
	s_nop 0
	global_load_lds_dwordx4 v[224:225], off
	v_lshl_add_u64 v[224:225], v[196:197], 0, s[18:19]
	s_add_i32 s14, s13, 0x800
	s_mov_b32 m0, s14
	s_nop 0
	global_load_lds_dwordx4 v[224:225], off
	v_lshl_add_u64 v[196:197], v[196:197], 0, s[20:21]
	s_addk_i32 s13, 0xc00
	s_mov_b32 m0, s13
	s_nop 0
	global_load_lds_dwordx4 v[196:197], off
	s_add_i32 s12, s12, s9
	v_lshl_add_u64 v[194:195], v[128:129], 0, s[40:41]
	s_mov_b32 m0, s12
	s_nop 0
	global_load_lds_dwordx4 v[194:195], off
	s_addk_i32 s12, 0x400
	v_lshl_add_u64 v[194:195], v[194:195], 0, s[16:17]
	s_mov_b32 m0, s12
	s_nop 0
	global_load_lds_dwordx4 v[194:195], off
	s_waitcnt lgkmcnt(7)
	v_mfma_f32_16x16x32_bf16 v[124:127], v[154:157], v[138:141], v[124:127]
	s_add_i32 s10, s10, 1
	s_add_i32 s11, s11, 1
	s_cmp_lg_u32 s10, 3
	v_mfma_f32_16x16x32_bf16 v[120:123], v[154:157], v[142:145], v[120:123]
	s_cselect_b32 s10, s10, 0
	s_cmp_lg_u32 s11, 3
	s_cselect_b32 s11, s11, 0
	v_mfma_f32_16x16x32_bf16 v[116:119], v[154:157], v[146:149], v[116:119]
	s_add_u32 s40, s40, 64
	s_addc_u32 s41, s41, 0
	s_cmpk_lg_i32 s40, 0x780
	v_mfma_f32_16x16x32_bf16 v[112:115], v[154:157], v[150:153], v[112:115]
	s_waitcnt lgkmcnt(6)
	v_mfma_f32_16x16x32_bf16 v[108:111], v[158:161], v[138:141], v[108:111]
	v_mfma_f32_16x16x32_bf16 v[104:107], v[158:161], v[142:145], v[104:107]
	v_mfma_f32_16x16x32_bf16 v[100:103], v[158:161], v[146:149], v[100:103]
	v_mfma_f32_16x16x32_bf16 v[96:99], v[158:161], v[150:153], v[96:99]
	s_waitcnt lgkmcnt(5)
	v_mfma_f32_16x16x32_bf16 v[92:95], v[162:165], v[138:141], v[92:95]
	v_mfma_f32_16x16x32_bf16 v[88:91], v[162:165], v[142:145], v[88:91]
	v_mfma_f32_16x16x32_bf16 v[84:87], v[162:165], v[146:149], v[84:87]
	v_mfma_f32_16x16x32_bf16 v[80:83], v[162:165], v[150:153], v[80:83]
	s_waitcnt lgkmcnt(4)
	v_mfma_f32_16x16x32_bf16 v[76:79], v[166:169], v[138:141], v[76:79]
	v_mfma_f32_16x16x32_bf16 v[72:75], v[166:169], v[142:145], v[72:75]
	v_mfma_f32_16x16x32_bf16 v[68:71], v[166:169], v[146:149], v[68:71]
	v_mfma_f32_16x16x32_bf16 v[64:67], v[166:169], v[150:153], v[64:67]
	s_waitcnt lgkmcnt(3)
	v_mfma_f32_16x16x32_bf16 v[60:63], v[226:229], v[138:141], v[60:63]
	v_mfma_f32_16x16x32_bf16 v[56:59], v[226:229], v[142:145], v[56:59]
	v_mfma_f32_16x16x32_bf16 v[52:55], v[226:229], v[146:149], v[52:55]
	v_mfma_f32_16x16x32_bf16 v[48:51], v[226:229], v[150:153], v[48:51]
	s_waitcnt lgkmcnt(2)
	v_mfma_f32_16x16x32_bf16 v[44:47], v[230:233], v[138:141], v[44:47]
	v_mfma_f32_16x16x32_bf16 v[40:43], v[230:233], v[142:145], v[40:43]
	v_mfma_f32_16x16x32_bf16 v[36:39], v[230:233], v[146:149], v[36:39]
	v_mfma_f32_16x16x32_bf16 v[32:35], v[230:233], v[150:153], v[32:35]
	s_waitcnt lgkmcnt(1)
	v_mfma_f32_16x16x32_bf16 v[28:31], v[234:237], v[138:141], v[28:31]
	v_mfma_f32_16x16x32_bf16 v[24:27], v[234:237], v[142:145], v[24:27]
	v_mfma_f32_16x16x32_bf16 v[20:23], v[234:237], v[146:149], v[20:23]
	v_mfma_f32_16x16x32_bf16 v[16:19], v[234:237], v[150:153], v[16:19]
	s_waitcnt lgkmcnt(0)
	v_mfma_f32_16x16x32_bf16 v[12:15], v[238:241], v[138:141], v[12:15]
	v_mfma_f32_16x16x32_bf16 v[8:11], v[238:241], v[142:145], v[8:11]
	v_mfma_f32_16x16x32_bf16 v[4:7], v[238:241], v[146:149], v[4:7]
	v_mfma_f32_16x16x32_bf16 v[0:3], v[238:241], v[150:153], v[0:3]
	s_cbranch_scc1 .LBB0_32
	v_add_u32_e32 v180, v134, v136
	s_waitcnt vmcnt(6)
	s_barrier
	ds_read_b128 v[128:131], v180
	ds_read_b128 v[136:139], v180 offset:1024
	ds_read_b128 v[140:143], v180 offset:2048
	ds_read_b128 v[144:147], v180 offset:3072
	ds_read_b128 v[148:151], v134 offset:16384
	ds_read_b128 v[152:155], v134 offset:17408
	ds_read_b128 v[156:159], v134 offset:18432
	ds_read_b128 v[160:163], v134 offset:19456
	s_waitcnt lgkmcnt(3)
	v_mfma_f32_16x16x32_bf16 v[124:127], v[148:151], v[128:131], v[124:127]
	s_lshl_b32 s7, s7, 8
	v_lshl_or_b32 v182, v132, 3, s7
	v_mfma_f32_16x16x32_bf16 v[120:123], v[148:151], v[136:139], v[120:123]
	v_mfma_f32_16x16x32_bf16 v[116:119], v[148:151], v[140:143], v[116:119]
	v_mfma_f32_16x16x32_bf16 v[112:115], v[148:151], v[144:147], v[112:115]
	s_waitcnt lgkmcnt(2)
	v_mfma_f32_16x16x32_bf16 v[108:111], v[152:155], v[128:131], v[108:111]
	v_mfma_f32_16x16x32_bf16 v[104:107], v[152:155], v[136:139], v[104:107]
	v_mfma_f32_16x16x32_bf16 v[100:103], v[152:155], v[140:143], v[100:103]
	v_mfma_f32_16x16x32_bf16 v[96:99], v[152:155], v[144:147], v[96:99]
	s_waitcnt lgkmcnt(1)
	v_mfma_f32_16x16x32_bf16 v[92:95], v[156:159], v[128:131], v[92:95]
	v_mfma_f32_16x16x32_bf16 v[88:91], v[156:159], v[136:139], v[88:91]
	v_mfma_f32_16x16x32_bf16 v[84:87], v[156:159], v[140:143], v[84:87]
	v_mfma_f32_16x16x32_bf16 v[148:151], v[156:159], v[144:147], v[80:83]
	s_waitcnt lgkmcnt(0)
	v_mfma_f32_16x16x32_bf16 v[76:79], v[160:163], v[128:131], v[76:79]
	v_mfma_f32_16x16x32_bf16 v[152:155], v[160:163], v[136:139], v[72:75]
	v_mfma_f32_16x16x32_bf16 v[68:71], v[160:163], v[140:143], v[68:71]
	v_mfma_f32_16x16x32_bf16 v[156:159], v[160:163], v[144:147], v[64:67]
	s_nop 2
	ds_read_b128 v[64:67], v134 offset:20480
	ds_read_b128 v[72:75], v134 offset:21504
	ds_read_b128 v[80:83], v134 offset:22528
	ds_read_b128 v[160:163], v134 offset:23552
	s_waitcnt vmcnt(0)
	s_waitcnt lgkmcnt(0)
	v_mfma_f32_16x16x32_bf16 v[60:63], v[64:67], v[128:131], v[60:63]
	s_barrier
; template <int BM, class Epi>
; DI void gemm_dma(const u16* __restrict__ X, long ldx, const u16* __restrict__ W, long ldw, int K, char* smem,
;                  int m0, int n0, const Epi& epi) {
;     ...
;     bf16x8 xf[MT];
; #pragma unroll
;     for (int i = 0; i < MT; ++i) xf[i] = *(const bf16x8*)(base + (xrow0 + i * 16) * 64 + rd);
; #pragma unroll
;     for (int nh = 0; nh < NT / 4; ++nh) {
;       bf16x8 wf[4];
; #pragma unroll
;       for (int i = 0; i < 4; ++i) wf[i] = *(const bf16x8*)(base + BM * 64 + (wrow0 + (nh * 4 + i) * 16) * 64 + rd);
; #pragma unroll
;       for (int i = 0; i < 4; ++i)
; #pragma unroll
;         for (int mt = 0; mt < MT; ++mt)
;           acc[nh * 4 + i][mt] = __builtin_amdgcn_mfma_f32_16x16x32_bf16(wf[i], xf[mt], acc[nh * 4 + i][mt], 0, 0, 0);
;     }
	v_mfma_f32_16x16x32_bf16 v[164:167], v[64:67], v[136:139], v[56:59]
	v_mfma_f32_16x16x32_bf16 v[52:55], v[64:67], v[140:143], v[52:55]
	v_mfma_f32_16x16x32_bf16 v[168:171], v[64:67], v[144:147], v[48:51]
	v_mfma_f32_16x16x32_bf16 v[44:47], v[72:75], v[128:131], v[44:47]
	v_mfma_f32_16x16x32_bf16 v[172:175], v[72:75], v[136:139], v[40:43]
	v_mfma_f32_16x16x32_bf16 v[36:39], v[72:75], v[140:143], v[36:39]
	v_mfma_f32_16x16x32_bf16 v[176:179], v[72:75], v[144:147], v[32:35]
	v_mfma_f32_16x16x32_bf16 v[28:31], v[80:83], v[128:131], v[28:31]
	v_mfma_f32_16x16x32_bf16 v[24:27], v[80:83], v[136:139], v[24:27]
	v_mfma_f32_16x16x32_bf16 v[20:23], v[80:83], v[140:143], v[20:23]
	v_mfma_f32_16x16x32_bf16 v[16:19], v[80:83], v[144:147], v[16:19]
	v_mfma_f32_16x16x32_bf16 v[12:15], v[160:163], v[128:131], v[12:15]
	v_mfma_f32_16x16x32_bf16 v[8:11], v[160:163], v[136:139], v[8:11]
	v_mfma_f32_16x16x32_bf16 v[4:7], v[160:163], v[140:143], v[4:7]
	v_mfma_f32_16x16x32_bf16 v[0:3], v[160:163], v[144:147], v[0:3]
	ds_read_b128 v[128:131], v180 offset:24576
	ds_read_b128 v[136:139], v180 offset:25600
	ds_read_b128 v[140:143], v180 offset:26624
	ds_read_b128 v[144:147], v180 offset:27648
	ds_read_b128 v[32:35], v134 offset:40960
	ds_read_b128 v[40:43], v134 offset:41984
	ds_read_b128 v[48:51], v134 offset:43008
	ds_read_b128 v[160:163], v134 offset:44032
	s_waitcnt lgkmcnt(2)
	v_mfma_f32_16x16x32_bf16 v[108:111], v[40:43], v[128:131], v[108:111]
	v_mfma_f32_16x16x32_bf16 v[104:107], v[40:43], v[136:139], v[104:107]
	v_mfma_f32_16x16x32_bf16 v[100:103], v[40:43], v[140:143], v[100:103]
	s_nop 5
	v_cvt_pk_bf16_f32 v108, v108, v109
	v_cvt_pk_bf16_f32 v109, v110, v111
	v_cvt_pk_bf16_f32 v104, v104, v105
	v_mfma_f32_16x16x32_bf16 v[96:99], v[40:43], v[144:147], v[96:99]
	v_cvt_pk_bf16_f32 v105, v106, v107
	v_cvt_pk_bf16_f32 v100, v100, v101
	v_cvt_pk_bf16_f32 v101, v102, v103
	s_waitcnt lgkmcnt(1)
	v_mfma_f32_16x16x32_bf16 v[92:95], v[48:51], v[128:131], v[92:95]
	v_mfma_f32_16x16x32_bf16 v[80:83], v[48:51], v[136:139], v[88:91]
	s_nop 1
	v_cvt_pk_bf16_f32 v96, v96, v97
	v_cvt_pk_bf16_f32 v97, v98, v99
	s_nop 2
	v_cvt_pk_bf16_f32 v92, v92, v93
	v_mfma_f32_16x16x32_bf16 v[72:75], v[48:51], v[140:143], v[84:87]
	v_cvt_pk_bf16_f32 v93, v94, v95
	v_cvt_pk_bf16_f32 v80, v80, v81
	v_cvt_pk_bf16_f32 v81, v82, v83
	v_mfma_f32_16x16x32_bf16 v[64:67], v[48:51], v[144:147], v[148:151]
	s_waitcnt lgkmcnt(0)
	v_mfma_f32_16x16x32_bf16 v[48:51], v[160:163], v[136:139], v[152:155]
	s_nop 1
	v_cvt_pk_bf16_f32 v72, v72, v73
	v_cvt_pk_bf16_f32 v73, v74, v75
	s_nop 1
	v_cvt_pk_bf16_f32 v64, v64, v65
	v_mfma_f32_16x16x32_bf16 v[40:43], v[160:163], v[140:143], v[68:71]
	s_nop 2
	ds_read_b128 v[68:71], v134 offset:45056
	ds_read_b128 v[88:91], v134 offset:46080
	ds_read_b128 v[148:151], v134 offset:47104
	ds_read_b128 v[152:155], v134 offset:48128
	v_cvt_pk_bf16_f32 v65, v66, v67
	v_cvt_pk_bf16_f32 v48, v48, v49
	v_mfma_f32_16x16x32_bf16 v[124:127], v[32:35], v[128:131], v[124:127]
	v_cvt_pk_bf16_f32 v49, v50, v51
	v_cvt_pk_bf16_f32 v40, v40, v41
	v_cvt_pk_bf16_f32 v41, v42, v43
	v_mfma_f32_16x16x32_bf16 v[120:123], v[32:35], v[136:139], v[120:123]
	v_mfma_f32_16x16x32_bf16 v[116:119], v[32:35], v[140:143], v[116:119]
	v_mfma_f32_16x16x32_bf16 v[112:115], v[32:35], v[144:147], v[112:115]
	s_nop 5
	v_cvt_pk_bf16_f32 v120, v120, v121
	v_cvt_pk_bf16_f32 v121, v122, v123
	v_cvt_pk_bf16_f32 v116, v116, v117
	v_mfma_f32_16x16x32_bf16 v[56:59], v[160:163], v[128:131], v[76:79]
	v_cvt_pk_bf16_f32 v117, v118, v119
	v_cvt_pk_bf16_f32 v112, v112, v113
	v_cvt_pk_bf16_f32 v113, v114, v115
	v_mfma_f32_16x16x32_bf16 v[32:35], v[160:163], v[144:147], v[156:159]
	s_waitcnt lgkmcnt(3)
	v_mfma_f32_16x16x32_bf16 v[156:159], v[68:71], v[128:131], v[60:63]
	s_nop 1
	v_cvt_pk_bf16_f32 v56, v56, v57
	s_nop 2
	v_cvt_pk_bf16_f32 v32, v32, v33
	v_cvt_pk_bf16_f32 v33, v34, v35
	v_mfma_f32_16x16x32_bf16 v[76:79], v[68:71], v[140:143], v[52:55]
	v_cvt_pk_bf16_f32 v57, v58, v59
	s_waitcnt lgkmcnt(2)
	v_mfma_f32_16x16x32_bf16 v[60:63], v[88:91], v[128:131], v[44:47]
	v_mfma_f32_16x16x32_bf16 v[52:55], v[88:91], v[136:139], v[172:175]
	v_mfma_f32_16x16x32_bf16 v[44:47], v[88:91], v[140:143], v[36:39]
	v_mfma_f32_16x16x32_bf16 v[36:39], v[88:91], v[144:147], v[176:179]
	v_lshl_add_u32 v88, s38, 8, v135
	v_cvt_pk_bf16_f32 v90, v124, v125
	v_cvt_pk_bf16_f32 v91, v126, v127
	s_waitcnt lgkmcnt(1)
	v_mfma_f32_16x16x32_bf16 v[28:31], v[148:151], v[128:131], v[28:31]
	s_waitcnt lgkmcnt(0)
; DI void st_bf4(u16* p, float a, float b, float c, float d) { *(uint2*)p = make_uint2(pk2(a, b), pk2(c, d)); }
;   template <int NT, int MT> DI void run(f32x4 (&acc)[NT][MT], int mb, int nb) const {
; #pragma unroll
;     for (int nt = 0; nt < NT; ++nt)
; #pragma unroll
;       for (int mt = 0; mt < MT; ++mt) {
;         f32x4 v = acc[nt][mt];
;         st_bf4(C + (size_t)(mb + mt * 16) * ldc + nb + nt * 16, v[0], v[1], v[2], v[3]);
;       }
;   }
	v_mfma_f32_16x16x32_bf16 v[12:15], v[152:155], v[128:131], v[12:15]
	v_or_b32_e32 v128, v88, v133
	v_ashrrev_i32_e32 v129, 31, v128
	v_lshlrev_b64 v[88:89], 11, v[128:129]
	v_lshl_add_u64 v[88:89], s[92:93], 0, v[88:89]
	v_bfe_u32 v160, v185, 4, 1
	v_mad_u32_u24 v182, v160, 24, v182
	v_lshl_add_u64 v[88:89], v[88:89], 0, v[182:183]
	v_mov_b32_e32 v160, v90
	v_mov_b32_e32 v161, v91
	v_or_b32_e32 v90, 16, v128
	v_ashrrev_i32_e32 v91, 31, v90
	v_lshlrev_b64 v[90:91], 11, v[90:91]
	v_lshl_add_u64 v[90:91], s[92:93], 0, v[90:91]
	v_lshl_add_u64 v[90:91], v[90:91], 0, v[182:183]
	v_mov_b32_e32 v172, v120
	v_mov_b32_e32 v173, v121
	v_or_b32_e32 v120, 32, v128
	v_ashrrev_i32_e32 v121, 31, v120
	v_lshlrev_b64 v[120:121], 11, v[120:121]
	v_lshl_add_u64 v[120:121], s[92:93], 0, v[120:121]
	v_lshl_add_u64 v[120:121], v[120:121], 0, v[182:183]
	v_mov_b32_e32 v176, v116
	v_mov_b32_e32 v177, v117
	v_or_b32_e32 v116, 48, v128
	v_ashrrev_i32_e32 v117, 31, v116
	v_mfma_f32_16x16x32_bf16 v[84:87], v[68:71], v[136:139], v[164:167]
	v_lshlrev_b64 v[116:117], 11, v[116:117]
	v_lshl_add_u64 v[116:117], s[92:93], 0, v[116:117]
	v_lshl_add_u64 v[116:117], v[116:117], 0, v[182:183]
	v_mfma_f32_16x16x32_bf16 v[68:71], v[68:71], v[144:147], v[168:171]
	v_mov_b32_e32 v196, v32
	v_mov_b32_e32 v197, v33
	v_cvt_pk_bf16_f32 v32, v156, v157
	v_cvt_pk_bf16_f32 v33, v158, v159
	v_mov_b32_e32 v224, v32
	v_mov_b32_e32 v225, v33
	v_cvt_pk_bf16_f32 v32, v84, v85
	v_cvt_pk_bf16_f32 v33, v86, v87
	v_mov_b32_e32 v128, v32
	v_mov_b32_e32 v129, v33
	v_cvt_pk_bf16_f32 v32, v76, v77
	v_cvt_pk_bf16_f32 v33, v78, v79
	v_mfma_f32_16x16x32_bf16 v[24:27], v[148:151], v[136:139], v[24:27]
	v_mov_b32_e32 v164, v32
	v_mov_b32_e32 v165, v33
	v_cvt_pk_bf16_f32 v32, v68, v69
	v_cvt_pk_bf16_f32 v33, v70, v71
	v_mfma_f32_16x16x32_bf16 v[20:23], v[148:151], v[140:143], v[20:23]
	v_mov_b32_e32 v156, v32
	v_mov_b32_e32 v157, v33
	v_cvt_pk_bf16_f32 v32, v60, v61
	v_cvt_pk_bf16_f32 v33, v62, v63
	v_mfma_f32_16x16x32_bf16 v[16:19], v[148:151], v[144:147], v[16:19]
	v_mov_b32_e32 v226, v32
	v_mov_b32_e32 v227, v33
	s_nop 1
	v_permlane16_swap_b32_e32 v224, v226
	v_permlane16_swap_b32_e32 v225, v227
	global_store_dwordx4 v[88:89], v[224:227], off offset:128
	v_cvt_pk_bf16_f32 v32, v52, v53
	v_cvt_pk_bf16_f32 v33, v54, v55
	v_mfma_f32_16x16x32_bf16 v[8:11], v[152:155], v[136:139], v[8:11]
	v_mov_b32_e32 v130, v32
	v_mov_b32_e32 v131, v33
	s_nop 1
	v_permlane16_swap_b32_e32 v128, v130
	v_permlane16_swap_b32_e32 v129, v131
	global_store_dwordx4 v[90:91], v[128:131], off offset:128
	v_cvt_pk_bf16_f32 v32, v44, v45
	v_cvt_pk_bf16_f32 v33, v46, v47
	v_mfma_f32_16x16x32_bf16 v[4:7], v[152:155], v[140:143], v[4:7]
	v_mov_b32_e32 v166, v32
	v_mov_b32_e32 v167, v33
	s_nop 1
	v_permlane16_swap_b32_e32 v164, v166
	v_permlane16_swap_b32_e32 v165, v167
	global_store_dwordx4 v[120:121], v[164:167], off offset:128
	v_cvt_pk_bf16_f32 v32, v36, v37
	v_cvt_pk_bf16_f32 v33, v38, v39
	v_mfma_f32_16x16x32_bf16 v[0:3], v[152:155], v[144:147], v[0:3]
	v_cvt_pk_bf16_f32 v28, v28, v29
	v_cvt_pk_bf16_f32 v29, v30, v31
	v_cvt_pk_bf16_f32 v24, v24, v25
	v_cvt_pk_bf16_f32 v25, v26, v27
	v_cvt_pk_bf16_f32 v20, v20, v21
	v_cvt_pk_bf16_f32 v21, v22, v23
	v_cvt_pk_bf16_f32 v16, v16, v17
	v_cvt_pk_bf16_f32 v17, v18, v19
	v_cvt_pk_bf16_f32 v12, v12, v13
	v_cvt_pk_bf16_f32 v13, v14, v15
	v_cvt_pk_bf16_f32 v8, v8, v9
	v_cvt_pk_bf16_f32 v9, v10, v11
	v_cvt_pk_bf16_f32 v4, v4, v5
	v_cvt_pk_bf16_f32 v5, v6, v7
	v_cvt_pk_bf16_f32 v0, v0, v1
	v_cvt_pk_bf16_f32 v1, v2, v3
	v_mov_b32_e32 v128, v112
	v_mov_b32_e32 v129, v113
	v_mov_b32_e32 v162, v108
	v_mov_b32_e32 v163, v109
	s_nop 1
	v_permlane16_swap_b32_e32 v160, v162
	v_permlane16_swap_b32_e32 v161, v163
	global_store_dwordx4 v[88:89], v[160:163], off
	v_mov_b32_e32 v174, v104
	v_mov_b32_e32 v175, v105
	s_nop 1
	v_permlane16_swap_b32_e32 v172, v174
	v_permlane16_swap_b32_e32 v173, v175
	global_store_dwordx4 v[90:91], v[172:175], off
	v_mov_b32_e32 v178, v100
	v_mov_b32_e32 v179, v101
	s_nop 1
	v_permlane16_swap_b32_e32 v176, v178
	v_permlane16_swap_b32_e32 v177, v179
	global_store_dwordx4 v[120:121], v[176:179], off
	v_mov_b32_e32 v130, v96
	v_mov_b32_e32 v131, v97
	s_nop 1
	v_permlane16_swap_b32_e32 v128, v130
	v_permlane16_swap_b32_e32 v129, v131
	global_store_dwordx4 v[116:117], v[128:131], off
	s_nop 1
	v_mov_b32_e32 v128, v92
	v_mov_b32_e32 v129, v93
	v_mov_b32_e32 v138, v80
	v_mov_b32_e32 v139, v81
	v_mov_b32_e32 v142, v72
	v_mov_b32_e32 v143, v73
	v_mov_b32_e32 v194, v64
	v_mov_b32_e32 v195, v65
	s_nop 1
	v_permlane16_swap_b32_e32 v194, v196
	v_permlane16_swap_b32_e32 v195, v197
	global_store_dwordx4 v[116:117], v[194:197], off offset:64
	v_mov_b32_e32 v130, v56
	v_mov_b32_e32 v131, v57
	s_nop 1
	v_permlane16_swap_b32_e32 v128, v130
	v_permlane16_swap_b32_e32 v129, v131
	global_store_dwordx4 v[88:89], v[128:131], off offset:64
	v_mov_b32_e32 v140, v48
	v_mov_b32_e32 v141, v49
	s_nop 1
	v_permlane16_swap_b32_e32 v138, v140
	v_permlane16_swap_b32_e32 v139, v141
	global_store_dwordx4 v[90:91], v[138:141], off offset:64
	v_mov_b32_e32 v144, v40
	v_mov_b32_e32 v145, v41
	s_nop 1
	v_permlane16_swap_b32_e32 v142, v144
	v_permlane16_swap_b32_e32 v143, v145
	global_store_dwordx4 v[120:121], v[142:145], off offset:64
	v_mov_b32_e32 v158, v32
	v_mov_b32_e32 v159, v33
	s_nop 1
	v_permlane16_swap_b32_e32 v156, v158
	v_permlane16_swap_b32_e32 v157, v159
	global_store_dwordx4 v[116:117], v[156:159], off offset:128
	v_mov_b32_e32 v128, v28
	v_mov_b32_e32 v129, v29
	v_mov_b32_e32 v138, v24
	v_mov_b32_e32 v139, v25
	v_mov_b32_e32 v142, v20
	v_mov_b32_e32 v143, v21
	v_mov_b32_e32 v146, v16
	v_mov_b32_e32 v147, v17
	v_mov_b32_e32 v130, v12
	v_mov_b32_e32 v131, v13
	s_nop 1
	v_permlane16_swap_b32_e32 v128, v130
	v_permlane16_swap_b32_e32 v129, v131
	global_store_dwordx4 v[88:89], v[128:131], off offset:192
	v_mov_b32_e32 v140, v8
	v_mov_b32_e32 v141, v9
	s_nop 1
	v_permlane16_swap_b32_e32 v138, v140
	v_permlane16_swap_b32_e32 v139, v141
	global_store_dwordx4 v[90:91], v[138:141], off offset:192
	v_mov_b32_e32 v144, v4
	v_mov_b32_e32 v145, v5
	s_nop 1
	v_permlane16_swap_b32_e32 v142, v144
	v_permlane16_swap_b32_e32 v143, v145
	global_store_dwordx4 v[120:121], v[142:145], off offset:192
	v_mov_b32_e32 v148, v0
	v_mov_b32_e32 v149, v1
	s_nop 1
	v_permlane16_swap_b32_e32 v146, v148
	v_permlane16_swap_b32_e32 v147, v149
	global_store_dwordx4 v[116:117], v[146:149], off offset:192
	s_branch .LBB0_25

; template <int BM, class Epi>
; DI void gemm_dma(const u16* __restrict__ X, long ldx, const u16* __restrict__ W, long ldw, int K, char* smem,
;                  int m0, int n0, const Epi& epi) {
;     ...
;   const int wu = __builtin_amdgcn_readfirstlane(wave);
;   const unsigned sbase = (unsigned)__builtin_amdgcn_readfirstlane((int)(unsigned)(size_t)smem);
;   const int r16 = lane >> 2, chunk = (lane & 3) ^ ((4 - (r16 >> 2)) & 3);
;   const u16* xs = X + (long)(wu * XD * 16 + r16) * ldx + (chunk << 3);
;   const u16* ws = W + (long)(wu * 32 + r16) * ldw + (chunk << 3);
;   const long ldx16 = 16 * ldx, ldw16 = 16 * ldw;
;   const unsigned xdst = sbase + wu * XD * 1024, wdst = sbase + BM * 64 + wu * 2048;
;     ...
;   const int nk = K >> 5;
;   __syncthreads();
; #pragma unroll
;   for (int s = 0; s < D - 1; ++s) GD_ISSUE(s)
;   int cur = 0, nxt = D - 1, kt = 0;
; DI void knope_tile(const Params& p, int u, char* smem) {
;     ...
;   const int tm = u >> 3, tn = u & 7;
;   gemm_dma<256>(ckvb + (size_t)tm * 256 * 256, 256, W + WO_KV + (size_t)tn * 128 * 256, 256, 256, smem, tm * 256, tn * 128, ek);
.LBB0_84:
	s_cmpk_gt_i32 s4, 0x77f
	s_cbranch_scc1 .LBB0_92
	s_cmpk_gt_i32 s4, 0x43f
	s_mov_b64 s[38:39], -1
	s_cbranch_scc0 .LBB0_87
	s_add_i32 s5, s4, 0xfffffcc0
	s_bfe_u32 s98, s5, 0x30003
	s_and_b32 s99, s5, 7
	s_lshl_b32 s99, s99, 3
	s_andn2_b32 s5, s5, 63
	s_or_b32 s5, s5, s99
	s_or_b32 s5, s5, s98
	s_lshr_b32 s6, s5, 3
	s_and_b32 s5, s5, 7
	s_lshl_b32 s7, s6, 17
	s_add_u32 s8, s0, s7
	s_addc_u32 s9, s1, 0
	s_lshl_b32 s7, s5, 16
	v_mov_b32_e32 v11, v185
	s_add_u32 s10, s87, s7
	s_addc_u32 s11, s90, 0
	v_readfirstlane_b32 s7, v11
	v_lshrrev_b32_e32 v6, 4, v11
	s_ashr_i32 s12, s7, 6
	v_bfe_u32 v8, v11, 2, 4
	v_sub_u32_e32 v6, 0, v6
	s_andn2_b32 s7, s7, 63
	v_lshrrev_b32_e32 v3, 2, v11
	v_xor_b32_e32 v9, v11, v6
	v_or_b32_e32 v6, s7, v8
	v_and_b32_e32 v90, 15, v11
	v_bfe_u32 v1, v11, 4, 2
	v_sub_u32_e32 v3, 0, v3
	v_ashrrev_i32_e32 v7, 31, v6
	v_lshlrev_b32_e32 v2, 6, v90
	v_bitop3_b32 v3, v1, v3, 3 bitop3:0x78
	v_lshlrev_b64 v[6:7], 9, v[6:7]
	v_lshlrev_b32_e32 v9, 4, v9
	v_lshl_or_b32 v8, s12, 5, v8
	v_lshl_or_b32 v10, v3, 4, v2
	v_mov_b32_e32 v2, v183
	v_lshl_add_u64 v[6:7], s[8:9], 0, v[6:7]
	v_and_b32_e32 v182, 48, v9
	v_ashrrev_i32_e32 v9, 31, v8
	v_lshl_add_u64 v[6:7], v[6:7], 0, v[182:183]
	v_lshlrev_b64 v[8:9], 9, v[8:9]
	s_lshl_b32 s14, s12, 12
	s_barrier
	s_mov_b32 m0, s14
	s_nop 0
	global_load_lds_dwordx4 v[6:7], off
	s_mov_b64 s[8:9], 0x2000
	v_lshl_add_u64 v[8:9], s[10:11], 0, v[8:9]
	v_lshl_add_u64 v[12:13], v[6:7], 0, s[8:9]
	s_or_b32 s15, s14, 0x400
	s_mov_b32 m0, s15
	s_nop 0
	global_load_lds_dwordx4 v[12:13], off
	s_mov_b64 s[10:11], 0x4000
	v_lshl_add_u64 v[12:13], v[6:7], 0, s[10:11]
	s_or_b32 s16, s14, 0x800
	s_mov_b32 m0, s16
	s_nop 0
	global_load_lds_dwordx4 v[12:13], off
	s_mov_b64 s[10:11], 0x6000
	s_lshl_b32 s41, s12, 11
	v_lshl_add_u64 v[12:13], v[6:7], 0, s[10:11]
	s_or_b32 s17, s14, 0xc00
	s_mov_b32 m0, s17
	s_nop 0
	global_load_lds_dwordx4 v[12:13], off
	v_lshl_add_u64 v[8:9], v[8:9], 0, v[182:183]
	s_add_i32 s13, s41, 0x4000
	s_mov_b32 m0, s13
	s_nop 0
	global_load_lds_dwordx4 v[8:9], off
	v_lshl_add_u64 v[12:13], v[8:9], 0, s[8:9]
	s_add_i32 s18, s41, 0x4400
	s_mov_b32 m0, s18
	s_nop 0
	global_load_lds_dwordx4 v[12:13], off
	v_lshl_add_u64 v[12:13], v[6:7], 0, 64
	s_add_i32 s7, s14, 0x6000
	s_mov_b32 m0, s7
	s_nop 0
	global_load_lds_dwordx4 v[12:13], off
	s_mov_b64 s[20:21], 0x2040
	v_lshl_add_u64 v[12:13], v[6:7], 0, s[20:21]
	s_add_i32 s8, s14, 0x6400
	s_mov_b32 m0, s8
	s_nop 0
	global_load_lds_dwordx4 v[12:13], off
	s_mov_b64 s[10:11], 0x4040
	v_lshl_add_u64 v[12:13], v[6:7], 0, s[10:11]
	s_add_i32 s9, s14, 0x6800
	s_mov_b32 m0, s9
	s_nop 0
	global_load_lds_dwordx4 v[12:13], off
	s_mov_b64 s[10:11], 0x6040
	v_lshl_add_u64 v[12:13], v[6:7], 0, s[10:11]
	s_add_i32 s10, s14, 0x6c00
	s_mov_b32 m0, s10
	s_nop 0
	global_load_lds_dwordx4 v[12:13], off
	v_lshl_add_u64 v[14:15], v[8:9], 0, 64
	s_add_i32 s11, s41, 0xa000
	s_mov_b32 m0, s11
	s_nop 0
	global_load_lds_dwordx4 v[14:15], off
	v_lshl_add_u64 v[12:13], v[8:9], 0, s[20:21]
	s_add_i32 s12, s41, 0xa400
	s_mov_b32 m0, s12
	s_nop 0
	global_load_lds_dwordx4 v[12:13], off
	s_waitcnt vmcnt(6)
	s_barrier
	v_lshl_add_u64 v[14:15], v[6:7], 0, s[28:29]
	s_add_i32 s19, s14, 0xc000
	s_mov_b32 m0, s19
	s_nop 0
	global_load_lds_dwordx4 v[14:15], off
	s_mov_b64 s[20:21], 0x2080
	v_lshl_add_u64 v[14:15], v[6:7], 0, s[20:21]
	s_add_i32 s34, s14, 0xc400
	s_mov_b32 m0, s34
	s_nop 0
	global_load_lds_dwordx4 v[14:15], off
	v_lshl_add_u64 v[14:15], v[6:7], 0, s[94:95]
	s_add_i32 s38, s14, 0xc800
	s_mov_b32 m0, s38
	s_nop 0
	global_load_lds_dwordx4 v[14:15], off
	s_mov_b64 s[22:23], 0x6080
	v_lshl_add_u64 v[14:15], v[6:7], 0, s[22:23]
	s_add_i32 s39, s14, 0xcc00
	s_mov_b32 m0, s39
	s_nop 0
	global_load_lds_dwordx4 v[14:15], off
	v_and_b32_e32 v91, 0xffffffc0, v11
	v_lshl_add_u64 v[12:13], v[8:9], 0, s[28:29]
	s_add_i32 s40, s41, 0x10000
	s_mov_b32 m0, s40
	s_nop 0
	global_load_lds_dwordx4 v[12:13], off
	v_lshl_add_u64 v[12:13], v[8:9], 0, s[20:21]
	s_add_i32 s41, s41, 0x10400
	s_mov_b32 m0, s41
	s_nop 0
	global_load_lds_dwordx4 v[12:13], off
	v_lshl_or_b32 v11, v91, 6, v10
	ds_read_b128 v[12:15], v11
	ds_read_b128 v[16:19], v11 offset:1024
	ds_read_b128 v[20:23], v11 offset:2048
	ds_read_b128 v[24:27], v11 offset:3072
	ds_read_b128 v[28:31], v10 offset:16384
	ds_read_b128 v[32:35], v10 offset:17408
	ds_read_b128 v[36:39], v10 offset:18432
	ds_read_b128 v[40:43], v10 offset:19456
	ds_read_b128 v[96:99], v10 offset:20480
	ds_read_b128 v[100:103], v10 offset:21504
	ds_read_b128 v[104:107], v10 offset:22528
	ds_read_b128 v[108:111], v10 offset:23552
	s_mov_b64 s[20:21], 0xc0
	v_mov_b32_e32 v3, v2
	v_mov_b32_e32 v4, v2
	v_mov_b32_e32 v5, v2
	v_lshl_add_u64 v[88:89], v[6:7], 0, s[20:21]
	v_lshl_add_u64 v[148:149], v[8:9], 0, s[20:21]
	s_waitcnt vmcnt(6)
	s_waitcnt lgkmcnt(0)
	s_barrier
; template <int N> DI void wait_vm() { asm volatile("s_waitcnt vmcnt(%0)" ::"n"(N) : "memory"); }
; template <int BM, class Epi>
; DI void gemm_dma(const u16* __restrict__ X, long ldx, const u16* __restrict__ W, long ldw, int K, char* smem,
;                  int m0, int n0, const Epi& epi) {
;     ...
;   do {
;     if (kt + D - 2 < nk) wait_vm<PW * (D - 2)>(); else wait_vm<0>();
;     __syncthreads();
;     if (kt + D - 1 < nk) GD_ISSUE(nxt)
;     nxt = (nxt + 1 == D) ? 0 : nxt + 1;
;     const char* base = smem + cur * STG;
;     cur = (cur + 1 == D) ? 0 : cur + 1;
;     bf16x8 xf[MT];
; #pragma unroll
;     for (int i = 0; i < MT; ++i) xf[i] = *(const bf16x8*)(base + (xrow0 + i * 16) * 64 + rd);
; #pragma unroll
;     for (int nh = 0; nh < NT / 4; ++nh) {
;       bf16x8 wf[4];
; #pragma unroll
;       for (int i = 0; i < 4; ++i) wf[i] = *(const bf16x8*)(base + BM * 64 + (wrow0 + (nh * 4 + i) * 16) * 64 + rd);
; #pragma unroll
;       for (int i = 0; i < 4; ++i)
; #pragma unroll
;         for (int mt = 0; mt < MT; ++mt)
;           acc[nh * 4 + i][mt] = __builtin_amdgcn_mfma_f32_16x16x32_bf16(wf[i], xf[mt], acc[nh * 4 + i][mt], 0, 0, 0);
;     }
;   } while (++kt < nk);
	s_mov_b32 m0, s14
	s_nop 0
	global_load_lds_dwordx4 v[88:89], off
	s_mov_b64 s[20:21], 0x20c0
	v_mfma_f32_16x16x32_bf16 v[44:47], v[28:31], v[12:15], v[2:5]
	s_mov_b64 s[22:23], 0x40c0
	v_or_b32_e32 v174, 0x10000, v10
	v_or_b32_e32 v175, 0x10400, v10
	v_mfma_f32_16x16x32_bf16 v[48:51], v[28:31], v[16:19], v[2:5]
	v_or_b32_e32 v176, 0x10800, v10
	v_or_b32_e32 v177, 0x10c00, v10
	v_or_b32_e32 v178, 0x11000, v10
	v_mfma_f32_16x16x32_bf16 v[52:55], v[28:31], v[20:23], v[2:5]
	v_or_b32_e32 v179, 0x11400, v10
	v_or_b32_e32 v180, 0x11800, v10
	v_or_b32_e32 v181, 0x11c00, v10
	v_mfma_f32_16x16x32_bf16 v[28:31], v[28:31], v[24:27], v[2:5]
	v_lshl_add_u32 v91, s6, 8, v91
	s_lshl_b32 s5, s5, 8
	v_lshl_or_b32 v182, v1, 3, s5
	v_mfma_f32_16x16x32_bf16 v[56:59], v[32:35], v[12:15], v[2:5]
	v_mfma_f32_16x16x32_bf16 v[60:63], v[32:35], v[16:19], v[2:5]
	v_mfma_f32_16x16x32_bf16 v[64:67], v[32:35], v[20:23], v[2:5]
	v_mfma_f32_16x16x32_bf16 v[32:35], v[32:35], v[24:27], v[2:5]
	v_mfma_f32_16x16x32_bf16 v[68:71], v[36:39], v[12:15], v[2:5]
	v_mfma_f32_16x16x32_bf16 v[72:75], v[36:39], v[16:19], v[2:5]
	v_mfma_f32_16x16x32_bf16 v[76:79], v[36:39], v[20:23], v[2:5]
	v_mfma_f32_16x16x32_bf16 v[36:39], v[36:39], v[24:27], v[2:5]
	v_mfma_f32_16x16x32_bf16 v[80:83], v[40:43], v[12:15], v[2:5]
	v_mfma_f32_16x16x32_bf16 v[84:87], v[40:43], v[16:19], v[2:5]
	v_mfma_f32_16x16x32_bf16 v[92:95], v[40:43], v[20:23], v[2:5]
	v_mfma_f32_16x16x32_bf16 v[40:43], v[40:43], v[24:27], v[2:5]
	v_mfma_f32_16x16x32_bf16 v[112:115], v[96:99], v[12:15], v[2:5]
	v_mfma_f32_16x16x32_bf16 v[116:119], v[96:99], v[16:19], v[2:5]
	v_mfma_f32_16x16x32_bf16 v[120:123], v[96:99], v[20:23], v[2:5]
	v_mfma_f32_16x16x32_bf16 v[96:99], v[96:99], v[24:27], v[2:5]
	v_mfma_f32_16x16x32_bf16 v[124:127], v[100:103], v[12:15], v[2:5]
	v_mfma_f32_16x16x32_bf16 v[128:131], v[100:103], v[16:19], v[2:5]
	v_mfma_f32_16x16x32_bf16 v[132:135], v[100:103], v[20:23], v[2:5]
	v_mfma_f32_16x16x32_bf16 v[100:103], v[100:103], v[24:27], v[2:5]
	v_mfma_f32_16x16x32_bf16 v[136:139], v[104:107], v[12:15], v[2:5]
	v_mfma_f32_16x16x32_bf16 v[140:143], v[104:107], v[16:19], v[2:5]
	v_mfma_f32_16x16x32_bf16 v[144:147], v[104:107], v[20:23], v[2:5]
	v_mfma_f32_16x16x32_bf16 v[104:107], v[104:107], v[24:27], v[2:5]
	v_mfma_f32_16x16x32_bf16 v[12:15], v[108:111], v[12:15], v[2:5]
	v_mfma_f32_16x16x32_bf16 v[16:19], v[108:111], v[16:19], v[2:5]
	v_mfma_f32_16x16x32_bf16 v[20:23], v[108:111], v[20:23], v[2:5]
	v_mfma_f32_16x16x32_bf16 v[2:5], v[108:111], v[24:27], v[2:5]
	v_lshl_add_u64 v[24:25], v[6:7], 0, s[20:21]
	s_mov_b32 m0, s15
	s_nop 0
	global_load_lds_dwordx4 v[24:25], off
	v_lshl_add_u64 v[24:25], v[6:7], 0, s[22:23]
	s_mov_b32 m0, s16
	s_nop 0
	global_load_lds_dwordx4 v[24:25], off
	s_mov_b64 s[22:23], 0x60c0
	v_lshl_add_u64 v[24:25], v[6:7], 0, s[22:23]
	s_mov_b32 m0, s17
	s_nop 0
	global_load_lds_dwordx4 v[24:25], off
	v_lshl_add_u64 v[24:25], v[8:9], 0, s[20:21]
	s_mov_b32 m0, s13
	s_nop 0
	global_load_lds_dwordx4 v[148:149], off
	s_mov_b64 s[20:21], 0x100
	s_mov_b32 m0, s18
	s_nop 0
	global_load_lds_dwordx4 v[24:25], off
	ds_read_b128 v[24:27], v11 offset:24576
	ds_read_b128 v[108:111], v11 offset:25600
	ds_read_b128 v[148:151], v11 offset:26624
	ds_read_b128 v[152:155], v11 offset:27648
	ds_read_b128 v[156:159], v10 offset:40960
	ds_read_b128 v[160:163], v10 offset:41984
	ds_read_b128 v[164:167], v10 offset:43008
	ds_read_b128 v[168:171], v10 offset:44032
	s_waitcnt lgkmcnt(3)
	v_mfma_f32_16x16x32_bf16 v[44:47], v[156:159], v[24:27], v[44:47]
	v_lshl_add_u64 v[88:89], v[6:7], 0, s[20:21]
	v_lshl_add_u64 v[172:173], v[8:9], 0, s[20:21]
	s_mov_b64 s[20:21], 0x2100
	v_mfma_f32_16x16x32_bf16 v[48:51], v[156:159], v[108:111], v[48:51]
	s_mov_b64 s[22:23], 0x4100
	v_mfma_f32_16x16x32_bf16 v[52:55], v[156:159], v[148:151], v[52:55]
	v_mfma_f32_16x16x32_bf16 v[28:31], v[156:159], v[152:155], v[28:31]
	s_waitcnt lgkmcnt(2)
	v_mfma_f32_16x16x32_bf16 v[56:59], v[160:163], v[24:27], v[56:59]
	v_mfma_f32_16x16x32_bf16 v[60:63], v[160:163], v[108:111], v[60:63]
	v_mfma_f32_16x16x32_bf16 v[64:67], v[160:163], v[148:151], v[64:67]
	v_mfma_f32_16x16x32_bf16 v[32:35], v[160:163], v[152:155], v[32:35]
	s_waitcnt lgkmcnt(1)
	v_mfma_f32_16x16x32_bf16 v[68:71], v[164:167], v[24:27], v[68:71]
	v_mfma_f32_16x16x32_bf16 v[72:75], v[164:167], v[108:111], v[72:75]
	v_mfma_f32_16x16x32_bf16 v[76:79], v[164:167], v[148:151], v[76:79]
	v_mfma_f32_16x16x32_bf16 v[36:39], v[164:167], v[152:155], v[36:39]
	s_waitcnt lgkmcnt(0)
	v_mfma_f32_16x16x32_bf16 v[80:83], v[168:171], v[24:27], v[80:83]
	v_mfma_f32_16x16x32_bf16 v[84:87], v[168:171], v[108:111], v[84:87]
	v_mfma_f32_16x16x32_bf16 v[92:95], v[168:171], v[148:151], v[92:95]
	v_mfma_f32_16x16x32_bf16 v[40:43], v[168:171], v[152:155], v[40:43]
	ds_read_b128 v[156:159], v10 offset:45056
	ds_read_b128 v[160:163], v10 offset:46080
	ds_read_b128 v[164:167], v10 offset:47104
	ds_read_b128 v[168:171], v10 offset:48128
	s_waitcnt vmcnt(6)
	s_waitcnt lgkmcnt(0)
	s_barrier
; template <int N> DI void wait_vm() { asm volatile("s_waitcnt vmcnt(%0)" ::"n"(N) : "memory"); }
; template <int BM, class Epi>
; DI void gemm_dma(const u16* __restrict__ X, long ldx, const u16* __restrict__ W, long ldw, int K, char* smem,
;                  int m0, int n0, const Epi& epi) {
;     ...
;   do {
;     if (kt + D - 2 < nk) wait_vm<PW * (D - 2)>(); else wait_vm<0>();
;     __syncthreads();
;     if (kt + D - 1 < nk) GD_ISSUE(nxt)
;     nxt = (nxt + 1 == D) ? 0 : nxt + 1;
;     const char* base = smem + cur * STG;
;     cur = (cur + 1 == D) ? 0 : cur + 1;
;     bf16x8 xf[MT];
; #pragma unroll
;     for (int i = 0; i < MT; ++i) xf[i] = *(const bf16x8*)(base + (xrow0 + i * 16) * 64 + rd);
; #pragma unroll
;     for (int nh = 0; nh < NT / 4; ++nh) {
;       bf16x8 wf[4];
; #pragma unroll
;       for (int i = 0; i < 4; ++i) wf[i] = *(const bf16x8*)(base + BM * 64 + (wrow0 + (nh * 4 + i) * 16) * 64 + rd);
; #pragma unroll
;       for (int i = 0; i < 4; ++i)
; #pragma unroll
;         for (int mt = 0; mt < MT; ++mt)
;           acc[nh * 4 + i][mt] = __builtin_amdgcn_mfma_f32_16x16x32_bf16(wf[i], xf[mt], acc[nh * 4 + i][mt], 0, 0, 0);
;     }
;   } while (++kt < nk);
	s_mov_b32 m0, s7
	s_nop 0
	global_load_lds_dwordx4 v[88:89], off
	v_mfma_f32_16x16x32_bf16 v[112:115], v[156:159], v[24:27], v[112:115]
	v_mfma_f32_16x16x32_bf16 v[124:127], v[160:163], v[24:27], v[124:127]
	v_mfma_f32_16x16x32_bf16 v[136:139], v[164:167], v[24:27], v[136:139]
	v_mfma_f32_16x16x32_bf16 v[12:15], v[168:171], v[24:27], v[12:15]
	v_lshl_add_u64 v[24:25], v[6:7], 0, s[20:21]
	s_mov_b32 m0, s8
	s_nop 0
	global_load_lds_dwordx4 v[24:25], off
	v_lshl_add_u64 v[24:25], v[6:7], 0, s[22:23]
	s_mov_b32 m0, s9
	s_nop 0
	global_load_lds_dwordx4 v[24:25], off
	s_mov_b64 s[22:23], 0x6100
	v_lshl_add_u64 v[24:25], v[6:7], 0, s[22:23]
	s_mov_b32 m0, s10
	s_nop 0
	global_load_lds_dwordx4 v[24:25], off
	v_lshl_add_u64 v[24:25], v[8:9], 0, s[20:21]
	s_mov_b32 m0, s11
	s_nop 0
	global_load_lds_dwordx4 v[172:173], off
	v_mfma_f32_16x16x32_bf16 v[116:119], v[156:159], v[108:111], v[116:119]
	s_mov_b32 m0, s12
	s_nop 0
	global_load_lds_dwordx4 v[24:25], off
	s_mov_b64 s[20:21], 0x140
	v_lshl_add_u64 v[88:89], v[6:7], 0, s[20:21]
	v_mfma_f32_16x16x32_bf16 v[120:123], v[156:159], v[148:151], v[120:123]
	v_lshl_add_u64 v[172:173], v[8:9], 0, s[20:21]
	s_mov_b64 s[20:21], 0x2140
	s_mov_b64 s[22:23], 0x4140
	v_mfma_f32_16x16x32_bf16 v[96:99], v[156:159], v[152:155], v[96:99]
	v_mfma_f32_16x16x32_bf16 v[128:131], v[160:163], v[108:111], v[128:131]
	v_mfma_f32_16x16x32_bf16 v[132:135], v[160:163], v[148:151], v[132:135]
	v_mfma_f32_16x16x32_bf16 v[100:103], v[160:163], v[152:155], v[100:103]
	v_mfma_f32_16x16x32_bf16 v[140:143], v[164:167], v[108:111], v[140:143]
	v_mfma_f32_16x16x32_bf16 v[144:147], v[164:167], v[148:151], v[144:147]
	v_mfma_f32_16x16x32_bf16 v[104:107], v[164:167], v[152:155], v[104:107]
	v_mfma_f32_16x16x32_bf16 v[16:19], v[168:171], v[108:111], v[16:19]
	v_mfma_f32_16x16x32_bf16 v[20:23], v[168:171], v[148:151], v[20:23]
	v_mfma_f32_16x16x32_bf16 v[2:5], v[168:171], v[152:155], v[2:5]
	ds_read_b128 v[24:27], v11 offset:49152
	ds_read_b128 v[108:111], v11 offset:50176
	ds_read_b128 v[148:151], v11 offset:51200
	ds_read_b128 v[152:155], v11 offset:52224
	ds_read_b128 v[156:159], v174
	ds_read_b128 v[160:163], v175
	ds_read_b128 v[164:167], v176
	ds_read_b128 v[168:171], v177
	s_waitcnt lgkmcnt(3)
	v_mfma_f32_16x16x32_bf16 v[44:47], v[156:159], v[24:27], v[44:47]
	v_mfma_f32_16x16x32_bf16 v[48:51], v[156:159], v[108:111], v[48:51]
	v_mfma_f32_16x16x32_bf16 v[52:55], v[156:159], v[148:151], v[52:55]
	v_mfma_f32_16x16x32_bf16 v[28:31], v[156:159], v[152:155], v[28:31]
	ds_read_b128 v[156:159], v178
	s_waitcnt lgkmcnt(3)
	v_mfma_f32_16x16x32_bf16 v[56:59], v[160:163], v[24:27], v[56:59]
	v_mfma_f32_16x16x32_bf16 v[60:63], v[160:163], v[108:111], v[60:63]
	v_mfma_f32_16x16x32_bf16 v[64:67], v[160:163], v[148:151], v[64:67]
	v_mfma_f32_16x16x32_bf16 v[32:35], v[160:163], v[152:155], v[32:35]
	ds_read_b128 v[160:163], v179
	s_waitcnt lgkmcnt(3)
	v_mfma_f32_16x16x32_bf16 v[68:71], v[164:167], v[24:27], v[68:71]
	v_mfma_f32_16x16x32_bf16 v[72:75], v[164:167], v[108:111], v[72:75]
	v_mfma_f32_16x16x32_bf16 v[76:79], v[164:167], v[148:151], v[76:79]
	v_mfma_f32_16x16x32_bf16 v[36:39], v[164:167], v[152:155], v[36:39]
	ds_read_b128 v[164:167], v180
	s_waitcnt lgkmcnt(3)
	v_mfma_f32_16x16x32_bf16 v[80:83], v[168:171], v[24:27], v[80:83]
	v_mfma_f32_16x16x32_bf16 v[84:87], v[168:171], v[108:111], v[84:87]
	v_mfma_f32_16x16x32_bf16 v[92:95], v[168:171], v[148:151], v[92:95]
	v_mfma_f32_16x16x32_bf16 v[40:43], v[168:171], v[152:155], v[40:43]
	ds_read_b128 v[168:171], v181
	s_waitcnt vmcnt(6)
	s_waitcnt lgkmcnt(0)
	s_barrier
	s_mov_b32 m0, s19
	s_nop 0
	global_load_lds_dwordx4 v[88:89], off
	v_mfma_f32_16x16x32_bf16 v[112:115], v[156:159], v[24:27], v[112:115]
	v_mfma_f32_16x16x32_bf16 v[124:127], v[160:163], v[24:27], v[124:127]
	v_mfma_f32_16x16x32_bf16 v[136:139], v[164:167], v[24:27], v[136:139]
	v_mfma_f32_16x16x32_bf16 v[12:15], v[168:171], v[24:27], v[12:15]
	v_lshl_add_u64 v[24:25], v[6:7], 0, s[20:21]
	s_mov_b32 m0, s34
	s_nop 0
	global_load_lds_dwordx4 v[24:25], off
	v_lshl_add_u64 v[24:25], v[6:7], 0, s[22:23]
	s_mov_b32 m0, s38
	s_nop 0
	global_load_lds_dwordx4 v[24:25], off
	s_mov_b64 s[22:23], 0x6140
	v_lshl_add_u64 v[24:25], v[6:7], 0, s[22:23]
	s_mov_b32 m0, s39
	s_nop 0
	global_load_lds_dwordx4 v[24:25], off
	v_lshl_add_u64 v[24:25], v[8:9], 0, s[20:21]
	s_mov_b32 m0, s40
	s_nop 0
	global_load_lds_dwordx4 v[172:173], off
	v_mfma_f32_16x16x32_bf16 v[116:119], v[156:159], v[108:111], v[116:119]
	s_mov_b32 m0, s41
	s_nop 0
	global_load_lds_dwordx4 v[24:25], off
	s_mov_b64 s[20:21], 0x180
	v_lshl_add_u64 v[88:89], v[6:7], 0, s[20:21]
	v_mfma_f32_16x16x32_bf16 v[120:123], v[156:159], v[148:151], v[120:123]
	v_lshl_add_u64 v[172:173], v[8:9], 0, s[20:21]
	s_mov_b64 s[20:21], 0x2180
	s_mov_b64 s[38:39], 0
	v_mfma_f32_16x16x32_bf16 v[96:99], v[156:159], v[152:155], v[96:99]
	v_mfma_f32_16x16x32_bf16 v[128:131], v[160:163], v[108:111], v[128:131]
	v_mfma_f32_16x16x32_bf16 v[132:135], v[160:163], v[148:151], v[132:135]
	v_mfma_f32_16x16x32_bf16 v[100:103], v[160:163], v[152:155], v[100:103]
	v_mfma_f32_16x16x32_bf16 v[140:143], v[164:167], v[108:111], v[140:143]
	v_mfma_f32_16x16x32_bf16 v[144:147], v[164:167], v[148:151], v[144:147]
	v_mfma_f32_16x16x32_bf16 v[104:107], v[164:167], v[152:155], v[104:107]
	v_mfma_f32_16x16x32_bf16 v[16:19], v[168:171], v[108:111], v[16:19]
	v_mfma_f32_16x16x32_bf16 v[20:23], v[168:171], v[148:151], v[20:23]
	v_mfma_f32_16x16x32_bf16 v[2:5], v[168:171], v[152:155], v[2:5]
	ds_read_b128 v[24:27], v11
	ds_read_b128 v[108:111], v11 offset:1024
	ds_read_b128 v[148:151], v11 offset:2048
	ds_read_b128 v[152:155], v11 offset:3072
	ds_read_b128 v[156:159], v10 offset:16384
	ds_read_b128 v[160:163], v10 offset:17408
	ds_read_b128 v[164:167], v10 offset:18432
	ds_read_b128 v[168:171], v10 offset:19456
	s_waitcnt lgkmcnt(3)
; template <int N> DI void wait_vm() { asm volatile("s_waitcnt vmcnt(%0)" ::"n"(N) : "memory"); }
; template <int BM, class Epi>
; DI void gemm_dma(const u16* __restrict__ X, long ldx, const u16* __restrict__ W, long ldw, int K, char* smem,
;                  int m0, int n0, const Epi& epi) {
;     ...
;   do {
;     if (kt + D - 2 < nk) wait_vm<PW * (D - 2)>(); else wait_vm<0>();
;     __syncthreads();
;     if (kt + D - 1 < nk) GD_ISSUE(nxt)
;     nxt = (nxt + 1 == D) ? 0 : nxt + 1;
;     const char* base = smem + cur * STG;
;     cur = (cur + 1 == D) ? 0 : cur + 1;
;     bf16x8 xf[MT];
; #pragma unroll
;     for (int i = 0; i < MT; ++i) xf[i] = *(const bf16x8*)(base + (xrow0 + i * 16) * 64 + rd);
; #pragma unroll
;     for (int nh = 0; nh < NT / 4; ++nh) {
;       bf16x8 wf[4];
; #pragma unroll
;       for (int i = 0; i < 4; ++i) wf[i] = *(const bf16x8*)(base + BM * 64 + (wrow0 + (nh * 4 + i) * 16) * 64 + rd);
; #pragma unroll
;       for (int i = 0; i < 4; ++i)
; #pragma unroll
;         for (int mt = 0; mt < MT; ++mt)
;           acc[nh * 4 + i][mt] = __builtin_amdgcn_mfma_f32_16x16x32_bf16(wf[i], xf[mt], acc[nh * 4 + i][mt], 0, 0, 0);
;     }
;   } while (++kt < nk);
	v_mfma_f32_16x16x32_bf16 v[44:47], v[156:159], v[24:27], v[44:47]
	v_mfma_f32_16x16x32_bf16 v[48:51], v[156:159], v[108:111], v[48:51]
	v_mfma_f32_16x16x32_bf16 v[52:55], v[156:159], v[148:151], v[52:55]
	v_mfma_f32_16x16x32_bf16 v[28:31], v[156:159], v[152:155], v[28:31]
	s_waitcnt lgkmcnt(2)
	v_mfma_f32_16x16x32_bf16 v[56:59], v[160:163], v[24:27], v[56:59]
	v_mfma_f32_16x16x32_bf16 v[60:63], v[160:163], v[108:111], v[60:63]
	v_mfma_f32_16x16x32_bf16 v[64:67], v[160:163], v[148:151], v[64:67]
	v_mfma_f32_16x16x32_bf16 v[32:35], v[160:163], v[152:155], v[32:35]
	s_waitcnt lgkmcnt(1)
	v_mfma_f32_16x16x32_bf16 v[68:71], v[164:167], v[24:27], v[68:71]
	v_mfma_f32_16x16x32_bf16 v[72:75], v[164:167], v[108:111], v[72:75]
	v_mfma_f32_16x16x32_bf16 v[76:79], v[164:167], v[148:151], v[76:79]
	v_mfma_f32_16x16x32_bf16 v[36:39], v[164:167], v[152:155], v[36:39]
	s_waitcnt lgkmcnt(0)
	v_mfma_f32_16x16x32_bf16 v[80:83], v[168:171], v[24:27], v[80:83]
	v_mfma_f32_16x16x32_bf16 v[84:87], v[168:171], v[108:111], v[84:87]
	v_mfma_f32_16x16x32_bf16 v[92:95], v[168:171], v[148:151], v[92:95]
	v_mfma_f32_16x16x32_bf16 v[40:43], v[168:171], v[152:155], v[40:43]
	ds_read_b128 v[156:159], v10 offset:20480
	ds_read_b128 v[160:163], v10 offset:21504
	ds_read_b128 v[164:167], v10 offset:22528
	ds_read_b128 v[168:171], v10 offset:23552
	s_waitcnt vmcnt(6)
	s_waitcnt lgkmcnt(0)
	s_barrier
	s_mov_b32 m0, s14
	s_nop 0
	global_load_lds_dwordx4 v[88:89], off
	v_mfma_f32_16x16x32_bf16 v[112:115], v[156:159], v[24:27], v[112:115]
	v_mfma_f32_16x16x32_bf16 v[124:127], v[160:163], v[24:27], v[124:127]
	v_mfma_f32_16x16x32_bf16 v[136:139], v[164:167], v[24:27], v[136:139]
	v_mfma_f32_16x16x32_bf16 v[12:15], v[168:171], v[24:27], v[12:15]
	v_lshl_add_u64 v[24:25], v[6:7], 0, s[20:21]
	s_mov_b32 m0, s15
	s_nop 0
	global_load_lds_dwordx4 v[24:25], off
	s_mov_b64 s[14:15], 0x4180
	v_lshl_add_u64 v[24:25], v[6:7], 0, s[14:15]
	s_mov_b32 m0, s16
	s_nop 0
	global_load_lds_dwordx4 v[24:25], off
	s_mov_b64 s[14:15], 0x6180
	v_lshl_add_u64 v[24:25], v[6:7], 0, s[14:15]
	s_mov_b32 m0, s17
	s_nop 0
	global_load_lds_dwordx4 v[24:25], off
	v_lshl_add_u64 v[24:25], v[8:9], 0, s[20:21]
	s_mov_b32 m0, s13
	s_nop 0
	global_load_lds_dwordx4 v[172:173], off
	s_mov_b32 m0, s18
	s_nop 0
	global_load_lds_dwordx4 v[24:25], off
	v_mfma_f32_16x16x32_bf16 v[116:119], v[156:159], v[108:111], v[116:119]
	s_mov_b64 s[14:15], 0x1c0
	v_lshl_add_u64 v[88:89], v[6:7], 0, s[14:15]
	v_lshl_add_u64 v[172:173], v[8:9], 0, s[14:15]
	v_mfma_f32_16x16x32_bf16 v[120:123], v[156:159], v[148:151], v[120:123]
	s_mov_b64 s[14:15], 0x21c0
	s_mov_b64 s[16:17], 0x41c0
	v_mfma_f32_16x16x32_bf16 v[96:99], v[156:159], v[152:155], v[96:99]
	v_mfma_f32_16x16x32_bf16 v[128:131], v[160:163], v[108:111], v[128:131]
	v_mfma_f32_16x16x32_bf16 v[132:135], v[160:163], v[148:151], v[132:135]
	v_mfma_f32_16x16x32_bf16 v[100:103], v[160:163], v[152:155], v[100:103]
	v_mfma_f32_16x16x32_bf16 v[140:143], v[164:167], v[108:111], v[140:143]
	v_mfma_f32_16x16x32_bf16 v[144:147], v[164:167], v[148:151], v[144:147]
	v_mfma_f32_16x16x32_bf16 v[104:107], v[164:167], v[152:155], v[104:107]
	v_mfma_f32_16x16x32_bf16 v[16:19], v[168:171], v[108:111], v[16:19]
	v_mfma_f32_16x16x32_bf16 v[20:23], v[168:171], v[148:151], v[20:23]
	v_mfma_f32_16x16x32_bf16 v[2:5], v[168:171], v[152:155], v[2:5]
	ds_read_b128 v[24:27], v11 offset:24576
	ds_read_b128 v[108:111], v11 offset:25600
	ds_read_b128 v[148:151], v11 offset:26624
	ds_read_b128 v[152:155], v11 offset:27648
	ds_read_b128 v[156:159], v10 offset:40960
	ds_read_b128 v[160:163], v10 offset:41984
	ds_read_b128 v[164:167], v10 offset:43008
	ds_read_b128 v[168:171], v10 offset:44032
	s_waitcnt lgkmcnt(3)
	v_mfma_f32_16x16x32_bf16 v[44:47], v[156:159], v[24:27], v[44:47]
	v_mfma_f32_16x16x32_bf16 v[48:51], v[156:159], v[108:111], v[48:51]
	v_mfma_f32_16x16x32_bf16 v[52:55], v[156:159], v[148:151], v[52:55]
	v_mfma_f32_16x16x32_bf16 v[28:31], v[156:159], v[152:155], v[28:31]
	s_waitcnt lgkmcnt(2)
	v_mfma_f32_16x16x32_bf16 v[56:59], v[160:163], v[24:27], v[56:59]
	v_mfma_f32_16x16x32_bf16 v[60:63], v[160:163], v[108:111], v[60:63]
	v_mfma_f32_16x16x32_bf16 v[64:67], v[160:163], v[148:151], v[64:67]
	v_mfma_f32_16x16x32_bf16 v[32:35], v[160:163], v[152:155], v[32:35]
	s_waitcnt lgkmcnt(1)
	v_mfma_f32_16x16x32_bf16 v[68:71], v[164:167], v[24:27], v[68:71]
	v_mfma_f32_16x16x32_bf16 v[72:75], v[164:167], v[108:111], v[72:75]
	v_mfma_f32_16x16x32_bf16 v[76:79], v[164:167], v[148:151], v[76:79]
	v_mfma_f32_16x16x32_bf16 v[36:39], v[164:167], v[152:155], v[36:39]
	s_waitcnt lgkmcnt(0)
	v_mfma_f32_16x16x32_bf16 v[80:83], v[168:171], v[24:27], v[80:83]
	v_mfma_f32_16x16x32_bf16 v[84:87], v[168:171], v[108:111], v[84:87]
	v_mfma_f32_16x16x32_bf16 v[92:95], v[168:171], v[148:151], v[92:95]
	v_mfma_f32_16x16x32_bf16 v[40:43], v[168:171], v[152:155], v[40:43]
	ds_read_b128 v[156:159], v10 offset:45056
	ds_read_b128 v[160:163], v10 offset:46080
	ds_read_b128 v[164:167], v10 offset:47104
	ds_read_b128 v[168:171], v10 offset:48128
	s_waitcnt vmcnt(6)
	s_waitcnt lgkmcnt(0)
	s_barrier
; template <int N> DI void wait_vm() { asm volatile("s_waitcnt vmcnt(%0)" ::"n"(N) : "memory"); }
; template <int BM, class Epi>
; DI void gemm_dma(const u16* __restrict__ X, long ldx, const u16* __restrict__ W, long ldw, int K, char* smem,
;                  int m0, int n0, const Epi& epi) {
;     ...
;   do {
;     if (kt + D - 2 < nk) wait_vm<PW * (D - 2)>(); else wait_vm<0>();
;     __syncthreads();
;     if (kt + D - 1 < nk) GD_ISSUE(nxt)
;     nxt = (nxt + 1 == D) ? 0 : nxt + 1;
;     const char* base = smem + cur * STG;
;     cur = (cur + 1 == D) ? 0 : cur + 1;
;     bf16x8 xf[MT];
; #pragma unroll
;     for (int i = 0; i < MT; ++i) xf[i] = *(const bf16x8*)(base + (xrow0 + i * 16) * 64 + rd);
; #pragma unroll
;     for (int nh = 0; nh < NT / 4; ++nh) {
;       bf16x8 wf[4];
; #pragma unroll
;       for (int i = 0; i < 4; ++i) wf[i] = *(const bf16x8*)(base + BM * 64 + (wrow0 + (nh * 4 + i) * 16) * 64 + rd);
; #pragma unroll
;       for (int i = 0; i < 4; ++i)
; #pragma unroll
;         for (int mt = 0; mt < MT; ++mt)
;           acc[nh * 4 + i][mt] = __builtin_amdgcn_mfma_f32_16x16x32_bf16(wf[i], xf[mt], acc[nh * 4 + i][mt], 0, 0, 0);
;     }
;   } while (++kt < nk);
	s_mov_b32 m0, s7
	s_nop 0
	global_load_lds_dwordx4 v[88:89], off
	v_mfma_f32_16x16x32_bf16 v[112:115], v[156:159], v[24:27], v[112:115]
	v_mfma_f32_16x16x32_bf16 v[124:127], v[160:163], v[24:27], v[124:127]
	v_mfma_f32_16x16x32_bf16 v[136:139], v[164:167], v[24:27], v[136:139]
	v_mfma_f32_16x16x32_bf16 v[12:15], v[168:171], v[24:27], v[12:15]
	v_lshl_add_u64 v[24:25], v[6:7], 0, s[14:15]
	s_mov_b32 m0, s8
	s_nop 0
	global_load_lds_dwordx4 v[24:25], off
	v_lshl_add_u64 v[24:25], v[6:7], 0, s[16:17]
	s_mov_b32 m0, s9
	s_nop 0
	global_load_lds_dwordx4 v[24:25], off
	s_mov_b64 s[8:9], 0x61c0
	v_lshl_add_u64 v[6:7], v[6:7], 0, s[8:9]
	s_mov_b32 m0, s10
	s_nop 0
	global_load_lds_dwordx4 v[6:7], off
	v_lshl_add_u64 v[6:7], v[8:9], 0, s[14:15]
	s_mov_b32 m0, s11
	s_nop 0
	global_load_lds_dwordx4 v[172:173], off
	v_mfma_f32_16x16x32_bf16 v[116:119], v[156:159], v[108:111], v[116:119]
	s_mov_b32 m0, s12
	s_nop 0
	global_load_lds_dwordx4 v[6:7], off
	v_mfma_f32_16x16x32_bf16 v[120:123], v[156:159], v[148:151], v[120:123]
	v_mfma_f32_16x16x32_bf16 v[96:99], v[156:159], v[152:155], v[96:99]
	v_mfma_f32_16x16x32_bf16 v[128:131], v[160:163], v[108:111], v[128:131]
	v_mfma_f32_16x16x32_bf16 v[132:135], v[160:163], v[148:151], v[132:135]
	v_mfma_f32_16x16x32_bf16 v[100:103], v[160:163], v[152:155], v[100:103]
	v_mfma_f32_16x16x32_bf16 v[140:143], v[164:167], v[108:111], v[140:143]
	v_mfma_f32_16x16x32_bf16 v[144:147], v[164:167], v[148:151], v[144:147]
	v_mfma_f32_16x16x32_bf16 v[104:107], v[164:167], v[152:155], v[104:107]
	v_mfma_f32_16x16x32_bf16 v[16:19], v[168:171], v[108:111], v[16:19]
	v_mfma_f32_16x16x32_bf16 v[20:23], v[168:171], v[148:151], v[20:23]
	v_mfma_f32_16x16x32_bf16 v[2:5], v[168:171], v[152:155], v[2:5]
	ds_read_b128 v[6:9], v11 offset:49152
	ds_read_b128 v[24:27], v11 offset:50176
	ds_read_b128 v[108:111], v11 offset:51200
	ds_read_b128 v[148:151], v11 offset:52224
	ds_read_b128 v[152:155], v174
	ds_read_b128 v[156:159], v175
	ds_read_b128 v[160:163], v176
	ds_read_b128 v[164:167], v177
	s_waitcnt lgkmcnt(3)
	v_mfma_f32_16x16x32_bf16 v[44:47], v[152:155], v[6:9], v[44:47]
	v_mfma_f32_16x16x32_bf16 v[48:51], v[152:155], v[24:27], v[48:51]
	v_mfma_f32_16x16x32_bf16 v[52:55], v[152:155], v[108:111], v[52:55]
	v_mfma_f32_16x16x32_bf16 v[28:31], v[152:155], v[148:151], v[28:31]
	s_waitcnt lgkmcnt(2)
	v_mfma_f32_16x16x32_bf16 v[56:59], v[156:159], v[6:9], v[56:59]
	v_mfma_f32_16x16x32_bf16 v[60:63], v[156:159], v[24:27], v[60:63]
	v_mfma_f32_16x16x32_bf16 v[64:67], v[156:159], v[108:111], v[64:67]
	v_mfma_f32_16x16x32_bf16 v[32:35], v[156:159], v[148:151], v[32:35]
	s_waitcnt lgkmcnt(1)
	v_mfma_f32_16x16x32_bf16 v[68:71], v[160:163], v[6:9], v[68:71]
	v_mfma_f32_16x16x32_bf16 v[72:75], v[160:163], v[24:27], v[72:75]
	v_mfma_f32_16x16x32_bf16 v[76:79], v[160:163], v[108:111], v[76:79]
	v_mfma_f32_16x16x32_bf16 v[36:39], v[160:163], v[148:151], v[36:39]
	s_waitcnt lgkmcnt(0)
	v_mfma_f32_16x16x32_bf16 v[80:83], v[164:167], v[6:9], v[80:83]
	v_mfma_f32_16x16x32_bf16 v[84:87], v[164:167], v[24:27], v[84:87]
	v_mfma_f32_16x16x32_bf16 v[92:95], v[164:167], v[108:111], v[92:95]
	v_mfma_f32_16x16x32_bf16 v[40:43], v[164:167], v[148:151], v[40:43]
	ds_read_b128 v[152:155], v178
	ds_read_b128 v[156:159], v179
	ds_read_b128 v[160:163], v180
	ds_read_b128 v[164:167], v181
	s_waitcnt vmcnt(6)
	s_waitcnt lgkmcnt(0)
	v_mfma_f32_16x16x32_bf16 v[112:115], v[152:155], v[6:9], v[112:115]
	s_barrier
	v_mfma_f32_16x16x32_bf16 v[116:119], v[152:155], v[24:27], v[116:119]
	v_mfma_f32_16x16x32_bf16 v[120:123], v[152:155], v[108:111], v[120:123]
	v_mfma_f32_16x16x32_bf16 v[96:99], v[152:155], v[148:151], v[96:99]
	v_mfma_f32_16x16x32_bf16 v[124:127], v[156:159], v[6:9], v[124:127]
	v_mfma_f32_16x16x32_bf16 v[128:131], v[156:159], v[24:27], v[128:131]
	v_mfma_f32_16x16x32_bf16 v[132:135], v[156:159], v[108:111], v[132:135]
	v_mfma_f32_16x16x32_bf16 v[100:103], v[156:159], v[148:151], v[100:103]
	v_mfma_f32_16x16x32_bf16 v[136:139], v[160:163], v[6:9], v[136:139]
	v_mfma_f32_16x16x32_bf16 v[140:143], v[160:163], v[24:27], v[140:143]
	v_mfma_f32_16x16x32_bf16 v[144:147], v[160:163], v[108:111], v[144:147]
	v_mfma_f32_16x16x32_bf16 v[104:107], v[160:163], v[148:151], v[104:107]
	v_mfma_f32_16x16x32_bf16 v[6:9], v[164:167], v[6:9], v[12:15]
	v_mfma_f32_16x16x32_bf16 v[12:15], v[164:167], v[24:27], v[16:19]
	v_mfma_f32_16x16x32_bf16 v[16:19], v[164:167], v[108:111], v[20:23]
	v_mfma_f32_16x16x32_bf16 v[2:5], v[164:167], v[148:151], v[2:5]
	s_nop 1
	ds_read_b128 v[20:23], v10 offset:23552
	ds_read_b128 v[24:27], v10 offset:22528
	ds_read_b128 v[108:111], v10 offset:21504
	ds_read_b128 v[148:151], v10 offset:20480
	ds_read_b128 v[152:155], v10 offset:19456
	ds_read_b128 v[156:159], v10 offset:18432
	ds_read_b128 v[160:163], v10 offset:17408
	ds_read_b128 v[164:167], v10 offset:16384
	ds_read_b128 v[168:171], v11 offset:3072
	ds_read_b128 v[172:175], v11 offset:2048
	ds_read_b128 v[176:179], v11 offset:1024
	ds_read_b128 v[186:189], v11
	s_waitcnt vmcnt(0)
	s_waitcnt lgkmcnt(0)
	v_mfma_f32_16x16x32_bf16 v[44:47], v[164:167], v[186:189], v[44:47]
	s_barrier
; DI void st_bf4(u16* p, float a, float b, float c, float d) { *(uint2*)p = make_uint2(pk2(a, b), pk2(c, d)); }
; template <int BM, class Epi>
; DI void gemm_dma(const u16* __restrict__ X, long ldx, const u16* __restrict__ W, long ldw, int K, char* smem,
;                  int m0, int n0, const Epi& epi) {
;     ...
;     bf16x8 xf[MT];
; #pragma unroll
;     for (int i = 0; i < MT; ++i) xf[i] = *(const bf16x8*)(base + (xrow0 + i * 16) * 64 + rd);
; #pragma unroll
;     for (int nh = 0; nh < NT / 4; ++nh) {
;       bf16x8 wf[4];
; #pragma unroll
;       for (int i = 0; i < 4; ++i) wf[i] = *(const bf16x8*)(base + BM * 64 + (wrow0 + (nh * 4 + i) * 16) * 64 + rd);
; #pragma unroll
;       for (int i = 0; i < 4; ++i)
; #pragma unroll
;         for (int mt = 0; mt < MT; ++mt)
;           acc[nh * 4 + i][mt] = __builtin_amdgcn_mfma_f32_16x16x32_bf16(wf[i], xf[mt], acc[nh * 4 + i][mt], 0, 0, 0);
;     }
;   template <int NT, int MT> DI void run(f32x4 (&acc)[NT][MT], int mb, int nb) const {
;     ...
;     for (int nt = 0; nt < NT; ++nt)
; #pragma unroll
;       for (int mt = 0; mt < MT; ++mt) {
;         f32x4 v = acc[nt][mt];
;         st_bf4(C + (size_t)(mb + mt * 16) * ldc + nb + nt * 16, v[0], v[1], v[2], v[3]);
	v_mfma_f32_16x16x32_bf16 v[48:51], v[164:167], v[176:179], v[48:51]
	v_mfma_f32_16x16x32_bf16 v[52:55], v[164:167], v[172:175], v[52:55]
	v_mfma_f32_16x16x32_bf16 v[28:31], v[164:167], v[168:171], v[28:31]
	v_mfma_f32_16x16x32_bf16 v[56:59], v[160:163], v[186:189], v[56:59]
	v_mfma_f32_16x16x32_bf16 v[60:63], v[160:163], v[176:179], v[60:63]
	v_mfma_f32_16x16x32_bf16 v[64:67], v[160:163], v[172:175], v[64:67]
	v_mfma_f32_16x16x32_bf16 v[32:35], v[160:163], v[168:171], v[32:35]
	v_mfma_f32_16x16x32_bf16 v[68:71], v[156:159], v[186:189], v[68:71]
	v_mfma_f32_16x16x32_bf16 v[72:75], v[156:159], v[176:179], v[72:75]
	v_mfma_f32_16x16x32_bf16 v[76:79], v[156:159], v[172:175], v[76:79]
	v_mfma_f32_16x16x32_bf16 v[36:39], v[156:159], v[168:171], v[36:39]
	v_mfma_f32_16x16x32_bf16 v[156:159], v[152:155], v[186:189], v[80:83]
	v_mfma_f32_16x16x32_bf16 v[86:89], v[152:155], v[176:179], v[84:87]
	v_mfma_f32_16x16x32_bf16 v[92:95], v[152:155], v[172:175], v[92:95]
	v_mfma_f32_16x16x32_bf16 v[152:155], v[152:155], v[168:171], v[40:43]
	v_mfma_f32_16x16x32_bf16 v[112:115], v[148:151], v[186:189], v[112:115]
	v_mfma_f32_16x16x32_bf16 v[116:119], v[148:151], v[176:179], v[116:119]
	v_mfma_f32_16x16x32_bf16 v[120:123], v[148:151], v[172:175], v[120:123]
	v_mfma_f32_16x16x32_bf16 v[96:99], v[148:151], v[168:171], v[96:99]
	v_mfma_f32_16x16x32_bf16 v[124:127], v[108:111], v[186:189], v[124:127]
	v_mfma_f32_16x16x32_bf16 v[128:131], v[108:111], v[176:179], v[128:131]
	v_mfma_f32_16x16x32_bf16 v[132:135], v[108:111], v[172:175], v[132:135]
	v_mfma_f32_16x16x32_bf16 v[100:103], v[108:111], v[168:171], v[100:103]
	v_mfma_f32_16x16x32_bf16 v[108:111], v[24:27], v[186:189], v[136:139]
	v_mfma_f32_16x16x32_bf16 v[136:139], v[24:27], v[176:179], v[140:143]
	v_mfma_f32_16x16x32_bf16 v[140:143], v[24:27], v[172:175], v[144:147]
	v_mfma_f32_16x16x32_bf16 v[104:107], v[24:27], v[168:171], v[104:107]
	v_mfma_f32_16x16x32_bf16 v[6:9], v[20:23], v[186:189], v[6:9]
	v_mfma_f32_16x16x32_bf16 v[144:147], v[20:23], v[176:179], v[12:15]
	v_mfma_f32_16x16x32_bf16 v[148:151], v[20:23], v[172:175], v[16:19]
	v_mfma_f32_16x16x32_bf16 v[2:5], v[20:23], v[168:171], v[2:5]
	s_nop 0
	ds_read_b128 v[12:15], v11 offset:24576
	ds_read_b128 v[160:163], v11 offset:25600
	ds_read_b128 v[164:167], v11 offset:26624
	ds_read_b128 v[168:171], v11 offset:27648
	ds_read_b128 v[16:19], v10 offset:40960
	ds_read_b128 v[20:23], v10 offset:41984
	ds_read_b128 v[24:27], v10 offset:43008
	ds_read_b128 v[172:175], v10 offset:44032
	s_waitcnt lgkmcnt(3)
	v_mfma_f32_16x16x32_bf16 v[176:179], v[16:19], v[12:15], v[44:47]
	v_mfma_f32_16x16x32_bf16 v[186:189], v[16:19], v[160:163], v[48:51]
	v_mfma_f32_16x16x32_bf16 v[190:193], v[16:19], v[164:167], v[52:55]
	v_mfma_f32_16x16x32_bf16 v[194:197], v[16:19], v[168:171], v[28:31]
	s_waitcnt lgkmcnt(2)
	v_mfma_f32_16x16x32_bf16 v[224:227], v[20:23], v[12:15], v[56:59]
	v_mfma_f32_16x16x32_bf16 v[228:231], v[20:23], v[160:163], v[60:63]
	v_mfma_f32_16x16x32_bf16 v[232:235], v[20:23], v[164:167], v[64:67]
	v_mfma_f32_16x16x32_bf16 v[236:239], v[20:23], v[168:171], v[32:35]
	s_waitcnt lgkmcnt(1)
	v_mfma_f32_16x16x32_bf16 v[240:243], v[24:27], v[12:15], v[68:71]
	v_mfma_f32_16x16x32_bf16 v[66:69], v[24:27], v[168:171], v[36:39]
	s_waitcnt lgkmcnt(0)
	v_mfma_f32_16x16x32_bf16 v[42:45], v[172:175], v[164:167], v[92:95]
	v_mfma_f32_16x16x32_bf16 v[34:37], v[172:175], v[168:171], v[152:155]
	ds_read_b128 v[16:19], v10 offset:45056
	ds_read_b128 v[20:23], v10 offset:46080
	ds_read_b128 v[92:95], v10 offset:47104
	ds_read_b128 v[152:155], v10 offset:48128
	s_nop 0
	v_cvt_pk_bf16_f32 v66, v66, v67
	v_cvt_pk_bf16_f32 v67, v68, v69
	v_mfma_f32_16x16x32_bf16 v[82:85], v[24:27], v[160:163], v[72:75]
	v_cvt_pk_bf16_f32 v34, v34, v35
	v_cvt_pk_bf16_f32 v35, v36, v37
	v_cvt_pk_bf16_f32 v42, v42, v43
	v_mfma_f32_16x16x32_bf16 v[74:77], v[24:27], v[164:167], v[76:79]
	v_cvt_pk_bf16_f32 v43, v44, v45
	s_nop 2
	v_cvt_pk_bf16_f32 v82, v82, v83
	v_cvt_pk_bf16_f32 v83, v84, v85
	v_mfma_f32_16x16x32_bf16 v[50:53], v[172:175], v[160:163], v[86:89]
	s_waitcnt lgkmcnt(3)
	v_mfma_f32_16x16x32_bf16 v[112:115], v[16:19], v[12:15], v[112:115]
	v_cvt_pk_bf16_f32 v74, v74, v75
	v_cvt_pk_bf16_f32 v75, v76, v77
	s_nop 3
	v_cvt_pk_bf16_f32 v50, v50, v51
	v_mfma_f32_16x16x32_bf16 v[86:89], v[16:19], v[160:163], v[116:119]
	v_cvt_pk_bf16_f32 v51, v52, v53
	v_mfma_f32_16x16x32_bf16 v[78:81], v[16:19], v[164:167], v[120:123]
	v_mfma_f32_16x16x32_bf16 v[70:73], v[16:19], v[168:171], v[96:99]
	s_waitcnt lgkmcnt(2)
	v_mfma_f32_16x16x32_bf16 v[62:65], v[20:23], v[12:15], v[124:127]
	s_nop 0
	v_cvt_pk_bf16_f32 v96, v186, v187
	v_cvt_pk_bf16_f32 v97, v188, v189
	v_cvt_pk_bf16_f32 v98, v190, v191
	v_mfma_f32_16x16x32_bf16 v[54:57], v[20:23], v[160:163], v[128:131]
	v_cvt_pk_bf16_f32 v99, v192, v193
	v_mfma_f32_16x16x32_bf16 v[46:49], v[20:23], v[164:167], v[132:135]
	v_mfma_f32_16x16x32_bf16 v[38:41], v[20:23], v[168:171], v[100:103]
	s_waitcnt lgkmcnt(1)
; DI void st_bf4(u16* p, float a, float b, float c, float d) { *(uint2*)p = make_uint2(pk2(a, b), pk2(c, d)); }
; template <int BM, class Epi>
; DI void gemm_dma(const u16* __restrict__ X, long ldx, const u16* __restrict__ W, long ldw, int K, char* smem,
;                  int m0, int n0, const Epi& epi) {
;     ...
;     for (int nh = 0; nh < NT / 4; ++nh) {
;       bf16x8 wf[4];
; #pragma unroll
;       for (int i = 0; i < 4; ++i) wf[i] = *(const bf16x8*)(base + BM * 64 + (wrow0 + (nh * 4 + i) * 16) * 64 + rd);
; #pragma unroll
;       for (int i = 0; i < 4; ++i)
; #pragma unroll
;         for (int mt = 0; mt < MT; ++mt)
;           acc[nh * 4 + i][mt] = __builtin_amdgcn_mfma_f32_16x16x32_bf16(wf[i], xf[mt], acc[nh * 4 + i][mt], 0, 0, 0);
;     }
;   } while (++kt < nk);
;     ...
;   epi.run(acc, m0 + xrow0 + lr, n0 + wrow0 + 4 * g);
;   template <int NT, int MT> DI void run(f32x4 (&acc)[NT][MT], int mb, int nb) const {
; #pragma unroll
;     for (int nt = 0; nt < NT; ++nt)
; #pragma unroll
;       for (int mt = 0; mt < MT; ++mt) {
;         f32x4 v = acc[nt][mt];
;         st_bf4(C + (size_t)(mb + mt * 16) * ldc + nb + nt * 16, v[0], v[1], v[2], v[3]);
;       }
	v_mfma_f32_16x16x32_bf16 v[30:33], v[92:95], v[12:15], v[108:111]
	v_mfma_f32_16x16x32_bf16 v[26:29], v[92:95], v[160:163], v[136:139]
	v_mfma_f32_16x16x32_bf16 v[22:25], v[92:95], v[164:167], v[140:143]
	s_nop 5
	v_cvt_pk_bf16_f32 v30, v30, v31
	v_cvt_pk_bf16_f32 v31, v32, v33
	v_cvt_pk_bf16_f32 v26, v26, v27
	v_mfma_f32_16x16x32_bf16 v[18:21], v[92:95], v[168:171], v[104:107]
	v_or_b32_e32 v94, v91, v90
	v_ashrrev_i32_e32 v95, 31, v94
	v_lshlrev_b64 v[90:91], 11, v[94:95]
	v_lshl_add_u64 v[90:91], s[92:93], 0, v[90:91]
	v_bfe_u32 v1, v185, 4, 1
	v_mad_u32_u24 v182, v1, 24, v182
	v_lshl_add_u64 v[90:91], v[90:91], 0, v[182:183]
	v_cvt_pk_bf16_f32 v92, v176, v177
	v_cvt_pk_bf16_f32 v93, v178, v179
	v_mov_b32_e32 v100, v92
	v_mov_b32_e32 v101, v93
	v_or_b32_e32 v92, 16, v94
	v_ashrrev_i32_e32 v93, 31, v92
	v_lshlrev_b64 v[92:93], 11, v[92:93]
	v_lshl_add_u64 v[92:93], s[92:93], 0, v[92:93]
	v_lshl_add_u64 v[92:93], v[92:93], 0, v[182:183]
	v_mov_b32_e32 v104, v96
	v_mov_b32_e32 v105, v97
	v_or_b32_e32 v96, 32, v94
	v_or_b32_e32 v94, 48, v94
	v_ashrrev_i32_e32 v95, 31, v94
	v_lshlrev_b64 v[94:95], 11, v[94:95]
	v_ashrrev_i32_e32 v97, 31, v96
	v_lshl_add_u64 v[94:95], s[92:93], 0, v[94:95]
	v_lshlrev_b64 v[96:97], 11, v[96:97]
	v_lshl_add_u64 v[94:95], v[94:95], 0, v[182:183]
	v_lshl_add_u64 v[96:97], s[92:93], 0, v[96:97]
	v_mov_b32_e32 v110, v34
	v_mov_b32_e32 v111, v35
	v_cvt_pk_bf16_f32 v34, v112, v113
	v_cvt_pk_bf16_f32 v35, v114, v115
	v_lshl_add_u64 v[96:97], v[96:97], 0, v[182:183]
	v_mov_b32_e32 v116, v34
	v_mov_b32_e32 v117, v35
	v_cvt_pk_bf16_f32 v34, v86, v87
	v_cvt_pk_bf16_f32 v35, v88, v89
	v_mov_b32_e32 v120, v98
	v_mov_b32_e32 v121, v99
	v_cvt_pk_bf16_f32 v98, v194, v195
	v_cvt_pk_bf16_f32 v99, v196, v197
	v_mov_b32_e32 v124, v34
	v_mov_b32_e32 v125, v35
	v_cvt_pk_bf16_f32 v34, v78, v79
	v_cvt_pk_bf16_f32 v35, v80, v81
	v_mfma_f32_16x16x32_bf16 v[58:61], v[172:175], v[12:15], v[156:159]
	v_mov_b32_e32 v112, v98
	v_mov_b32_e32 v113, v99
	v_cvt_pk_bf16_f32 v98, v224, v225
	v_cvt_pk_bf16_f32 v99, v226, v227
	s_waitcnt lgkmcnt(0)
	v_mfma_f32_16x16x32_bf16 v[14:17], v[152:155], v[12:15], v[6:9]
	v_mov_b32_e32 v84, v34
	v_mov_b32_e32 v85, v35
	v_cvt_pk_bf16_f32 v34, v70, v71
	v_cvt_pk_bf16_f32 v35, v72, v73
	v_mfma_f32_16x16x32_bf16 v[10:13], v[152:155], v[160:163], v[144:147]
	v_mov_b32_e32 v102, v98
	v_mov_b32_e32 v103, v99
	s_nop 1
	v_permlane16_swap_b32_e32 v100, v102
	v_permlane16_swap_b32_e32 v101, v103
	global_store_dwordx4 v[90:91], v[100:103], off
	v_cvt_pk_bf16_f32 v98, v228, v229
	v_cvt_pk_bf16_f32 v99, v230, v231
	v_mfma_f32_16x16x32_bf16 v[6:9], v[152:155], v[164:167], v[148:151]
	v_mov_b32_e32 v76, v34
	v_mov_b32_e32 v77, v35
	v_cvt_pk_bf16_f32 v34, v62, v63
	v_cvt_pk_bf16_f32 v35, v64, v65
	v_mfma_f32_16x16x32_bf16 v[2:5], v[152:155], v[168:171], v[2:5]
	v_mov_b32_e32 v106, v98
	v_mov_b32_e32 v107, v99
	s_nop 1
	v_permlane16_swap_b32_e32 v104, v106
	v_permlane16_swap_b32_e32 v105, v107
	global_store_dwordx4 v[92:93], v[104:107], off
	v_cvt_pk_bf16_f32 v98, v232, v233
	v_cvt_pk_bf16_f32 v99, v234, v235
	v_mov_b32_e32 v118, v34
	v_mov_b32_e32 v119, v35
	s_nop 1
	v_permlane16_swap_b32_e32 v116, v118
	v_permlane16_swap_b32_e32 v117, v119
	global_store_dwordx4 v[90:91], v[116:119], off offset:128
	v_cvt_pk_bf16_f32 v34, v54, v55
	v_cvt_pk_bf16_f32 v35, v56, v57
	v_mov_b32_e32 v122, v98
	v_mov_b32_e32 v123, v99
	s_nop 1
	v_permlane16_swap_b32_e32 v120, v122
	v_permlane16_swap_b32_e32 v121, v123
	global_store_dwordx4 v[96:97], v[120:123], off
	v_cvt_pk_bf16_f32 v98, v236, v237
	v_cvt_pk_bf16_f32 v99, v238, v239
	v_mov_b32_e32 v126, v34
	v_mov_b32_e32 v127, v35
	s_nop 1
	v_permlane16_swap_b32_e32 v124, v126
	v_permlane16_swap_b32_e32 v125, v127
	global_store_dwordx4 v[92:93], v[124:127], off offset:128
	v_cvt_pk_bf16_f32 v34, v46, v47
	v_cvt_pk_bf16_f32 v35, v48, v49
	v_mov_b32_e32 v114, v98
	v_mov_b32_e32 v115, v99
	s_nop 1
	v_permlane16_swap_b32_e32 v112, v114
	v_permlane16_swap_b32_e32 v113, v115
	global_store_dwordx4 v[94:95], v[112:115], off
	v_cvt_pk_bf16_f32 v98, v240, v241
	v_cvt_pk_bf16_f32 v99, v242, v243
	v_cvt_pk_bf16_f32 v58, v58, v59
	v_cvt_pk_bf16_f32 v59, v60, v61
	v_mov_b32_e32 v86, v34
	v_mov_b32_e32 v87, v35
	s_nop 1
	v_permlane16_swap_b32_e32 v84, v86
	v_permlane16_swap_b32_e32 v85, v87
	global_store_dwordx4 v[96:97], v[84:87], off offset:128
	v_cvt_pk_bf16_f32 v34, v38, v39
	v_cvt_pk_bf16_f32 v35, v40, v41
	v_cvt_pk_bf16_f32 v27, v28, v29
	v_cvt_pk_bf16_f32 v22, v22, v23
	v_cvt_pk_bf16_f32 v23, v24, v25
	v_cvt_pk_bf16_f32 v18, v18, v19
	v_cvt_pk_bf16_f32 v19, v20, v21
	v_cvt_pk_bf16_f32 v14, v14, v15
	v_cvt_pk_bf16_f32 v15, v16, v17
	v_cvt_pk_bf16_f32 v10, v10, v11
	v_cvt_pk_bf16_f32 v11, v12, v13
	v_cvt_pk_bf16_f32 v6, v6, v7
	v_cvt_pk_bf16_f32 v7, v8, v9
	v_cvt_pk_bf16_f32 v2, v2, v3
	v_cvt_pk_bf16_f32 v3, v4, v5
	v_mov_b32_e32 v36, v98
	v_mov_b32_e32 v37, v99
	v_mov_b32_e32 v44, v82
	v_mov_b32_e32 v45, v83
	v_mov_b32_e32 v52, v74
	v_mov_b32_e32 v53, v75
	v_mov_b32_e32 v108, v66
	v_mov_b32_e32 v109, v67
	s_nop 1
	v_permlane16_swap_b32_e32 v108, v110
	v_permlane16_swap_b32_e32 v109, v111
	global_store_dwordx4 v[94:95], v[108:111], off offset:64
	v_mov_b32_e32 v38, v58
	v_mov_b32_e32 v39, v59
	s_nop 1
	v_permlane16_swap_b32_e32 v36, v38
	v_permlane16_swap_b32_e32 v37, v39
	global_store_dwordx4 v[90:91], v[36:39], off offset:64
	v_mov_b32_e32 v46, v50
	v_mov_b32_e32 v47, v51
	s_nop 1
	v_permlane16_swap_b32_e32 v44, v46
	v_permlane16_swap_b32_e32 v45, v47
	global_store_dwordx4 v[92:93], v[44:47], off offset:64
	v_mov_b32_e32 v54, v42
	v_mov_b32_e32 v55, v43
	s_nop 1
	v_permlane16_swap_b32_e32 v52, v54
	v_permlane16_swap_b32_e32 v53, v55
	global_store_dwordx4 v[96:97], v[52:55], off offset:64
	v_mov_b32_e32 v78, v34
	v_mov_b32_e32 v79, v35
	s_nop 1
	v_permlane16_swap_b32_e32 v76, v78
	v_permlane16_swap_b32_e32 v77, v79
	global_store_dwordx4 v[94:95], v[76:79], off offset:128
	v_mov_b32_e32 v36, v30
	v_mov_b32_e32 v37, v31
	v_mov_b32_e32 v44, v26
	v_mov_b32_e32 v45, v27
	v_mov_b32_e32 v52, v22
	v_mov_b32_e32 v53, v23
	v_mov_b32_e32 v60, v18
	v_mov_b32_e32 v61, v19
	v_mov_b32_e32 v38, v14
	v_mov_b32_e32 v39, v15
	s_nop 1
	v_permlane16_swap_b32_e32 v36, v38
	v_permlane16_swap_b32_e32 v37, v39
	global_store_dwordx4 v[90:91], v[36:39], off offset:192
	v_mov_b32_e32 v46, v10
	v_mov_b32_e32 v47, v11
	s_nop 1
	v_permlane16_swap_b32_e32 v44, v46
	v_permlane16_swap_b32_e32 v45, v47
	global_store_dwordx4 v[92:93], v[44:47], off offset:192
	v_mov_b32_e32 v54, v6
	v_mov_b32_e32 v55, v7
	s_nop 1
	v_permlane16_swap_b32_e32 v52, v54
	v_permlane16_swap_b32_e32 v53, v55
	global_store_dwordx4 v[96:97], v[52:55], off offset:192
	v_mov_b32_e32 v62, v2
	v_mov_b32_e32 v63, v3
	s_nop 1
	v_permlane16_swap_b32_e32 v60, v62
	v_permlane16_swap_b32_e32 v61, v63
	global_store_dwordx4 v[94:95], v[60:63], off offset:192

; DI int get_bid() { int b = blockIdx.x; asm volatile("" : "+s"(b)); return b; }
; template <int N> DI void wait_vm() { asm volatile("s_waitcnt vmcnt(%0)" ::"n"(N) : "memory"); }
; template <int BM, class Epi>
; DI void gemm_dma(const u16* __restrict__ X, long ldx, const u16* __restrict__ W, long ldw, int K, char* smem,
;                  int m0, int n0, const Epi& epi) {
;     ...
;   const int wu = __builtin_amdgcn_readfirstlane(wave);
;   const unsigned sbase = (unsigned)__builtin_amdgcn_readfirstlane((int)(unsigned)(size_t)smem);
;   const int r16 = lane >> 2, chunk = (lane & 3) ^ ((4 - (r16 >> 2)) & 3);
;   const u16* xs = X + (long)(wu * XD * 16 + r16) * ldx + (chunk << 3);
;   const u16* ws = W + (long)(wu * 32 + r16) * ldw + (chunk << 3);
;   const long ldx16 = 16 * ldx, ldw16 = 16 * ldw;
;   const unsigned xdst = sbase + wu * XD * 1024, wdst = sbase + BM * 64 + wu * 2048;
;     ...
;   const int nk = K >> 5;
;   __syncthreads();
; #pragma unroll
;   for (int s = 0; s < D - 1; ++s) GD_ISSUE(s)
;   int cur = 0, nxt = D - 1, kt = 0;
;   do {
;     if (kt + D - 2 < nk) wait_vm<PW * (D - 2)>(); else wait_vm<0>();
;     __syncthreads();
;     if (kt + D - 1 < nk) GD_ISSUE(nxt)
; DI void phase_odd(const Params& p, int o, int sub, char* smem) {
;     ...
;     for (int t = get_bid(); t < 1584 + 256; t += gridDim.x) {
;       if (t < 1584) {
;         const int tm = t / 12, tn = t % 12;
;         const int t2 = t + gridDim.x, tm2 = t2 / 12, tn2 = t2 % 12;
;         const bool nx = t2 < 1584;
;         gemm_tile<4>(qn + (size_t)tm * 128 * 384, 384, W + WO_Q + (size_t)tn * 128 * 384, 384, 384, smem, tm * 128, tn * 128, eq, pre,
;                      nx ? qn + (size_t)tm2 * 128 * 384 : nullptr, W + WO_Q + (size_t)tn2 * 128 * 384);
;         pre = nx;
;       } else {
;         knope_tile(p, t - 1584, smem);
.LBB0_99:
	s_cmpk_gt_i32 s5, 0x62f
	s_mov_b64 s[38:39], -1
	s_cbranch_scc0 .LBB0_101
	s_add_i32 s4, s5, 0xfffff9d0
	s_bfe_u32 s98, s4, 0x30003
	s_and_b32 s99, s4, 7
	s_lshl_b32 s99, s99, 3
	s_andn2_b32 s4, s4, 63
	s_or_b32 s4, s4, s99
	s_or_b32 s4, s4, s98
	s_lshr_b32 s6, s4, 3
	s_and_b32 s4, s4, 7
	s_lshl_b32 s7, s6, 17
	s_add_u32 s8, s0, s7
	s_addc_u32 s9, s1, 0
	s_lshl_b32 s7, s4, 16
	v_mov_b32_e32 v11, v185
	s_add_u32 s10, s87, s7
	s_addc_u32 s11, s90, 0
	v_readfirstlane_b32 s7, v11
	v_lshrrev_b32_e32 v6, 4, v11
	s_ashr_i32 s12, s7, 6
	v_bfe_u32 v8, v11, 2, 4
	v_sub_u32_e32 v6, 0, v6
	s_andn2_b32 s7, s7, 63
	v_lshrrev_b32_e32 v3, 2, v11
	v_xor_b32_e32 v9, v11, v6
	v_or_b32_e32 v6, s7, v8
	v_and_b32_e32 v90, 15, v11
	v_bfe_u32 v1, v11, 4, 2
	v_sub_u32_e32 v3, 0, v3
	v_ashrrev_i32_e32 v7, 31, v6
	v_lshlrev_b32_e32 v2, 6, v90
	v_bitop3_b32 v3, v1, v3, 3 bitop3:0x78
	v_lshlrev_b64 v[6:7], 9, v[6:7]
	v_lshlrev_b32_e32 v9, 4, v9
	v_lshl_or_b32 v8, s12, 5, v8
	v_lshl_or_b32 v10, v3, 4, v2
	v_mov_b32_e32 v2, v183
	v_lshl_add_u64 v[6:7], s[8:9], 0, v[6:7]
	v_and_b32_e32 v182, 48, v9
	v_ashrrev_i32_e32 v9, 31, v8
	v_lshl_add_u64 v[6:7], v[6:7], 0, v[182:183]
	v_lshlrev_b64 v[8:9], 9, v[8:9]
	s_lshl_b32 s14, s12, 12
	s_barrier
	s_mov_b32 m0, s14
	s_nop 0
	global_load_lds_dwordx4 v[6:7], off
	s_mov_b64 s[8:9], 0x2000
	v_lshl_add_u64 v[8:9], s[10:11], 0, v[8:9]
	v_lshl_add_u64 v[12:13], v[6:7], 0, s[8:9]
	s_or_b32 s15, s14, 0x400
	s_mov_b32 m0, s15
	s_nop 0
	global_load_lds_dwordx4 v[12:13], off
	s_mov_b64 s[10:11], 0x4000
	v_lshl_add_u64 v[12:13], v[6:7], 0, s[10:11]
	s_or_b32 s16, s14, 0x800
	s_mov_b32 m0, s16
	s_nop 0
	global_load_lds_dwordx4 v[12:13], off
	s_mov_b64 s[10:11], 0x6000
	s_lshl_b32 s42, s12, 11
	v_lshl_add_u64 v[12:13], v[6:7], 0, s[10:11]
	s_or_b32 s17, s14, 0xc00
	s_mov_b32 m0, s17
	s_nop 0
	global_load_lds_dwordx4 v[12:13], off
	v_lshl_add_u64 v[8:9], v[8:9], 0, v[182:183]
	s_add_i32 s13, s42, 0x4000
	s_mov_b32 m0, s13
	s_nop 0
	global_load_lds_dwordx4 v[8:9], off
	v_lshl_add_u64 v[12:13], v[8:9], 0, s[8:9]
	s_add_i32 s18, s42, 0x4400
	s_mov_b32 m0, s18
	s_nop 0
	global_load_lds_dwordx4 v[12:13], off
	v_lshl_add_u64 v[12:13], v[6:7], 0, 64
	s_add_i32 s7, s14, 0x6000
	s_mov_b32 m0, s7
	s_nop 0
	global_load_lds_dwordx4 v[12:13], off
	s_mov_b64 s[20:21], 0x2040
	v_lshl_add_u64 v[12:13], v[6:7], 0, s[20:21]
	s_add_i32 s8, s14, 0x6400
	s_mov_b32 m0, s8
	s_nop 0
	global_load_lds_dwordx4 v[12:13], off
	s_mov_b64 s[10:11], 0x4040
	v_lshl_add_u64 v[12:13], v[6:7], 0, s[10:11]
	s_add_i32 s9, s14, 0x6800
	s_mov_b32 m0, s9
	s_nop 0
	global_load_lds_dwordx4 v[12:13], off
	s_mov_b64 s[10:11], 0x6040
	v_lshl_add_u64 v[12:13], v[6:7], 0, s[10:11]
	s_add_i32 s10, s14, 0x6c00
	s_mov_b32 m0, s10
	s_nop 0
	global_load_lds_dwordx4 v[12:13], off
	v_lshl_add_u64 v[14:15], v[8:9], 0, 64
	s_add_i32 s11, s42, 0xa000
	s_mov_b32 m0, s11
	s_nop 0
	global_load_lds_dwordx4 v[14:15], off
	v_lshl_add_u64 v[12:13], v[8:9], 0, s[20:21]
	s_add_i32 s12, s42, 0xa400
	s_mov_b32 m0, s12
	s_nop 0
	global_load_lds_dwordx4 v[12:13], off
	s_waitcnt vmcnt(6)
	s_barrier
	v_lshl_add_u64 v[14:15], v[6:7], 0, s[28:29]
	s_add_i32 s19, s14, 0xc000
	s_mov_b32 m0, s19
	s_nop 0
	global_load_lds_dwordx4 v[14:15], off
	s_mov_b64 s[20:21], 0x2080
	v_lshl_add_u64 v[14:15], v[6:7], 0, s[20:21]
	s_add_i32 s34, s14, 0xc400
	s_mov_b32 m0, s34
	s_nop 0
	global_load_lds_dwordx4 v[14:15], off
	v_lshl_add_u64 v[14:15], v[6:7], 0, s[94:95]
	s_add_i32 s38, s14, 0xc800
	s_mov_b32 m0, s38
	s_nop 0
	global_load_lds_dwordx4 v[14:15], off
	s_mov_b64 s[22:23], 0x6080
	v_lshl_add_u64 v[14:15], v[6:7], 0, s[22:23]
	s_add_i32 s43, s14, 0xcc00
	s_mov_b32 m0, s43
	s_nop 0
	global_load_lds_dwordx4 v[14:15], off
	v_and_b32_e32 v91, 0xffffffc0, v11
	v_lshl_add_u64 v[12:13], v[8:9], 0, s[28:29]
	s_add_i32 s39, s42, 0x10000
	s_mov_b32 m0, s39
	s_nop 0
	global_load_lds_dwordx4 v[12:13], off
	v_lshl_add_u64 v[12:13], v[8:9], 0, s[20:21]
	s_add_i32 s42, s42, 0x10400
	s_mov_b32 m0, s42
	s_nop 0
	global_load_lds_dwordx4 v[12:13], off
	v_lshl_or_b32 v11, v91, 6, v10
	ds_read_b128 v[12:15], v11
	s_waitcnt vmcnt(7)
	ds_read_b128 v[16:19], v11 offset:1024
	s_waitcnt vmcnt(5)
	ds_read_b128 v[20:23], v11 offset:2048
	ds_read_b128 v[24:27], v11 offset:3072
	s_waitcnt vmcnt(4)
	ds_read_b128 v[28:31], v10 offset:16384
	ds_read_b128 v[32:35], v10 offset:17408
	ds_read_b128 v[36:39], v10 offset:18432
	ds_read_b128 v[40:43], v10 offset:19456
	s_waitcnt vmcnt(0)
	ds_read_b128 v[96:99], v10 offset:20480
	ds_read_b128 v[100:103], v10 offset:21504
	ds_read_b128 v[104:107], v10 offset:22528
	ds_read_b128 v[108:111], v10 offset:23552
	s_mov_b64 s[20:21], 0xc0
	v_mov_b32_e32 v3, v2
	v_mov_b32_e32 v4, v2
	v_mov_b32_e32 v5, v2
	v_lshl_add_u64 v[88:89], v[6:7], 0, s[20:21]
	v_lshl_add_u64 v[148:149], v[8:9], 0, s[20:21]
	s_waitcnt vmcnt(6)
	s_waitcnt lgkmcnt(0)
	s_barrier
; template <int N> DI void wait_vm() { asm volatile("s_waitcnt vmcnt(%0)" ::"n"(N) : "memory"); }
; template <int BM, class Epi>
; DI void gemm_dma(const u16* __restrict__ X, long ldx, const u16* __restrict__ W, long ldw, int K, char* smem,
;                  int m0, int n0, const Epi& epi) {
;     ...
;   do {
;     if (kt + D - 2 < nk) wait_vm<PW * (D - 2)>(); else wait_vm<0>();
;     __syncthreads();
;     if (kt + D - 1 < nk) GD_ISSUE(nxt)
;     nxt = (nxt + 1 == D) ? 0 : nxt + 1;
;     const char* base = smem + cur * STG;
;     cur = (cur + 1 == D) ? 0 : cur + 1;
;     bf16x8 xf[MT];
; #pragma unroll
;     for (int i = 0; i < MT; ++i) xf[i] = *(const bf16x8*)(base + (xrow0 + i * 16) * 64 + rd);
; #pragma unroll
;     for (int nh = 0; nh < NT / 4; ++nh) {
;       bf16x8 wf[4];
; #pragma unroll
;       for (int i = 0; i < 4; ++i) wf[i] = *(const bf16x8*)(base + BM * 64 + (wrow0 + (nh * 4 + i) * 16) * 64 + rd);
; #pragma unroll
;       for (int i = 0; i < 4; ++i)
; #pragma unroll
;         for (int mt = 0; mt < MT; ++mt)
;           acc[nh * 4 + i][mt] = __builtin_amdgcn_mfma_f32_16x16x32_bf16(wf[i], xf[mt], acc[nh * 4 + i][mt], 0, 0, 0);
;     }
;   } while (++kt < nk);
	s_mov_b32 m0, s14
	s_nop 0
	global_load_lds_dwordx4 v[88:89], off
	s_mov_b64 s[20:21], 0x20c0
	v_mfma_f32_16x16x32_bf16 v[44:47], v[28:31], v[12:15], v[2:5]
	s_mov_b64 s[22:23], 0x40c0
	v_or_b32_e32 v174, 0x10000, v10
	v_or_b32_e32 v175, 0x10400, v10
	v_mfma_f32_16x16x32_bf16 v[48:51], v[28:31], v[16:19], v[2:5]
	v_or_b32_e32 v176, 0x10800, v10
	v_or_b32_e32 v177, 0x10c00, v10
	v_or_b32_e32 v178, 0x11000, v10
	v_mfma_f32_16x16x32_bf16 v[52:55], v[28:31], v[20:23], v[2:5]
	v_or_b32_e32 v179, 0x11400, v10
	v_or_b32_e32 v180, 0x11800, v10
	v_or_b32_e32 v181, 0x11c00, v10
	v_mfma_f32_16x16x32_bf16 v[28:31], v[28:31], v[24:27], v[2:5]
	v_lshl_add_u32 v91, s6, 8, v91
	s_lshl_b32 s4, s4, 8
	v_lshl_or_b32 v182, v1, 3, s4
	v_mfma_f32_16x16x32_bf16 v[56:59], v[32:35], v[12:15], v[2:5]
	v_mfma_f32_16x16x32_bf16 v[60:63], v[32:35], v[16:19], v[2:5]
	v_mfma_f32_16x16x32_bf16 v[64:67], v[32:35], v[20:23], v[2:5]
	v_mfma_f32_16x16x32_bf16 v[32:35], v[32:35], v[24:27], v[2:5]
	v_mfma_f32_16x16x32_bf16 v[68:71], v[36:39], v[12:15], v[2:5]
	v_mfma_f32_16x16x32_bf16 v[72:75], v[36:39], v[16:19], v[2:5]
	v_mfma_f32_16x16x32_bf16 v[76:79], v[36:39], v[20:23], v[2:5]
	v_mfma_f32_16x16x32_bf16 v[36:39], v[36:39], v[24:27], v[2:5]
	v_mfma_f32_16x16x32_bf16 v[80:83], v[40:43], v[12:15], v[2:5]
	v_mfma_f32_16x16x32_bf16 v[84:87], v[40:43], v[16:19], v[2:5]
	v_mfma_f32_16x16x32_bf16 v[92:95], v[40:43], v[20:23], v[2:5]
	v_mfma_f32_16x16x32_bf16 v[40:43], v[40:43], v[24:27], v[2:5]
	v_mfma_f32_16x16x32_bf16 v[112:115], v[96:99], v[12:15], v[2:5]
	v_mfma_f32_16x16x32_bf16 v[116:119], v[96:99], v[16:19], v[2:5]
	v_mfma_f32_16x16x32_bf16 v[120:123], v[96:99], v[20:23], v[2:5]
	v_mfma_f32_16x16x32_bf16 v[96:99], v[96:99], v[24:27], v[2:5]
	v_mfma_f32_16x16x32_bf16 v[124:127], v[100:103], v[12:15], v[2:5]
	v_mfma_f32_16x16x32_bf16 v[128:131], v[100:103], v[16:19], v[2:5]
	v_mfma_f32_16x16x32_bf16 v[132:135], v[100:103], v[20:23], v[2:5]
	v_mfma_f32_16x16x32_bf16 v[100:103], v[100:103], v[24:27], v[2:5]
	v_mfma_f32_16x16x32_bf16 v[136:139], v[104:107], v[12:15], v[2:5]
	v_mfma_f32_16x16x32_bf16 v[140:143], v[104:107], v[16:19], v[2:5]
	v_mfma_f32_16x16x32_bf16 v[144:147], v[104:107], v[20:23], v[2:5]
	v_mfma_f32_16x16x32_bf16 v[104:107], v[104:107], v[24:27], v[2:5]
	v_mfma_f32_16x16x32_bf16 v[12:15], v[108:111], v[12:15], v[2:5]
	v_mfma_f32_16x16x32_bf16 v[16:19], v[108:111], v[16:19], v[2:5]
	v_mfma_f32_16x16x32_bf16 v[20:23], v[108:111], v[20:23], v[2:5]
	v_mfma_f32_16x16x32_bf16 v[2:5], v[108:111], v[24:27], v[2:5]
	v_lshl_add_u64 v[24:25], v[6:7], 0, s[20:21]
	s_mov_b32 m0, s15
	s_nop 0
	global_load_lds_dwordx4 v[24:25], off
	v_lshl_add_u64 v[24:25], v[6:7], 0, s[22:23]
	s_mov_b32 m0, s16
	s_nop 0
	global_load_lds_dwordx4 v[24:25], off
	s_mov_b64 s[22:23], 0x60c0
	v_lshl_add_u64 v[24:25], v[6:7], 0, s[22:23]
	s_mov_b32 m0, s17
	s_nop 0
	global_load_lds_dwordx4 v[24:25], off
	v_lshl_add_u64 v[24:25], v[8:9], 0, s[20:21]
	s_mov_b32 m0, s13
	s_nop 0
	global_load_lds_dwordx4 v[148:149], off
	s_mov_b64 s[20:21], 0x100
	s_mov_b32 m0, s18
	s_nop 0
	global_load_lds_dwordx4 v[24:25], off
	ds_read_b128 v[24:27], v11 offset:24576
	ds_read_b128 v[108:111], v11 offset:25600
	ds_read_b128 v[148:151], v11 offset:26624
	ds_read_b128 v[152:155], v11 offset:27648
	ds_read_b128 v[156:159], v10 offset:40960
	ds_read_b128 v[160:163], v10 offset:41984
	ds_read_b128 v[164:167], v10 offset:43008
	ds_read_b128 v[168:171], v10 offset:44032
	s_waitcnt lgkmcnt(3)
	v_mfma_f32_16x16x32_bf16 v[44:47], v[156:159], v[24:27], v[44:47]
	v_lshl_add_u64 v[88:89], v[6:7], 0, s[20:21]
	v_lshl_add_u64 v[172:173], v[8:9], 0, s[20:21]
	s_mov_b64 s[20:21], 0x2100
	v_mfma_f32_16x16x32_bf16 v[48:51], v[156:159], v[108:111], v[48:51]
	s_mov_b64 s[22:23], 0x4100
	v_mfma_f32_16x16x32_bf16 v[52:55], v[156:159], v[148:151], v[52:55]
	v_mfma_f32_16x16x32_bf16 v[28:31], v[156:159], v[152:155], v[28:31]
	s_waitcnt lgkmcnt(2)
	v_mfma_f32_16x16x32_bf16 v[56:59], v[160:163], v[24:27], v[56:59]
	v_mfma_f32_16x16x32_bf16 v[60:63], v[160:163], v[108:111], v[60:63]
	v_mfma_f32_16x16x32_bf16 v[64:67], v[160:163], v[148:151], v[64:67]
	v_mfma_f32_16x16x32_bf16 v[32:35], v[160:163], v[152:155], v[32:35]
	s_waitcnt lgkmcnt(1)
	v_mfma_f32_16x16x32_bf16 v[68:71], v[164:167], v[24:27], v[68:71]
	v_mfma_f32_16x16x32_bf16 v[72:75], v[164:167], v[108:111], v[72:75]
	v_mfma_f32_16x16x32_bf16 v[76:79], v[164:167], v[148:151], v[76:79]
	v_mfma_f32_16x16x32_bf16 v[36:39], v[164:167], v[152:155], v[36:39]
	s_waitcnt lgkmcnt(0)
	v_mfma_f32_16x16x32_bf16 v[80:83], v[168:171], v[24:27], v[80:83]
	v_mfma_f32_16x16x32_bf16 v[84:87], v[168:171], v[108:111], v[84:87]
	v_mfma_f32_16x16x32_bf16 v[92:95], v[168:171], v[148:151], v[92:95]
	v_mfma_f32_16x16x32_bf16 v[40:43], v[168:171], v[152:155], v[40:43]
	ds_read_b128 v[156:159], v10 offset:45056
	ds_read_b128 v[160:163], v10 offset:46080
	ds_read_b128 v[164:167], v10 offset:47104
	ds_read_b128 v[168:171], v10 offset:48128
	s_waitcnt vmcnt(6)
	s_waitcnt lgkmcnt(0)
	s_barrier
; template <int N> DI void wait_vm() { asm volatile("s_waitcnt vmcnt(%0)" ::"n"(N) : "memory"); }
; template <int BM, class Epi>
; DI void gemm_dma(const u16* __restrict__ X, long ldx, const u16* __restrict__ W, long ldw, int K, char* smem,
;                  int m0, int n0, const Epi& epi) {
;     ...
;   do {
;     if (kt + D - 2 < nk) wait_vm<PW * (D - 2)>(); else wait_vm<0>();
;     __syncthreads();
;     if (kt + D - 1 < nk) GD_ISSUE(nxt)
;     nxt = (nxt + 1 == D) ? 0 : nxt + 1;
;     const char* base = smem + cur * STG;
;     cur = (cur + 1 == D) ? 0 : cur + 1;
;     bf16x8 xf[MT];
; #pragma unroll
;     for (int i = 0; i < MT; ++i) xf[i] = *(const bf16x8*)(base + (xrow0 + i * 16) * 64 + rd);
; #pragma unroll
;     for (int nh = 0; nh < NT / 4; ++nh) {
;       bf16x8 wf[4];
; #pragma unroll
;       for (int i = 0; i < 4; ++i) wf[i] = *(const bf16x8*)(base + BM * 64 + (wrow0 + (nh * 4 + i) * 16) * 64 + rd);
; #pragma unroll
;       for (int i = 0; i < 4; ++i)
; #pragma unroll
;         for (int mt = 0; mt < MT; ++mt)
;           acc[nh * 4 + i][mt] = __builtin_amdgcn_mfma_f32_16x16x32_bf16(wf[i], xf[mt], acc[nh * 4 + i][mt], 0, 0, 0);
;     }
;   } while (++kt < nk);
	s_mov_b32 m0, s7
	s_nop 0
	global_load_lds_dwordx4 v[88:89], off
	v_mfma_f32_16x16x32_bf16 v[112:115], v[156:159], v[24:27], v[112:115]
	v_mfma_f32_16x16x32_bf16 v[124:127], v[160:163], v[24:27], v[124:127]
	v_mfma_f32_16x16x32_bf16 v[136:139], v[164:167], v[24:27], v[136:139]
	v_mfma_f32_16x16x32_bf16 v[12:15], v[168:171], v[24:27], v[12:15]
	v_lshl_add_u64 v[24:25], v[6:7], 0, s[20:21]
	s_mov_b32 m0, s8
	s_nop 0
	global_load_lds_dwordx4 v[24:25], off
	v_lshl_add_u64 v[24:25], v[6:7], 0, s[22:23]
	s_mov_b32 m0, s9
	s_nop 0
	global_load_lds_dwordx4 v[24:25], off
	s_mov_b64 s[22:23], 0x6100
	v_lshl_add_u64 v[24:25], v[6:7], 0, s[22:23]
	s_mov_b32 m0, s10
	s_nop 0
	global_load_lds_dwordx4 v[24:25], off
	v_lshl_add_u64 v[24:25], v[8:9], 0, s[20:21]
	s_mov_b32 m0, s11
	s_nop 0
	global_load_lds_dwordx4 v[172:173], off
	v_mfma_f32_16x16x32_bf16 v[116:119], v[156:159], v[108:111], v[116:119]
	s_mov_b32 m0, s12
	s_nop 0
	global_load_lds_dwordx4 v[24:25], off
	s_mov_b64 s[20:21], 0x140
	v_lshl_add_u64 v[88:89], v[6:7], 0, s[20:21]
	v_mfma_f32_16x16x32_bf16 v[120:123], v[156:159], v[148:151], v[120:123]
	v_lshl_add_u64 v[172:173], v[8:9], 0, s[20:21]
	s_mov_b64 s[20:21], 0x2140
	s_mov_b64 s[22:23], 0x4140
	v_mfma_f32_16x16x32_bf16 v[96:99], v[156:159], v[152:155], v[96:99]
	v_mfma_f32_16x16x32_bf16 v[128:131], v[160:163], v[108:111], v[128:131]
	v_mfma_f32_16x16x32_bf16 v[132:135], v[160:163], v[148:151], v[132:135]
	v_mfma_f32_16x16x32_bf16 v[100:103], v[160:163], v[152:155], v[100:103]
	v_mfma_f32_16x16x32_bf16 v[140:143], v[164:167], v[108:111], v[140:143]
	v_mfma_f32_16x16x32_bf16 v[144:147], v[164:167], v[148:151], v[144:147]
	v_mfma_f32_16x16x32_bf16 v[104:107], v[164:167], v[152:155], v[104:107]
	v_mfma_f32_16x16x32_bf16 v[16:19], v[168:171], v[108:111], v[16:19]
	v_mfma_f32_16x16x32_bf16 v[20:23], v[168:171], v[148:151], v[20:23]
	v_mfma_f32_16x16x32_bf16 v[2:5], v[168:171], v[152:155], v[2:5]
	ds_read_b128 v[24:27], v11 offset:49152
	ds_read_b128 v[108:111], v11 offset:50176
	ds_read_b128 v[148:151], v11 offset:51200
	ds_read_b128 v[152:155], v11 offset:52224
	ds_read_b128 v[156:159], v174
	ds_read_b128 v[160:163], v175
	ds_read_b128 v[164:167], v176
	ds_read_b128 v[168:171], v177
	s_waitcnt lgkmcnt(3)
	v_mfma_f32_16x16x32_bf16 v[44:47], v[156:159], v[24:27], v[44:47]
	v_mfma_f32_16x16x32_bf16 v[48:51], v[156:159], v[108:111], v[48:51]
	v_mfma_f32_16x16x32_bf16 v[52:55], v[156:159], v[148:151], v[52:55]
	v_mfma_f32_16x16x32_bf16 v[28:31], v[156:159], v[152:155], v[28:31]
	ds_read_b128 v[156:159], v178
	s_waitcnt lgkmcnt(3)
	v_mfma_f32_16x16x32_bf16 v[56:59], v[160:163], v[24:27], v[56:59]
	v_mfma_f32_16x16x32_bf16 v[60:63], v[160:163], v[108:111], v[60:63]
	v_mfma_f32_16x16x32_bf16 v[64:67], v[160:163], v[148:151], v[64:67]
	v_mfma_f32_16x16x32_bf16 v[32:35], v[160:163], v[152:155], v[32:35]
	ds_read_b128 v[160:163], v179
	s_waitcnt lgkmcnt(3)
	v_mfma_f32_16x16x32_bf16 v[68:71], v[164:167], v[24:27], v[68:71]
	v_mfma_f32_16x16x32_bf16 v[72:75], v[164:167], v[108:111], v[72:75]
	v_mfma_f32_16x16x32_bf16 v[76:79], v[164:167], v[148:151], v[76:79]
	v_mfma_f32_16x16x32_bf16 v[36:39], v[164:167], v[152:155], v[36:39]
	ds_read_b128 v[164:167], v180
	s_waitcnt lgkmcnt(3)
	v_mfma_f32_16x16x32_bf16 v[80:83], v[168:171], v[24:27], v[80:83]
	v_mfma_f32_16x16x32_bf16 v[84:87], v[168:171], v[108:111], v[84:87]
	v_mfma_f32_16x16x32_bf16 v[92:95], v[168:171], v[148:151], v[92:95]
	v_mfma_f32_16x16x32_bf16 v[40:43], v[168:171], v[152:155], v[40:43]
	ds_read_b128 v[168:171], v181
	s_waitcnt vmcnt(6)
	s_waitcnt lgkmcnt(0)
	s_barrier
	s_mov_b32 m0, s19
	s_nop 0
	global_load_lds_dwordx4 v[88:89], off
	v_mfma_f32_16x16x32_bf16 v[112:115], v[156:159], v[24:27], v[112:115]
	v_mfma_f32_16x16x32_bf16 v[124:127], v[160:163], v[24:27], v[124:127]
	v_mfma_f32_16x16x32_bf16 v[136:139], v[164:167], v[24:27], v[136:139]
	v_mfma_f32_16x16x32_bf16 v[12:15], v[168:171], v[24:27], v[12:15]
	v_lshl_add_u64 v[24:25], v[6:7], 0, s[20:21]
	s_mov_b32 m0, s34
	s_nop 0
	global_load_lds_dwordx4 v[24:25], off
	v_lshl_add_u64 v[24:25], v[6:7], 0, s[22:23]
	s_mov_b32 m0, s38
	s_nop 0
	global_load_lds_dwordx4 v[24:25], off
	s_mov_b64 s[22:23], 0x6140
	v_lshl_add_u64 v[24:25], v[6:7], 0, s[22:23]
	s_mov_b32 m0, s43
	s_nop 0
	global_load_lds_dwordx4 v[24:25], off
	v_lshl_add_u64 v[24:25], v[8:9], 0, s[20:21]
	s_mov_b32 m0, s39
	s_nop 0
	global_load_lds_dwordx4 v[172:173], off
	v_mfma_f32_16x16x32_bf16 v[116:119], v[156:159], v[108:111], v[116:119]
	s_mov_b32 m0, s42
	s_nop 0
	global_load_lds_dwordx4 v[24:25], off
	s_mov_b64 s[20:21], 0x180
	v_lshl_add_u64 v[88:89], v[6:7], 0, s[20:21]
	v_mfma_f32_16x16x32_bf16 v[120:123], v[156:159], v[148:151], v[120:123]
	v_lshl_add_u64 v[172:173], v[8:9], 0, s[20:21]
	s_mov_b64 s[20:21], 0x2180
	s_mov_b64 s[38:39], 0
	v_mfma_f32_16x16x32_bf16 v[96:99], v[156:159], v[152:155], v[96:99]
	v_mfma_f32_16x16x32_bf16 v[128:131], v[160:163], v[108:111], v[128:131]
	v_mfma_f32_16x16x32_bf16 v[132:135], v[160:163], v[148:151], v[132:135]
	v_mfma_f32_16x16x32_bf16 v[100:103], v[160:163], v[152:155], v[100:103]
	v_mfma_f32_16x16x32_bf16 v[140:143], v[164:167], v[108:111], v[140:143]
	v_mfma_f32_16x16x32_bf16 v[144:147], v[164:167], v[148:151], v[144:147]
	v_mfma_f32_16x16x32_bf16 v[104:107], v[164:167], v[152:155], v[104:107]
	v_mfma_f32_16x16x32_bf16 v[16:19], v[168:171], v[108:111], v[16:19]
	v_mfma_f32_16x16x32_bf16 v[20:23], v[168:171], v[148:151], v[20:23]
	v_mfma_f32_16x16x32_bf16 v[2:5], v[168:171], v[152:155], v[2:5]
	ds_read_b128 v[24:27], v11
	ds_read_b128 v[108:111], v11 offset:1024
	ds_read_b128 v[148:151], v11 offset:2048
	ds_read_b128 v[152:155], v11 offset:3072
	ds_read_b128 v[156:159], v10 offset:16384
	ds_read_b128 v[160:163], v10 offset:17408
	ds_read_b128 v[164:167], v10 offset:18432
	ds_read_b128 v[168:171], v10 offset:19456
	s_waitcnt lgkmcnt(3)
; template <int N> DI void wait_vm() { asm volatile("s_waitcnt vmcnt(%0)" ::"n"(N) : "memory"); }
; template <int BM, class Epi>
; DI void gemm_dma(const u16* __restrict__ X, long ldx, const u16* __restrict__ W, long ldw, int K, char* smem,
;                  int m0, int n0, const Epi& epi) {
;     ...
;   do {
;     if (kt + D - 2 < nk) wait_vm<PW * (D - 2)>(); else wait_vm<0>();
;     __syncthreads();
;     if (kt + D - 1 < nk) GD_ISSUE(nxt)
;     nxt = (nxt + 1 == D) ? 0 : nxt + 1;
;     const char* base = smem + cur * STG;
;     cur = (cur + 1 == D) ? 0 : cur + 1;
;     bf16x8 xf[MT];
; #pragma unroll
;     for (int i = 0; i < MT; ++i) xf[i] = *(const bf16x8*)(base + (xrow0 + i * 16) * 64 + rd);
; #pragma unroll
;     for (int nh = 0; nh < NT / 4; ++nh) {
;       bf16x8 wf[4];
; #pragma unroll
;       for (int i = 0; i < 4; ++i) wf[i] = *(const bf16x8*)(base + BM * 64 + (wrow0 + (nh * 4 + i) * 16) * 64 + rd);
; #pragma unroll
;       for (int i = 0; i < 4; ++i)
; #pragma unroll
;         for (int mt = 0; mt < MT; ++mt)
;           acc[nh * 4 + i][mt] = __builtin_amdgcn_mfma_f32_16x16x32_bf16(wf[i], xf[mt], acc[nh * 4 + i][mt], 0, 0, 0);
;     }
;   } while (++kt < nk);
	v_mfma_f32_16x16x32_bf16 v[44:47], v[156:159], v[24:27], v[44:47]
	v_mfma_f32_16x16x32_bf16 v[48:51], v[156:159], v[108:111], v[48:51]
	v_mfma_f32_16x16x32_bf16 v[52:55], v[156:159], v[148:151], v[52:55]
	v_mfma_f32_16x16x32_bf16 v[28:31], v[156:159], v[152:155], v[28:31]
	s_waitcnt lgkmcnt(2)
	v_mfma_f32_16x16x32_bf16 v[56:59], v[160:163], v[24:27], v[56:59]
	v_mfma_f32_16x16x32_bf16 v[60:63], v[160:163], v[108:111], v[60:63]
	v_mfma_f32_16x16x32_bf16 v[64:67], v[160:163], v[148:151], v[64:67]
	v_mfma_f32_16x16x32_bf16 v[32:35], v[160:163], v[152:155], v[32:35]
	s_waitcnt lgkmcnt(1)
	v_mfma_f32_16x16x32_bf16 v[68:71], v[164:167], v[24:27], v[68:71]
	v_mfma_f32_16x16x32_bf16 v[72:75], v[164:167], v[108:111], v[72:75]
	v_mfma_f32_16x16x32_bf16 v[76:79], v[164:167], v[148:151], v[76:79]
	v_mfma_f32_16x16x32_bf16 v[36:39], v[164:167], v[152:155], v[36:39]
	s_waitcnt lgkmcnt(0)
	v_mfma_f32_16x16x32_bf16 v[80:83], v[168:171], v[24:27], v[80:83]
	v_mfma_f32_16x16x32_bf16 v[84:87], v[168:171], v[108:111], v[84:87]
	v_mfma_f32_16x16x32_bf16 v[92:95], v[168:171], v[148:151], v[92:95]
	v_mfma_f32_16x16x32_bf16 v[40:43], v[168:171], v[152:155], v[40:43]
	ds_read_b128 v[156:159], v10 offset:20480
	ds_read_b128 v[160:163], v10 offset:21504
	ds_read_b128 v[164:167], v10 offset:22528
	ds_read_b128 v[168:171], v10 offset:23552
	s_waitcnt vmcnt(6)
	s_waitcnt lgkmcnt(0)
	s_barrier
	s_mov_b32 m0, s14
	s_nop 0
	global_load_lds_dwordx4 v[88:89], off
	v_mfma_f32_16x16x32_bf16 v[112:115], v[156:159], v[24:27], v[112:115]
	v_mfma_f32_16x16x32_bf16 v[124:127], v[160:163], v[24:27], v[124:127]
	v_mfma_f32_16x16x32_bf16 v[136:139], v[164:167], v[24:27], v[136:139]
	v_mfma_f32_16x16x32_bf16 v[12:15], v[168:171], v[24:27], v[12:15]
	v_lshl_add_u64 v[24:25], v[6:7], 0, s[20:21]
	s_mov_b32 m0, s15
	s_nop 0
	global_load_lds_dwordx4 v[24:25], off
	s_mov_b64 s[14:15], 0x4180
	v_lshl_add_u64 v[24:25], v[6:7], 0, s[14:15]
	s_mov_b32 m0, s16
	s_nop 0
	global_load_lds_dwordx4 v[24:25], off
	s_mov_b64 s[14:15], 0x6180
	v_lshl_add_u64 v[24:25], v[6:7], 0, s[14:15]
	s_mov_b32 m0, s17
	s_nop 0
	global_load_lds_dwordx4 v[24:25], off
	v_lshl_add_u64 v[24:25], v[8:9], 0, s[20:21]
	s_mov_b32 m0, s13
	s_nop 0
	global_load_lds_dwordx4 v[172:173], off
	s_mov_b32 m0, s18
	s_nop 0
	global_load_lds_dwordx4 v[24:25], off
	v_mfma_f32_16x16x32_bf16 v[116:119], v[156:159], v[108:111], v[116:119]
	s_mov_b64 s[14:15], 0x1c0
	v_lshl_add_u64 v[88:89], v[6:7], 0, s[14:15]
	v_lshl_add_u64 v[172:173], v[8:9], 0, s[14:15]
	v_mfma_f32_16x16x32_bf16 v[120:123], v[156:159], v[148:151], v[120:123]
	s_mov_b64 s[14:15], 0x21c0
	s_mov_b64 s[16:17], 0x41c0
	v_mfma_f32_16x16x32_bf16 v[96:99], v[156:159], v[152:155], v[96:99]
	v_mfma_f32_16x16x32_bf16 v[128:131], v[160:163], v[108:111], v[128:131]
	v_mfma_f32_16x16x32_bf16 v[132:135], v[160:163], v[148:151], v[132:135]
	v_mfma_f32_16x16x32_bf16 v[100:103], v[160:163], v[152:155], v[100:103]
	v_mfma_f32_16x16x32_bf16 v[140:143], v[164:167], v[108:111], v[140:143]
	v_mfma_f32_16x16x32_bf16 v[144:147], v[164:167], v[148:151], v[144:147]
	v_mfma_f32_16x16x32_bf16 v[104:107], v[164:167], v[152:155], v[104:107]
	v_mfma_f32_16x16x32_bf16 v[16:19], v[168:171], v[108:111], v[16:19]
	v_mfma_f32_16x16x32_bf16 v[20:23], v[168:171], v[148:151], v[20:23]
	v_mfma_f32_16x16x32_bf16 v[2:5], v[168:171], v[152:155], v[2:5]
	ds_read_b128 v[24:27], v11 offset:24576
	ds_read_b128 v[108:111], v11 offset:25600
	ds_read_b128 v[148:151], v11 offset:26624
	ds_read_b128 v[152:155], v11 offset:27648
	ds_read_b128 v[156:159], v10 offset:40960
	ds_read_b128 v[160:163], v10 offset:41984
	ds_read_b128 v[164:167], v10 offset:43008
	ds_read_b128 v[168:171], v10 offset:44032
	s_waitcnt lgkmcnt(3)
	v_mfma_f32_16x16x32_bf16 v[44:47], v[156:159], v[24:27], v[44:47]
	v_mfma_f32_16x16x32_bf16 v[48:51], v[156:159], v[108:111], v[48:51]
	v_mfma_f32_16x16x32_bf16 v[52:55], v[156:159], v[148:151], v[52:55]
	v_mfma_f32_16x16x32_bf16 v[28:31], v[156:159], v[152:155], v[28:31]
	s_waitcnt lgkmcnt(2)
	v_mfma_f32_16x16x32_bf16 v[56:59], v[160:163], v[24:27], v[56:59]
	v_mfma_f32_16x16x32_bf16 v[60:63], v[160:163], v[108:111], v[60:63]
	v_mfma_f32_16x16x32_bf16 v[64:67], v[160:163], v[148:151], v[64:67]
	v_mfma_f32_16x16x32_bf16 v[32:35], v[160:163], v[152:155], v[32:35]
	s_waitcnt lgkmcnt(1)
	v_mfma_f32_16x16x32_bf16 v[68:71], v[164:167], v[24:27], v[68:71]
	v_mfma_f32_16x16x32_bf16 v[72:75], v[164:167], v[108:111], v[72:75]
	v_mfma_f32_16x16x32_bf16 v[76:79], v[164:167], v[148:151], v[76:79]
	v_mfma_f32_16x16x32_bf16 v[36:39], v[164:167], v[152:155], v[36:39]
	s_waitcnt lgkmcnt(0)
	v_mfma_f32_16x16x32_bf16 v[80:83], v[168:171], v[24:27], v[80:83]
	v_mfma_f32_16x16x32_bf16 v[84:87], v[168:171], v[108:111], v[84:87]
	v_mfma_f32_16x16x32_bf16 v[92:95], v[168:171], v[148:151], v[92:95]
	v_mfma_f32_16x16x32_bf16 v[40:43], v[168:171], v[152:155], v[40:43]
	ds_read_b128 v[156:159], v10 offset:45056
	ds_read_b128 v[160:163], v10 offset:46080
	ds_read_b128 v[164:167], v10 offset:47104
	ds_read_b128 v[168:171], v10 offset:48128
	s_waitcnt vmcnt(6)
	s_waitcnt lgkmcnt(0)
	s_barrier
; DI int get_bid() { int b = blockIdx.x; asm volatile("" : "+s"(b)); return b; }
; template <int N> DI void wait_vm() { asm volatile("s_waitcnt vmcnt(%0)" ::"n"(N) : "memory"); }
; template <int BM, class Epi>
; DI void gemm_dma(const u16* __restrict__ X, long ldx, const u16* __restrict__ W, long ldw, int K, char* smem,
;                  int m0, int n0, const Epi& epi) {
;     ...
;   do {
;     if (kt + D - 2 < nk) wait_vm<PW * (D - 2)>(); else wait_vm<0>();
;     __syncthreads();
;     if (kt + D - 1 < nk) GD_ISSUE(nxt)
;     nxt = (nxt + 1 == D) ? 0 : nxt + 1;
;     const char* base = smem + cur * STG;
;     cur = (cur + 1 == D) ? 0 : cur + 1;
;     bf16x8 xf[MT];
; #pragma unroll
;     for (int i = 0; i < MT; ++i) xf[i] = *(const bf16x8*)(base + (xrow0 + i * 16) * 64 + rd);
; #pragma unroll
;     for (int nh = 0; nh < NT / 4; ++nh) {
;       bf16x8 wf[4];
; #pragma unroll
;       for (int i = 0; i < 4; ++i) wf[i] = *(const bf16x8*)(base + BM * 64 + (wrow0 + (nh * 4 + i) * 16) * 64 + rd);
; #pragma unroll
;       for (int i = 0; i < 4; ++i)
; #pragma unroll
;         for (int mt = 0; mt < MT; ++mt)
;           acc[nh * 4 + i][mt] = __builtin_amdgcn_mfma_f32_16x16x32_bf16(wf[i], xf[mt], acc[nh * 4 + i][mt], 0, 0, 0);
;     }
;   } while (++kt < nk);
; DI void phase_odd(const Params& p, int o, int sub, char* smem) {
;     ...
;     for (int t = get_bid(); t < 1584 + 256; t += gridDim.x) {
;       if (t < 1584) {
;         const int tm = t / 12, tn = t % 12;
;         const int t2 = t + gridDim.x, tm2 = t2 / 12, tn2 = t2 % 12;
;         const bool nx = t2 < 1584;
;         gemm_tile<4>(qn + (size_t)tm * 128 * 384, 384, W + WO_Q + (size_t)tn * 128 * 384, 384, 384, smem, tm * 128, tn * 128, eq, pre,
;                      nx ? qn + (size_t)tm2 * 128 * 384 : nullptr, W + WO_Q + (size_t)tn2 * 128 * 384);
;         pre = nx;
;       } else {
;         knope_tile(p, t - 1584, smem);
;       }
	s_mov_b32 m0, s7
	s_nop 0
	global_load_lds_dwordx4 v[88:89], off
	v_mfma_f32_16x16x32_bf16 v[112:115], v[156:159], v[24:27], v[112:115]
	v_mfma_f32_16x16x32_bf16 v[124:127], v[160:163], v[24:27], v[124:127]
	v_mfma_f32_16x16x32_bf16 v[136:139], v[164:167], v[24:27], v[136:139]
	v_mfma_f32_16x16x32_bf16 v[12:15], v[168:171], v[24:27], v[12:15]
	v_lshl_add_u64 v[24:25], v[6:7], 0, s[14:15]
	s_mov_b32 m0, s8
	s_nop 0
	global_load_lds_dwordx4 v[24:25], off
	v_lshl_add_u64 v[24:25], v[6:7], 0, s[16:17]
	s_mov_b32 m0, s9
	s_nop 0
	global_load_lds_dwordx4 v[24:25], off
	s_mov_b64 s[8:9], 0x61c0
	v_lshl_add_u64 v[6:7], v[6:7], 0, s[8:9]
	s_mov_b32 m0, s10
	s_nop 0
	global_load_lds_dwordx4 v[6:7], off
	v_lshl_add_u64 v[6:7], v[8:9], 0, s[14:15]
	s_mov_b32 m0, s11
	s_nop 0
	global_load_lds_dwordx4 v[172:173], off
	v_mfma_f32_16x16x32_bf16 v[116:119], v[156:159], v[108:111], v[116:119]
	s_mov_b32 m0, s12
	s_nop 0
	global_load_lds_dwordx4 v[6:7], off
	v_readlane_b32 s8, v255, 5
	v_readlane_b32 s14, v255, 11
	v_mfma_f32_16x16x32_bf16 v[120:123], v[156:159], v[148:151], v[120:123]
	v_readlane_b32 s9, v255, 6
	v_readlane_b32 s10, v255, 7
	v_readlane_b32 s11, v255, 8
	v_mfma_f32_16x16x32_bf16 v[96:99], v[156:159], v[152:155], v[96:99]
	v_readlane_b32 s12, v255, 9
	v_readlane_b32 s13, v255, 10
	v_readlane_b32 s15, v255, 12
	v_mfma_f32_16x16x32_bf16 v[128:131], v[160:163], v[108:111], v[128:131]
	s_add_i32 s4, s5, s14
	v_mfma_f32_16x16x32_bf16 v[132:135], v[160:163], v[148:151], v[132:135]
	v_mfma_f32_16x16x32_bf16 v[100:103], v[160:163], v[152:155], v[100:103]
	v_mfma_f32_16x16x32_bf16 v[140:143], v[164:167], v[108:111], v[140:143]
	v_mfma_f32_16x16x32_bf16 v[144:147], v[164:167], v[148:151], v[144:147]
	v_mfma_f32_16x16x32_bf16 v[104:107], v[164:167], v[152:155], v[104:107]
	v_mfma_f32_16x16x32_bf16 v[16:19], v[168:171], v[108:111], v[16:19]
	v_mfma_f32_16x16x32_bf16 v[20:23], v[168:171], v[148:151], v[20:23]
	v_mfma_f32_16x16x32_bf16 v[2:5], v[168:171], v[152:155], v[2:5]
	ds_read_b128 v[6:9], v11 offset:49152
	ds_read_b128 v[24:27], v11 offset:50176
	ds_read_b128 v[108:111], v11 offset:51200
	ds_read_b128 v[148:151], v11 offset:52224
	ds_read_b128 v[152:155], v174
	ds_read_b128 v[156:159], v175
	ds_read_b128 v[160:163], v176
	ds_read_b128 v[164:167], v177
	s_waitcnt lgkmcnt(3)
	v_mfma_f32_16x16x32_bf16 v[44:47], v[152:155], v[6:9], v[44:47]
	v_mfma_f32_16x16x32_bf16 v[48:51], v[152:155], v[24:27], v[48:51]
	v_mfma_f32_16x16x32_bf16 v[52:55], v[152:155], v[108:111], v[52:55]
	v_mfma_f32_16x16x32_bf16 v[28:31], v[152:155], v[148:151], v[28:31]
	s_waitcnt lgkmcnt(2)
	v_mfma_f32_16x16x32_bf16 v[56:59], v[156:159], v[6:9], v[56:59]
	v_mfma_f32_16x16x32_bf16 v[60:63], v[156:159], v[24:27], v[60:63]
	v_mfma_f32_16x16x32_bf16 v[64:67], v[156:159], v[108:111], v[64:67]
	v_mfma_f32_16x16x32_bf16 v[32:35], v[156:159], v[148:151], v[32:35]
	s_waitcnt lgkmcnt(1)
	v_mfma_f32_16x16x32_bf16 v[68:71], v[160:163], v[6:9], v[68:71]
	v_mfma_f32_16x16x32_bf16 v[72:75], v[160:163], v[24:27], v[72:75]
	v_mfma_f32_16x16x32_bf16 v[76:79], v[160:163], v[108:111], v[76:79]
	v_mfma_f32_16x16x32_bf16 v[36:39], v[160:163], v[148:151], v[36:39]
	s_waitcnt lgkmcnt(0)
	v_mfma_f32_16x16x32_bf16 v[80:83], v[164:167], v[6:9], v[80:83]
	v_mfma_f32_16x16x32_bf16 v[84:87], v[164:167], v[24:27], v[84:87]
	v_mfma_f32_16x16x32_bf16 v[92:95], v[164:167], v[108:111], v[92:95]
	v_mfma_f32_16x16x32_bf16 v[40:43], v[164:167], v[148:151], v[40:43]
	ds_read_b128 v[152:155], v178
	ds_read_b128 v[156:159], v179
	ds_read_b128 v[160:163], v180
	ds_read_b128 v[164:167], v181
	s_waitcnt vmcnt(6)
	s_waitcnt lgkmcnt(0)
	v_mfma_f32_16x16x32_bf16 v[112:115], v[152:155], v[6:9], v[112:115]
	s_barrier
	v_mfma_f32_16x16x32_bf16 v[116:119], v[152:155], v[24:27], v[116:119]
	v_mfma_f32_16x16x32_bf16 v[120:123], v[152:155], v[108:111], v[120:123]
	v_mfma_f32_16x16x32_bf16 v[96:99], v[152:155], v[148:151], v[96:99]
	v_mfma_f32_16x16x32_bf16 v[124:127], v[156:159], v[6:9], v[124:127]
	v_mfma_f32_16x16x32_bf16 v[128:131], v[156:159], v[24:27], v[128:131]
	v_mfma_f32_16x16x32_bf16 v[132:135], v[156:159], v[108:111], v[132:135]
	v_mfma_f32_16x16x32_bf16 v[100:103], v[156:159], v[148:151], v[100:103]
	v_mfma_f32_16x16x32_bf16 v[136:139], v[160:163], v[6:9], v[136:139]
	v_mfma_f32_16x16x32_bf16 v[140:143], v[160:163], v[24:27], v[140:143]
	v_mfma_f32_16x16x32_bf16 v[144:147], v[160:163], v[108:111], v[144:147]
	v_mfma_f32_16x16x32_bf16 v[104:107], v[160:163], v[148:151], v[104:107]
	v_mfma_f32_16x16x32_bf16 v[6:9], v[164:167], v[6:9], v[12:15]
	v_mfma_f32_16x16x32_bf16 v[12:15], v[164:167], v[24:27], v[16:19]
	v_mfma_f32_16x16x32_bf16 v[16:19], v[164:167], v[108:111], v[20:23]
	v_mfma_f32_16x16x32_bf16 v[2:5], v[164:167], v[148:151], v[2:5]
	s_nop 1
	ds_read_b128 v[20:23], v10 offset:23552
	ds_read_b128 v[24:27], v10 offset:22528
	ds_read_b128 v[108:111], v10 offset:21504
	ds_read_b128 v[148:151], v10 offset:20480
	ds_read_b128 v[152:155], v10 offset:19456
	ds_read_b128 v[156:159], v10 offset:18432
	ds_read_b128 v[160:163], v10 offset:17408
	ds_read_b128 v[164:167], v10 offset:16384
	ds_read_b128 v[168:171], v11 offset:3072
	ds_read_b128 v[172:175], v11 offset:2048
	ds_read_b128 v[176:179], v11 offset:1024
	ds_read_b128 v[186:189], v11
	s_waitcnt vmcnt(0)
	s_waitcnt lgkmcnt(0)
	v_mfma_f32_16x16x32_bf16 v[44:47], v[164:167], v[186:189], v[44:47]
	s_barrier
; DI void st_bf4(u16* p, float a, float b, float c, float d) { *(uint2*)p = make_uint2(pk2(a, b), pk2(c, d)); }
; template <int BM, class Epi>
; DI void gemm_dma(const u16* __restrict__ X, long ldx, const u16* __restrict__ W, long ldw, int K, char* smem,
;                  int m0, int n0, const Epi& epi) {
;     ...
;     for (int nh = 0; nh < NT / 4; ++nh) {
;       bf16x8 wf[4];
; #pragma unroll
;       for (int i = 0; i < 4; ++i) wf[i] = *(const bf16x8*)(base + BM * 64 + (wrow0 + (nh * 4 + i) * 16) * 64 + rd);
; #pragma unroll
;       for (int i = 0; i < 4; ++i)
; #pragma unroll
;         for (int mt = 0; mt < MT; ++mt)
;           acc[nh * 4 + i][mt] = __builtin_amdgcn_mfma_f32_16x16x32_bf16(wf[i], xf[mt], acc[nh * 4 + i][mt], 0, 0, 0);
;     }
;   } while (++kt < nk);
;   template <int NT, int MT> DI void run(f32x4 (&acc)[NT][MT], int mb, int nb) const {
; #pragma unroll
;     for (int nt = 0; nt < NT; ++nt)
; #pragma unroll
;       for (int mt = 0; mt < MT; ++mt) {
;         f32x4 v = acc[nt][mt];
;         st_bf4(C + (size_t)(mb + mt * 16) * ldc + nb + nt * 16, v[0], v[1], v[2], v[3]);
;       }
	v_mfma_f32_16x16x32_bf16 v[48:51], v[164:167], v[176:179], v[48:51]
	v_mfma_f32_16x16x32_bf16 v[52:55], v[164:167], v[172:175], v[52:55]
	v_mfma_f32_16x16x32_bf16 v[28:31], v[164:167], v[168:171], v[28:31]
	v_mfma_f32_16x16x32_bf16 v[56:59], v[160:163], v[186:189], v[56:59]
	v_mfma_f32_16x16x32_bf16 v[60:63], v[160:163], v[176:179], v[60:63]
	v_mfma_f32_16x16x32_bf16 v[64:67], v[160:163], v[172:175], v[64:67]
	v_mfma_f32_16x16x32_bf16 v[32:35], v[160:163], v[168:171], v[32:35]
	v_mfma_f32_16x16x32_bf16 v[68:71], v[156:159], v[186:189], v[68:71]
	v_mfma_f32_16x16x32_bf16 v[72:75], v[156:159], v[176:179], v[72:75]
	v_mfma_f32_16x16x32_bf16 v[76:79], v[156:159], v[172:175], v[76:79]
	v_mfma_f32_16x16x32_bf16 v[36:39], v[156:159], v[168:171], v[36:39]
	v_mfma_f32_16x16x32_bf16 v[156:159], v[152:155], v[186:189], v[80:83]
	v_mfma_f32_16x16x32_bf16 v[86:89], v[152:155], v[176:179], v[84:87]
	v_mfma_f32_16x16x32_bf16 v[92:95], v[152:155], v[172:175], v[92:95]
	v_mfma_f32_16x16x32_bf16 v[152:155], v[152:155], v[168:171], v[40:43]
	v_mfma_f32_16x16x32_bf16 v[112:115], v[148:151], v[186:189], v[112:115]
	v_mfma_f32_16x16x32_bf16 v[116:119], v[148:151], v[176:179], v[116:119]
	v_mfma_f32_16x16x32_bf16 v[120:123], v[148:151], v[172:175], v[120:123]
	v_mfma_f32_16x16x32_bf16 v[96:99], v[148:151], v[168:171], v[96:99]
	v_mfma_f32_16x16x32_bf16 v[124:127], v[108:111], v[186:189], v[124:127]
	v_mfma_f32_16x16x32_bf16 v[128:131], v[108:111], v[176:179], v[128:131]
	v_mfma_f32_16x16x32_bf16 v[132:135], v[108:111], v[172:175], v[132:135]
	v_mfma_f32_16x16x32_bf16 v[100:103], v[108:111], v[168:171], v[100:103]
	v_mfma_f32_16x16x32_bf16 v[108:111], v[24:27], v[186:189], v[136:139]
	v_mfma_f32_16x16x32_bf16 v[136:139], v[24:27], v[176:179], v[140:143]
	v_mfma_f32_16x16x32_bf16 v[140:143], v[24:27], v[172:175], v[144:147]
	v_mfma_f32_16x16x32_bf16 v[104:107], v[24:27], v[168:171], v[104:107]
	v_mfma_f32_16x16x32_bf16 v[6:9], v[20:23], v[186:189], v[6:9]
	v_mfma_f32_16x16x32_bf16 v[144:147], v[20:23], v[176:179], v[12:15]
	v_mfma_f32_16x16x32_bf16 v[148:151], v[20:23], v[172:175], v[16:19]
	v_mfma_f32_16x16x32_bf16 v[2:5], v[20:23], v[168:171], v[2:5]
	s_nop 0
	ds_read_b128 v[12:15], v11 offset:24576
	ds_read_b128 v[160:163], v11 offset:25600
	ds_read_b128 v[164:167], v11 offset:26624
	ds_read_b128 v[168:171], v11 offset:27648
	ds_read_b128 v[16:19], v10 offset:40960
	ds_read_b128 v[20:23], v10 offset:41984
	ds_read_b128 v[24:27], v10 offset:43008
	ds_read_b128 v[172:175], v10 offset:44032
	s_waitcnt lgkmcnt(3)
	v_mfma_f32_16x16x32_bf16 v[176:179], v[16:19], v[12:15], v[44:47]
	v_mfma_f32_16x16x32_bf16 v[186:189], v[16:19], v[160:163], v[48:51]
	v_mfma_f32_16x16x32_bf16 v[190:193], v[16:19], v[164:167], v[52:55]
	v_mfma_f32_16x16x32_bf16 v[194:197], v[16:19], v[168:171], v[28:31]
	s_waitcnt lgkmcnt(2)
	v_mfma_f32_16x16x32_bf16 v[224:227], v[20:23], v[12:15], v[56:59]
	v_mfma_f32_16x16x32_bf16 v[228:231], v[20:23], v[160:163], v[60:63]
	v_mfma_f32_16x16x32_bf16 v[232:235], v[20:23], v[164:167], v[64:67]
	v_mfma_f32_16x16x32_bf16 v[236:239], v[20:23], v[168:171], v[32:35]
	s_waitcnt lgkmcnt(1)
	v_mfma_f32_16x16x32_bf16 v[240:243], v[24:27], v[12:15], v[68:71]
	v_mfma_f32_16x16x32_bf16 v[66:69], v[24:27], v[168:171], v[36:39]
	s_waitcnt lgkmcnt(0)
	v_mfma_f32_16x16x32_bf16 v[42:45], v[172:175], v[164:167], v[92:95]
	v_mfma_f32_16x16x32_bf16 v[34:37], v[172:175], v[168:171], v[152:155]
	ds_read_b128 v[16:19], v10 offset:45056
	ds_read_b128 v[20:23], v10 offset:46080
	ds_read_b128 v[92:95], v10 offset:47104
	ds_read_b128 v[152:155], v10 offset:48128
	s_nop 0
	v_cvt_pk_bf16_f32 v66, v66, v67
	v_cvt_pk_bf16_f32 v67, v68, v69
	v_mfma_f32_16x16x32_bf16 v[82:85], v[24:27], v[160:163], v[72:75]
	v_cvt_pk_bf16_f32 v34, v34, v35
	v_cvt_pk_bf16_f32 v35, v36, v37
	v_cvt_pk_bf16_f32 v42, v42, v43
	v_mfma_f32_16x16x32_bf16 v[74:77], v[24:27], v[164:167], v[76:79]
	v_cvt_pk_bf16_f32 v43, v44, v45
	s_nop 2
	v_cvt_pk_bf16_f32 v82, v82, v83
	v_cvt_pk_bf16_f32 v83, v84, v85
	v_mfma_f32_16x16x32_bf16 v[50:53], v[172:175], v[160:163], v[86:89]
	s_waitcnt lgkmcnt(3)
	v_mfma_f32_16x16x32_bf16 v[112:115], v[16:19], v[12:15], v[112:115]
	v_cvt_pk_bf16_f32 v74, v74, v75
	v_cvt_pk_bf16_f32 v75, v76, v77
	s_nop 3
	v_cvt_pk_bf16_f32 v50, v50, v51
	v_mfma_f32_16x16x32_bf16 v[86:89], v[16:19], v[160:163], v[116:119]
	v_cvt_pk_bf16_f32 v51, v52, v53
	v_mfma_f32_16x16x32_bf16 v[78:81], v[16:19], v[164:167], v[120:123]
	v_mfma_f32_16x16x32_bf16 v[70:73], v[16:19], v[168:171], v[96:99]
	s_waitcnt lgkmcnt(2)
	v_mfma_f32_16x16x32_bf16 v[62:65], v[20:23], v[12:15], v[124:127]
	s_nop 0
	v_cvt_pk_bf16_f32 v96, v186, v187
	v_cvt_pk_bf16_f32 v97, v188, v189
	v_cvt_pk_bf16_f32 v98, v190, v191
	v_mfma_f32_16x16x32_bf16 v[54:57], v[20:23], v[160:163], v[128:131]
	v_cvt_pk_bf16_f32 v99, v192, v193
	v_mfma_f32_16x16x32_bf16 v[46:49], v[20:23], v[164:167], v[132:135]
	v_mfma_f32_16x16x32_bf16 v[38:41], v[20:23], v[168:171], v[100:103]
	s_waitcnt lgkmcnt(1)
; DI void st_bf4(u16* p, float a, float b, float c, float d) { *(uint2*)p = make_uint2(pk2(a, b), pk2(c, d)); }
; template <int BM, class Epi>
; DI void gemm_dma(const u16* __restrict__ X, long ldx, const u16* __restrict__ W, long ldw, int K, char* smem,
;                  int m0, int n0, const Epi& epi) {
;     ...
;     for (int nh = 0; nh < NT / 4; ++nh) {
;       bf16x8 wf[4];
; #pragma unroll
;       for (int i = 0; i < 4; ++i) wf[i] = *(const bf16x8*)(base + BM * 64 + (wrow0 + (nh * 4 + i) * 16) * 64 + rd);
; #pragma unroll
;       for (int i = 0; i < 4; ++i)
; #pragma unroll
;         for (int mt = 0; mt < MT; ++mt)
;           acc[nh * 4 + i][mt] = __builtin_amdgcn_mfma_f32_16x16x32_bf16(wf[i], xf[mt], acc[nh * 4 + i][mt], 0, 0, 0);
;     }
;   } while (++kt < nk);
;     ...
;   epi.run(acc, m0 + xrow0 + lr, n0 + wrow0 + 4 * g);
;   template <int NT, int MT> DI void run(f32x4 (&acc)[NT][MT], int mb, int nb) const {
; #pragma unroll
;     for (int nt = 0; nt < NT; ++nt)
; #pragma unroll
;       for (int mt = 0; mt < MT; ++mt) {
;         f32x4 v = acc[nt][mt];
;         st_bf4(C + (size_t)(mb + mt * 16) * ldc + nb + nt * 16, v[0], v[1], v[2], v[3]);
;       }
	v_mfma_f32_16x16x32_bf16 v[30:33], v[92:95], v[12:15], v[108:111]
	v_mfma_f32_16x16x32_bf16 v[26:29], v[92:95], v[160:163], v[136:139]
	v_mfma_f32_16x16x32_bf16 v[22:25], v[92:95], v[164:167], v[140:143]
	s_nop 5
	v_cvt_pk_bf16_f32 v30, v30, v31
	v_cvt_pk_bf16_f32 v31, v32, v33
	v_cvt_pk_bf16_f32 v26, v26, v27
	v_mfma_f32_16x16x32_bf16 v[18:21], v[92:95], v[168:171], v[104:107]
	v_or_b32_e32 v94, v91, v90
	v_ashrrev_i32_e32 v95, 31, v94
	v_lshlrev_b64 v[90:91], 11, v[94:95]
	v_lshl_add_u64 v[90:91], s[92:93], 0, v[90:91]
	v_bfe_u32 v1, v185, 4, 1
	v_mad_u32_u24 v182, v1, 24, v182
	v_lshl_add_u64 v[90:91], v[90:91], 0, v[182:183]
	v_cvt_pk_bf16_f32 v92, v176, v177
	v_cvt_pk_bf16_f32 v93, v178, v179
	v_mov_b32_e32 v100, v92
	v_mov_b32_e32 v101, v93
	v_or_b32_e32 v92, 16, v94
	v_ashrrev_i32_e32 v93, 31, v92
	v_lshlrev_b64 v[92:93], 11, v[92:93]
	v_lshl_add_u64 v[92:93], s[92:93], 0, v[92:93]
	v_lshl_add_u64 v[92:93], v[92:93], 0, v[182:183]
	v_mov_b32_e32 v104, v96
	v_mov_b32_e32 v105, v97
	v_or_b32_e32 v96, 32, v94
	v_or_b32_e32 v94, 48, v94
	v_ashrrev_i32_e32 v95, 31, v94
	v_lshlrev_b64 v[94:95], 11, v[94:95]
	v_ashrrev_i32_e32 v97, 31, v96
	v_lshl_add_u64 v[94:95], s[92:93], 0, v[94:95]
	v_lshlrev_b64 v[96:97], 11, v[96:97]
	v_lshl_add_u64 v[94:95], v[94:95], 0, v[182:183]
	v_lshl_add_u64 v[96:97], s[92:93], 0, v[96:97]
	v_mov_b32_e32 v110, v34
	v_mov_b32_e32 v111, v35
	v_cvt_pk_bf16_f32 v34, v112, v113
	v_cvt_pk_bf16_f32 v35, v114, v115
	v_lshl_add_u64 v[96:97], v[96:97], 0, v[182:183]
	v_mov_b32_e32 v116, v34
	v_mov_b32_e32 v117, v35
	v_cvt_pk_bf16_f32 v34, v86, v87
	v_cvt_pk_bf16_f32 v35, v88, v89
	v_mov_b32_e32 v120, v98
	v_mov_b32_e32 v121, v99
	v_cvt_pk_bf16_f32 v98, v194, v195
	v_cvt_pk_bf16_f32 v99, v196, v197
	v_mov_b32_e32 v124, v34
	v_mov_b32_e32 v125, v35
	v_cvt_pk_bf16_f32 v34, v78, v79
	v_cvt_pk_bf16_f32 v35, v80, v81
	v_mfma_f32_16x16x32_bf16 v[58:61], v[172:175], v[12:15], v[156:159]
	v_mov_b32_e32 v112, v98
	v_mov_b32_e32 v113, v99
	v_cvt_pk_bf16_f32 v98, v224, v225
	v_cvt_pk_bf16_f32 v99, v226, v227
	s_waitcnt lgkmcnt(0)
	v_mfma_f32_16x16x32_bf16 v[14:17], v[152:155], v[12:15], v[6:9]
	v_mov_b32_e32 v84, v34
	v_mov_b32_e32 v85, v35
	v_cvt_pk_bf16_f32 v34, v70, v71
	v_cvt_pk_bf16_f32 v35, v72, v73
	v_mfma_f32_16x16x32_bf16 v[10:13], v[152:155], v[160:163], v[144:147]
	v_mov_b32_e32 v102, v98
	v_mov_b32_e32 v103, v99
	s_nop 1
	v_permlane16_swap_b32_e32 v100, v102
	v_permlane16_swap_b32_e32 v101, v103
	global_store_dwordx4 v[90:91], v[100:103], off
	v_cvt_pk_bf16_f32 v98, v228, v229
	v_cvt_pk_bf16_f32 v99, v230, v231
	v_mfma_f32_16x16x32_bf16 v[6:9], v[152:155], v[164:167], v[148:151]
	v_mov_b32_e32 v76, v34
	v_mov_b32_e32 v77, v35
	v_cvt_pk_bf16_f32 v34, v62, v63
	v_cvt_pk_bf16_f32 v35, v64, v65
	v_mfma_f32_16x16x32_bf16 v[2:5], v[152:155], v[168:171], v[2:5]
	v_mov_b32_e32 v106, v98
	v_mov_b32_e32 v107, v99
	s_nop 1
	v_permlane16_swap_b32_e32 v104, v106
	v_permlane16_swap_b32_e32 v105, v107
	global_store_dwordx4 v[92:93], v[104:107], off
	v_cvt_pk_bf16_f32 v98, v232, v233
	v_cvt_pk_bf16_f32 v99, v234, v235
	v_mov_b32_e32 v118, v34
	v_mov_b32_e32 v119, v35
	s_nop 1
	v_permlane16_swap_b32_e32 v116, v118
	v_permlane16_swap_b32_e32 v117, v119
	global_store_dwordx4 v[90:91], v[116:119], off offset:128
	v_cvt_pk_bf16_f32 v34, v54, v55
	v_cvt_pk_bf16_f32 v35, v56, v57
	v_mov_b32_e32 v122, v98
	v_mov_b32_e32 v123, v99
	s_nop 1
	v_permlane16_swap_b32_e32 v120, v122
	v_permlane16_swap_b32_e32 v121, v123
	global_store_dwordx4 v[96:97], v[120:123], off
	v_cvt_pk_bf16_f32 v98, v236, v237
	v_cvt_pk_bf16_f32 v99, v238, v239
	v_mov_b32_e32 v126, v34
	v_mov_b32_e32 v127, v35
	s_nop 1
	v_permlane16_swap_b32_e32 v124, v126
	v_permlane16_swap_b32_e32 v125, v127
	global_store_dwordx4 v[92:93], v[124:127], off offset:128
	v_cvt_pk_bf16_f32 v34, v46, v47
	v_cvt_pk_bf16_f32 v35, v48, v49
	v_mov_b32_e32 v114, v98
	v_mov_b32_e32 v115, v99
	s_nop 1
	v_permlane16_swap_b32_e32 v112, v114
	v_permlane16_swap_b32_e32 v113, v115
	global_store_dwordx4 v[94:95], v[112:115], off
	v_cvt_pk_bf16_f32 v98, v240, v241
	v_cvt_pk_bf16_f32 v99, v242, v243
	v_cvt_pk_bf16_f32 v58, v58, v59
	v_cvt_pk_bf16_f32 v59, v60, v61
	v_mov_b32_e32 v86, v34
	v_mov_b32_e32 v87, v35
	s_nop 1
	v_permlane16_swap_b32_e32 v84, v86
	v_permlane16_swap_b32_e32 v85, v87
	global_store_dwordx4 v[96:97], v[84:87], off offset:128
	v_cvt_pk_bf16_f32 v34, v38, v39
	v_cvt_pk_bf16_f32 v35, v40, v41
	v_cvt_pk_bf16_f32 v27, v28, v29
	v_cvt_pk_bf16_f32 v22, v22, v23
	v_cvt_pk_bf16_f32 v23, v24, v25
	v_cvt_pk_bf16_f32 v18, v18, v19
	v_cvt_pk_bf16_f32 v19, v20, v21
	v_cvt_pk_bf16_f32 v14, v14, v15
	v_cvt_pk_bf16_f32 v15, v16, v17
	v_cvt_pk_bf16_f32 v10, v10, v11
	v_cvt_pk_bf16_f32 v11, v12, v13
	v_cvt_pk_bf16_f32 v6, v6, v7
	v_cvt_pk_bf16_f32 v7, v8, v9
	v_cvt_pk_bf16_f32 v2, v2, v3
	v_cvt_pk_bf16_f32 v3, v4, v5
	v_mov_b32_e32 v36, v98
	v_mov_b32_e32 v37, v99
	v_mov_b32_e32 v44, v82
	v_mov_b32_e32 v45, v83
	v_mov_b32_e32 v52, v74
	v_mov_b32_e32 v53, v75
	v_mov_b32_e32 v108, v66
	v_mov_b32_e32 v109, v67
	s_nop 1
	v_permlane16_swap_b32_e32 v108, v110
	v_permlane16_swap_b32_e32 v109, v111
	global_store_dwordx4 v[94:95], v[108:111], off offset:64
	v_mov_b32_e32 v38, v58
	v_mov_b32_e32 v39, v59
	s_nop 1
	v_permlane16_swap_b32_e32 v36, v38
	v_permlane16_swap_b32_e32 v37, v39
	global_store_dwordx4 v[90:91], v[36:39], off offset:64
	v_mov_b32_e32 v46, v50
	v_mov_b32_e32 v47, v51
	s_nop 1
	v_permlane16_swap_b32_e32 v44, v46
	v_permlane16_swap_b32_e32 v45, v47
	global_store_dwordx4 v[92:93], v[44:47], off offset:64
	v_mov_b32_e32 v54, v42
	v_mov_b32_e32 v55, v43
	s_nop 1
	v_permlane16_swap_b32_e32 v52, v54
	v_permlane16_swap_b32_e32 v53, v55
	global_store_dwordx4 v[96:97], v[52:55], off offset:64
	v_mov_b32_e32 v78, v34
	v_mov_b32_e32 v79, v35
	s_nop 1
	v_permlane16_swap_b32_e32 v76, v78
	v_permlane16_swap_b32_e32 v77, v79
	global_store_dwordx4 v[94:95], v[76:79], off offset:128
	v_mov_b32_e32 v36, v30
	v_mov_b32_e32 v37, v31
	v_mov_b32_e32 v44, v26
	v_mov_b32_e32 v45, v27
	v_mov_b32_e32 v52, v22
	v_mov_b32_e32 v53, v23
	v_mov_b32_e32 v60, v18
	v_mov_b32_e32 v61, v19
	v_mov_b32_e32 v38, v14
	v_mov_b32_e32 v39, v15
	s_nop 1
	v_permlane16_swap_b32_e32 v36, v38
	v_permlane16_swap_b32_e32 v37, v39
	global_store_dwordx4 v[90:91], v[36:39], off offset:192
	v_mov_b32_e32 v46, v10
	v_mov_b32_e32 v47, v11
	s_nop 1
	v_permlane16_swap_b32_e32 v44, v46
	v_permlane16_swap_b32_e32 v45, v47
	global_store_dwordx4 v[92:93], v[44:47], off offset:192
	v_mov_b32_e32 v54, v6
	v_mov_b32_e32 v55, v7
	s_nop 1
	v_permlane16_swap_b32_e32 v52, v54
	v_permlane16_swap_b32_e32 v53, v55
	global_store_dwordx4 v[96:97], v[52:55], off offset:192
	v_mov_b32_e32 v62, v2
	v_mov_b32_e32 v63, v3
	s_nop 1
	v_permlane16_swap_b32_e32 v60, v62
	v_permlane16_swap_b32_e32 v61, v63
	global_store_dwordx4 v[94:95], v[60:63], off offset:192

; template <int N> DI void wait_vm() { asm volatile("s_waitcnt vmcnt(%0)" ::"n"(N) : "memory"); }
; template <int BM, class Epi>
; DI void gemm_dma(const u16* __restrict__ X, long ldx, const u16* __restrict__ W, long ldw, int K, char* smem,
;                  int m0, int n0, const Epi& epi) {
;     ...
;   do {
;     if (kt + D - 2 < nk) wait_vm<PW * (D - 2)>(); else wait_vm<0>();
;     __syncthreads();
;     if (kt + D - 1 < nk) GD_ISSUE(nxt)
;     nxt = (nxt + 1 == D) ? 0 : nxt + 1;
;     const char* base = smem + cur * STG;
;     cur = (cur + 1 == D) ? 0 : cur + 1;
;     bf16x8 xf[MT];
; #pragma unroll
;     for (int i = 0; i < MT; ++i) xf[i] = *(const bf16x8*)(base + (xrow0 + i * 16) * 64 + rd);
; #pragma unroll
;     for (int nh = 0; nh < NT / 4; ++nh) {
;       bf16x8 wf[4];
; #pragma unroll
;       for (int i = 0; i < 4; ++i) wf[i] = *(const bf16x8*)(base + BM * 64 + (wrow0 + (nh * 4 + i) * 16) * 64 + rd);
; #pragma unroll
;       for (int i = 0; i < 4; ++i)
; #pragma unroll
;         for (int mt = 0; mt < MT; ++mt)
;           acc[nh * 4 + i][mt] = __builtin_amdgcn_mfma_f32_16x16x32_bf16(wf[i], xf[mt], acc[nh * 4 + i][mt], 0, 0, 0);
;     }
;   } while (++kt < nk);
.LBB0_292:
	s_mul_i32 s12, s10, 0x6000
	v_lshl_add_u64 v[196:197], v[132:133], 0, s[40:41]
	s_waitcnt vmcnt(6)
	s_barrier
	s_mul_i32 s98, s11, 0x6000
	v_or_b32_e32 v170, s98, v135
	v_add_u32_e32 v150, v170, v137
	ds_read_b128 v[138:141], v150
	ds_read_b128 v[142:145], v150 offset:1024
	ds_read_b128 v[146:149], v150 offset:2048
	ds_read_b128 v[150:153], v150 offset:3072
	ds_read_b128 v[154:157], v170 offset:16384
	ds_read_b128 v[158:161], v170 offset:17408
	ds_read_b128 v[162:165], v170 offset:18432
	ds_read_b128 v[166:169], v170 offset:19456
	ds_read_b128 v[226:229], v170 offset:20480
	ds_read_b128 v[230:233], v170 offset:21504
	ds_read_b128 v[234:237], v170 offset:22528
	ds_read_b128 v[238:241], v170 offset:23552
	s_add_i32 s13, s12, s8
	s_mov_b32 m0, s13
	s_nop 0
	global_load_lds_dwordx4 v[196:197], off
	v_lshl_add_u64 v[224:225], v[196:197], 0, s[16:17]
	s_add_i32 s14, s13, 0x400
	s_mov_b32 m0, s14
	s_nop 0
	global_load_lds_dwordx4 v[224:225], off
	v_lshl_add_u64 v[224:225], v[196:197], 0, s[20:21]
	s_add_i32 s14, s13, 0x800
	s_mov_b32 m0, s14
	s_nop 0
	global_load_lds_dwordx4 v[224:225], off
	v_lshl_add_u64 v[196:197], v[196:197], 0, s[22:23]
	s_addk_i32 s13, 0xc00
	s_mov_b32 m0, s13
	s_nop 0
	global_load_lds_dwordx4 v[196:197], off
	s_add_i32 s12, s12, s9
	v_lshl_add_u64 v[194:195], v[130:131], 0, s[40:41]
	s_mov_b32 m0, s12
	s_nop 0
	global_load_lds_dwordx4 v[194:195], off
	s_addk_i32 s12, 0x400
	v_lshl_add_u64 v[194:195], v[194:195], 0, s[16:17]
	s_mov_b32 m0, s12
	s_nop 0
	global_load_lds_dwordx4 v[194:195], off
	s_waitcnt lgkmcnt(7)
	v_mfma_f32_16x16x32_bf16 v[126:129], v[154:157], v[138:141], v[126:129]
	s_add_i32 s10, s10, 1
	s_add_i32 s11, s11, 1
	s_cmp_lg_u32 s10, 3
	v_mfma_f32_16x16x32_bf16 v[122:125], v[154:157], v[142:145], v[122:125]
	s_cselect_b32 s10, s10, 0
	s_cmp_lg_u32 s11, 3
	s_cselect_b32 s11, s11, 0
	v_mfma_f32_16x16x32_bf16 v[118:121], v[154:157], v[146:149], v[118:121]
	s_add_u32 s40, s40, 64
	s_addc_u32 s41, s41, 0
	s_cmpk_lg_i32 s40, 0xf80
	v_mfma_f32_16x16x32_bf16 v[114:117], v[154:157], v[150:153], v[114:117]
	s_waitcnt lgkmcnt(6)
	v_mfma_f32_16x16x32_bf16 v[110:113], v[158:161], v[138:141], v[110:113]
	v_mfma_f32_16x16x32_bf16 v[106:109], v[158:161], v[142:145], v[106:109]
	v_mfma_f32_16x16x32_bf16 v[102:105], v[158:161], v[146:149], v[102:105]
	v_mfma_f32_16x16x32_bf16 v[98:101], v[158:161], v[150:153], v[98:101]
	s_waitcnt lgkmcnt(5)
	v_mfma_f32_16x16x32_bf16 v[94:97], v[162:165], v[138:141], v[94:97]
	v_mfma_f32_16x16x32_bf16 v[90:93], v[162:165], v[142:145], v[90:93]
	v_mfma_f32_16x16x32_bf16 v[86:89], v[162:165], v[146:149], v[86:89]
	v_mfma_f32_16x16x32_bf16 v[82:85], v[162:165], v[150:153], v[82:85]
	s_waitcnt lgkmcnt(4)
	v_mfma_f32_16x16x32_bf16 v[78:81], v[166:169], v[138:141], v[78:81]
	v_mfma_f32_16x16x32_bf16 v[74:77], v[166:169], v[142:145], v[74:77]
	v_mfma_f32_16x16x32_bf16 v[70:73], v[166:169], v[146:149], v[70:73]
	v_mfma_f32_16x16x32_bf16 v[66:69], v[166:169], v[150:153], v[66:69]
	s_waitcnt lgkmcnt(3)
	v_mfma_f32_16x16x32_bf16 v[62:65], v[226:229], v[138:141], v[62:65]
	v_mfma_f32_16x16x32_bf16 v[58:61], v[226:229], v[142:145], v[58:61]
	v_mfma_f32_16x16x32_bf16 v[54:57], v[226:229], v[146:149], v[54:57]
	v_mfma_f32_16x16x32_bf16 v[50:53], v[226:229], v[150:153], v[50:53]
	s_waitcnt lgkmcnt(2)
	v_mfma_f32_16x16x32_bf16 v[46:49], v[230:233], v[138:141], v[46:49]
	v_mfma_f32_16x16x32_bf16 v[42:45], v[230:233], v[142:145], v[42:45]
	v_mfma_f32_16x16x32_bf16 v[38:41], v[230:233], v[146:149], v[38:41]
	v_mfma_f32_16x16x32_bf16 v[34:37], v[230:233], v[150:153], v[34:37]
	s_waitcnt lgkmcnt(1)
	v_mfma_f32_16x16x32_bf16 v[30:33], v[234:237], v[138:141], v[30:33]
	v_mfma_f32_16x16x32_bf16 v[26:29], v[234:237], v[142:145], v[26:29]
	v_mfma_f32_16x16x32_bf16 v[22:25], v[234:237], v[146:149], v[22:25]
	v_mfma_f32_16x16x32_bf16 v[18:21], v[234:237], v[150:153], v[18:21]
	s_waitcnt lgkmcnt(0)
	v_mfma_f32_16x16x32_bf16 v[14:17], v[238:241], v[138:141], v[14:17]
	v_mfma_f32_16x16x32_bf16 v[10:13], v[238:241], v[142:145], v[10:13]
	v_mfma_f32_16x16x32_bf16 v[6:9], v[238:241], v[146:149], v[6:9]
	v_mfma_f32_16x16x32_bf16 v[2:5], v[238:241], v[150:153], v[2:5]
	s_cbranch_scc1 .LBB0_292
	v_add_u32_e32 v137, v135, v137
	v_or_b32_e32 v150, 0x10000, v135
	v_or_b32_e32 v154, 0x10400, v135
	v_or_b32_e32 v158, 0x10800, v135
	v_or_b32_e32 v162, 0x10c00, v135
	s_waitcnt vmcnt(6)
	s_barrier
	ds_read_b128 v[130:133], v137 offset:49152
	ds_read_b128 v[138:141], v137 offset:50176
	ds_read_b128 v[142:145], v137 offset:51200
	ds_read_b128 v[146:149], v137 offset:52224
	ds_read_b128 v[150:153], v150
	ds_read_b128 v[154:157], v154
	ds_read_b128 v[158:161], v158
	ds_read_b128 v[162:165], v162
	s_waitcnt lgkmcnt(3)
	v_mfma_f32_16x16x32_bf16 v[126:129], v[150:153], v[130:133], v[126:129]
	v_readlane_b32 s8, v252, 33
	v_readlane_b32 s9, v252, 34
	s_lshl_b32 s7, s7, 8
	v_mfma_f32_16x16x32_bf16 v[122:125], v[150:153], v[138:141], v[122:125]
	v_lshl_or_b32 v182, v1, 3, s7
	v_mfma_f32_16x16x32_bf16 v[118:121], v[150:153], v[142:145], v[118:121]
	v_mfma_f32_16x16x32_bf16 v[114:117], v[150:153], v[146:149], v[114:117]
	s_waitcnt lgkmcnt(2)
	v_mfma_f32_16x16x32_bf16 v[110:113], v[154:157], v[130:133], v[110:113]
	v_mfma_f32_16x16x32_bf16 v[106:109], v[154:157], v[138:141], v[106:109]
	v_mfma_f32_16x16x32_bf16 v[102:105], v[154:157], v[142:145], v[102:105]
	v_mfma_f32_16x16x32_bf16 v[98:101], v[154:157], v[146:149], v[98:101]
	s_waitcnt lgkmcnt(1)
	v_mfma_f32_16x16x32_bf16 v[94:97], v[158:161], v[130:133], v[94:97]
	v_mfma_f32_16x16x32_bf16 v[150:153], v[158:161], v[138:141], v[90:93]
	v_mfma_f32_16x16x32_bf16 v[86:89], v[158:161], v[142:145], v[86:89]
	s_nop 1
	v_or_b32_e32 v90, 0x11c00, v135
	ds_read_b128 v[90:93], v90
	v_mfma_f32_16x16x32_bf16 v[154:157], v[158:161], v[146:149], v[82:85]
	s_waitcnt lgkmcnt(1)
	v_mfma_f32_16x16x32_bf16 v[78:81], v[162:165], v[130:133], v[78:81]
	s_nop 0
	v_or_b32_e32 v82, 0x11800, v135
	ds_read_b128 v[82:85], v82
	v_mfma_f32_16x16x32_bf16 v[158:161], v[162:165], v[138:141], v[74:77]
	v_mfma_f32_16x16x32_bf16 v[70:73], v[162:165], v[142:145], v[70:73]
	s_nop 1
	v_or_b32_e32 v74, 0x11400, v135
	ds_read_b128 v[74:77], v74
	v_mfma_f32_16x16x32_bf16 v[162:165], v[162:165], v[146:149], v[66:69]
	s_nop 2
	v_or_b32_e32 v66, 0x11000, v135
	ds_read_b128 v[66:69], v66
	s_waitcnt lgkmcnt(1)
	v_mfma_f32_16x16x32_bf16 v[46:49], v[74:77], v[130:133], v[46:49]
	s_waitcnt vmcnt(0)
	s_waitcnt lgkmcnt(0)
	s_barrier
; DI void st_bf4(u16* p, float a, float b, float c, float d) { *(uint2*)p = make_uint2(pk2(a, b), pk2(c, d)); }
; template <int BM, class Epi>
; DI void gemm_dma(const u16* __restrict__ X, long ldx, const u16* __restrict__ W, long ldw, int K, char* smem,
;                  int m0, int n0, const Epi& epi) {
;     ...
;     for (int nh = 0; nh < NT / 4; ++nh) {
;       bf16x8 wf[4];
; #pragma unroll
;       for (int i = 0; i < 4; ++i) wf[i] = *(const bf16x8*)(base + BM * 64 + (wrow0 + (nh * 4 + i) * 16) * 64 + rd);
; #pragma unroll
;       for (int i = 0; i < 4; ++i)
; #pragma unroll
;         for (int mt = 0; mt < MT; ++mt)
;           acc[nh * 4 + i][mt] = __builtin_amdgcn_mfma_f32_16x16x32_bf16(wf[i], xf[mt], acc[nh * 4 + i][mt], 0, 0, 0);
;     }
;   } while (++kt < nk);
;     ...
;   epi.run(acc, m0 + xrow0 + lr, n0 + wrow0 + 4 * g);
;   template <int NT, int MT> DI void run(f32x4 (&acc)[NT][MT], int mb, int nb) const {
; #pragma unroll
;     for (int nt = 0; nt < NT; ++nt)
; #pragma unroll
;       for (int mt = 0; mt < MT; ++mt) {
;         f32x4 v = acc[nt][mt];
;         st_bf4(C + (size_t)(mb + mt * 16) * ldc + nb + nt * 16, v[0], v[1], v[2], v[3]);
;       }
	v_mfma_f32_16x16x32_bf16 v[62:65], v[66:69], v[130:133], v[62:65]
	v_mfma_f32_16x16x32_bf16 v[166:169], v[66:69], v[138:141], v[58:61]
	v_mfma_f32_16x16x32_bf16 v[54:57], v[66:69], v[142:145], v[54:57]
	v_mfma_f32_16x16x32_bf16 v[170:173], v[66:69], v[146:149], v[50:53]
	v_mfma_f32_16x16x32_bf16 v[174:177], v[74:77], v[138:141], v[42:45]
	v_mfma_f32_16x16x32_bf16 v[38:41], v[74:77], v[142:145], v[38:41]
	v_mfma_f32_16x16x32_bf16 v[178:181], v[74:77], v[146:149], v[34:37]
	v_mfma_f32_16x16x32_bf16 v[30:33], v[82:85], v[130:133], v[30:33]
	v_mfma_f32_16x16x32_bf16 v[26:29], v[82:85], v[138:141], v[26:29]
	v_mfma_f32_16x16x32_bf16 v[22:25], v[82:85], v[142:145], v[22:25]
	v_mfma_f32_16x16x32_bf16 v[18:21], v[82:85], v[146:149], v[18:21]
	v_mfma_f32_16x16x32_bf16 v[14:17], v[90:93], v[130:133], v[14:17]
	v_mfma_f32_16x16x32_bf16 v[10:13], v[90:93], v[138:141], v[10:13]
	v_mfma_f32_16x16x32_bf16 v[6:9], v[90:93], v[142:145], v[6:9]
	v_mfma_f32_16x16x32_bf16 v[2:5], v[90:93], v[146:149], v[2:5]
	ds_read_b128 v[130:133], v137
	ds_read_b128 v[138:141], v137 offset:1024
	ds_read_b128 v[142:145], v137 offset:2048
	ds_read_b128 v[146:149], v137 offset:3072
	ds_read_b128 v[34:37], v135 offset:16384
	ds_read_b128 v[42:45], v135 offset:17408
	ds_read_b128 v[50:53], v135 offset:18432
	ds_read_b128 v[186:189], v135 offset:19456
	s_waitcnt lgkmcnt(2)
	v_mfma_f32_16x16x32_bf16 v[110:113], v[42:45], v[130:133], v[110:113]
	v_mfma_f32_16x16x32_bf16 v[106:109], v[42:45], v[138:141], v[106:109]
	v_mfma_f32_16x16x32_bf16 v[102:105], v[42:45], v[142:145], v[102:105]
	s_nop 5
	v_cvt_pk_bf16_f32 v110, v110, v111
	v_cvt_pk_bf16_f32 v111, v112, v113
	v_cvt_pk_bf16_f32 v106, v106, v107
	v_mfma_f32_16x16x32_bf16 v[190:193], v[42:45], v[146:149], v[98:101]
	v_cvt_pk_bf16_f32 v107, v108, v109
	v_cvt_pk_bf16_f32 v102, v102, v103
	v_cvt_pk_bf16_f32 v103, v104, v105
	s_waitcnt lgkmcnt(1)
	v_mfma_f32_16x16x32_bf16 v[82:85], v[50:53], v[138:141], v[150:153]
	v_mfma_f32_16x16x32_bf16 v[66:69], v[50:53], v[146:149], v[154:157]
	s_waitcnt lgkmcnt(0)
	v_mfma_f32_16x16x32_bf16 v[42:45], v[186:189], v[142:145], v[70:73]
	s_nop 2
	ds_read_b128 v[70:73], v135 offset:20480
	ds_read_b128 v[98:101], v135 offset:21504
	ds_read_b128 v[150:153], v135 offset:22528
	ds_read_b128 v[154:157], v135 offset:23552
	v_cvt_pk_bf16_f32 v82, v82, v83
	v_cvt_pk_bf16_f32 v83, v84, v85
	v_mfma_f32_16x16x32_bf16 v[90:93], v[50:53], v[130:133], v[94:97]
	v_cvt_pk_bf16_f32 v66, v66, v67
	v_cvt_pk_bf16_f32 v67, v68, v69
	v_cvt_pk_bf16_f32 v42, v42, v43
	v_mfma_f32_16x16x32_bf16 v[58:61], v[186:189], v[130:133], v[78:81]
	v_cvt_pk_bf16_f32 v43, v44, v45
	s_nop 2
	v_cvt_pk_bf16_f32 v90, v90, v91
	v_cvt_pk_bf16_f32 v91, v92, v93
	s_waitcnt lgkmcnt(3)
	v_mfma_f32_16x16x32_bf16 v[94:97], v[70:73], v[130:133], v[62:65]
	v_mfma_f32_16x16x32_bf16 v[78:81], v[70:73], v[142:145], v[54:57]
	v_cvt_pk_bf16_f32 v58, v58, v59
	v_cvt_pk_bf16_f32 v59, v60, v61
	s_waitcnt lgkmcnt(2)
	v_mfma_f32_16x16x32_bf16 v[62:65], v[98:101], v[130:133], v[46:49]
	v_mfma_f32_16x16x32_bf16 v[54:57], v[98:101], v[138:141], v[174:177]
	v_mfma_f32_16x16x32_bf16 v[46:49], v[98:101], v[142:145], v[38:41]
	v_mfma_f32_16x16x32_bf16 v[38:41], v[98:101], v[146:149], v[178:181]
	v_lshl_add_u32 v98, s38, 8, v136
	v_mfma_f32_16x16x32_bf16 v[126:129], v[34:37], v[130:133], v[126:129]
	s_waitcnt lgkmcnt(1)
	v_mfma_f32_16x16x32_bf16 v[30:33], v[150:153], v[130:133], v[30:33]
	s_waitcnt lgkmcnt(0)
	v_mfma_f32_16x16x32_bf16 v[14:17], v[154:157], v[130:133], v[14:17]
	v_or_b32_e32 v130, v98, v134
	v_ashrrev_i32_e32 v131, 31, v130
	v_lshlrev_b64 v[98:99], 11, v[130:131]
	v_lshl_add_u64 v[98:99], s[8:9], 0, v[98:99]
	v_bfe_u32 v174, v185, 4, 1
	v_mad_u32_u24 v182, v174, 24, v182
	v_lshl_add_u64 v[98:99], v[98:99], 0, v[182:183]
	v_cvt_pk_bf16_f32 v100, v126, v127
	v_cvt_pk_bf16_f32 v101, v128, v129
	v_mfma_f32_16x16x32_bf16 v[122:125], v[34:37], v[138:141], v[122:125]
	v_mov_b32_e32 v174, v100
	v_mov_b32_e32 v175, v101
	v_or_b32_e32 v100, 16, v130
	v_ashrrev_i32_e32 v101, 31, v100
	v_lshlrev_b64 v[100:101], 11, v[100:101]
	v_lshl_add_u64 v[100:101], s[8:9], 0, v[100:101]
	v_lshl_add_u64 v[100:101], v[100:101], 0, v[182:183]
	s_nop 1
	v_cvt_pk_bf16_f32 v122, v122, v123
	v_cvt_pk_bf16_f32 v123, v124, v125
	v_mfma_f32_16x16x32_bf16 v[118:121], v[34:37], v[142:145], v[118:121]
	v_mov_b32_e32 v178, v122
	v_mov_b32_e32 v179, v123
	v_or_b32_e32 v122, 32, v130
	v_ashrrev_i32_e32 v123, 31, v122
	v_lshlrev_b64 v[122:123], 11, v[122:123]
	v_lshl_add_u64 v[122:123], s[8:9], 0, v[122:123]
	v_lshl_add_u64 v[122:123], v[122:123], 0, v[182:183]
	s_nop 1
	v_cvt_pk_bf16_f32 v118, v118, v119
	v_cvt_pk_bf16_f32 v119, v120, v121
	v_mfma_f32_16x16x32_bf16 v[114:117], v[34:37], v[146:149], v[114:117]
	v_mov_b32_e32 v194, v118
	v_mov_b32_e32 v195, v119
	v_or_b32_e32 v118, 48, v130
	v_ashrrev_i32_e32 v119, 31, v118
	v_mfma_f32_16x16x32_bf16 v[34:37], v[186:189], v[146:149], v[162:165]
	v_lshlrev_b64 v[118:119], 11, v[118:119]
	v_lshl_add_u64 v[118:119], s[8:9], 0, v[118:119]
	v_lshl_add_u64 v[118:119], v[118:119], 0, v[182:183]
	v_mfma_f32_16x16x32_bf16 v[74:77], v[50:53], v[142:145], v[86:89]
	v_cvt_pk_bf16_f32 v114, v114, v115
	s_nop 2
	v_cvt_pk_bf16_f32 v34, v34, v35
	v_cvt_pk_bf16_f32 v35, v36, v37
	v_mfma_f32_16x16x32_bf16 v[86:89], v[70:73], v[138:141], v[166:169]
	v_mov_b32_e32 v132, v34
	v_mov_b32_e32 v133, v35
	v_cvt_pk_bf16_f32 v34, v94, v95
	v_cvt_pk_bf16_f32 v35, v96, v97
; DI void st_bf4(u16* p, float a, float b, float c, float d) { *(uint2*)p = make_uint2(pk2(a, b), pk2(c, d)); }
;   template <int NT, int MT> DI void run(f32x4 (&acc)[NT][MT], int mb, int nb) const {
; #pragma unroll
;     for (int nt = 0; nt < NT; ++nt)
; #pragma unroll
;       for (int mt = 0; mt < MT; ++mt) {
;         f32x4 v = acc[nt][mt];
;         st_bf4(C + (size_t)(mb + mt * 16) * ldc + nb + nt * 16, v[0], v[1], v[2], v[3]);
;       }
	v_mfma_f32_16x16x32_bf16 v[70:73], v[70:73], v[146:149], v[170:173]
	v_mov_b32_e32 v162, v34
	v_mov_b32_e32 v163, v35
	s_nop 2
	v_cvt_pk_bf16_f32 v34, v86, v87
	v_cvt_pk_bf16_f32 v35, v88, v89
	v_mov_b32_e32 v224, v34
	v_mov_b32_e32 v225, v35
	v_cvt_pk_bf16_f32 v34, v78, v79
	v_cvt_pk_bf16_f32 v35, v80, v81
	v_mfma_f32_16x16x32_bf16 v[50:53], v[186:189], v[138:141], v[158:161]
	v_mov_b32_e32 v166, v34
	v_mov_b32_e32 v167, v35
	v_cvt_pk_bf16_f32 v34, v70, v71
	v_cvt_pk_bf16_f32 v35, v72, v73
	v_mfma_f32_16x16x32_bf16 v[26:29], v[150:153], v[138:141], v[26:29]
	v_mov_b32_e32 v170, v34
	v_mov_b32_e32 v171, v35
	v_cvt_pk_bf16_f32 v34, v62, v63
	v_cvt_pk_bf16_f32 v35, v64, v65
	v_mfma_f32_16x16x32_bf16 v[22:25], v[150:153], v[142:145], v[22:25]
	v_mov_b32_e32 v164, v34
	v_mov_b32_e32 v165, v35
	s_nop 1
	v_permlane16_swap_b32_e32 v162, v164
	v_permlane16_swap_b32_e32 v163, v165
	global_store_dwordx4 v[98:99], v[162:165], off offset:128
	v_cvt_pk_bf16_f32 v34, v54, v55
	v_cvt_pk_bf16_f32 v35, v56, v57
	v_mfma_f32_16x16x32_bf16 v[18:21], v[150:153], v[146:149], v[18:21]
	v_mov_b32_e32 v226, v34
	v_mov_b32_e32 v227, v35
	s_nop 1
	v_permlane16_swap_b32_e32 v224, v226
	v_permlane16_swap_b32_e32 v225, v227
	global_store_dwordx4 v[100:101], v[224:227], off offset:128
	v_cvt_pk_bf16_f32 v34, v46, v47
	v_cvt_pk_bf16_f32 v35, v48, v49
	v_mfma_f32_16x16x32_bf16 v[10:13], v[154:157], v[138:141], v[10:13]
	v_cvt_pk_bf16_f32 v115, v116, v117
	v_mov_b32_e32 v196, v102
	v_mov_b32_e32 v197, v103
	s_nop 1
	v_permlane16_swap_b32_e32 v194, v196
	v_permlane16_swap_b32_e32 v195, v197
	global_store_dwordx4 v[122:123], v[194:197], off
	v_cvt_pk_bf16_f32 v102, v190, v191
	v_mfma_f32_16x16x32_bf16 v[6:9], v[154:157], v[142:145], v[6:9]
	v_cvt_pk_bf16_f32 v103, v192, v193
	v_cvt_pk_bf16_f32 v74, v74, v75
	v_cvt_pk_bf16_f32 v75, v76, v77
	v_mfma_f32_16x16x32_bf16 v[2:5], v[154:157], v[146:149], v[2:5]
	v_cvt_pk_bf16_f32 v50, v50, v51
	v_cvt_pk_bf16_f32 v51, v52, v53
	v_mov_b32_e32 v168, v34
	v_mov_b32_e32 v169, v35
	s_nop 1
	v_permlane16_swap_b32_e32 v166, v168
	v_permlane16_swap_b32_e32 v167, v169
	global_store_dwordx4 v[122:123], v[166:169], off offset:128
	v_cvt_pk_bf16_f32 v34, v38, v39
	v_cvt_pk_bf16_f32 v35, v40, v41
	v_cvt_pk_bf16_f32 v30, v30, v31
	v_cvt_pk_bf16_f32 v31, v32, v33
	v_cvt_pk_bf16_f32 v26, v26, v27
	v_cvt_pk_bf16_f32 v27, v28, v29
	v_cvt_pk_bf16_f32 v22, v22, v23
	v_cvt_pk_bf16_f32 v23, v24, v25
	v_cvt_pk_bf16_f32 v18, v18, v19
	v_cvt_pk_bf16_f32 v19, v20, v21
	v_cvt_pk_bf16_f32 v14, v14, v15
	v_cvt_pk_bf16_f32 v15, v16, v17
	v_cvt_pk_bf16_f32 v10, v10, v11
	v_cvt_pk_bf16_f32 v11, v12, v13
	v_cvt_pk_bf16_f32 v6, v6, v7
	v_cvt_pk_bf16_f32 v7, v8, v9
	v_cvt_pk_bf16_f32 v2, v2, v3
	v_cvt_pk_bf16_f32 v3, v4, v5
	v_mov_b32_e32 v138, v114
	v_mov_b32_e32 v139, v115
	v_mov_b32_e32 v176, v110
	v_mov_b32_e32 v177, v111
	s_nop 1
	v_permlane16_swap_b32_e32 v174, v176
	v_permlane16_swap_b32_e32 v175, v177
	global_store_dwordx4 v[98:99], v[174:177], off
	v_mov_b32_e32 v180, v106
	v_mov_b32_e32 v181, v107
	s_nop 1
	v_permlane16_swap_b32_e32 v178, v180
	v_permlane16_swap_b32_e32 v179, v181
	global_store_dwordx4 v[100:101], v[178:181], off
	v_mov_b32_e32 v140, v102
	v_mov_b32_e32 v141, v103
	s_nop 1
	v_permlane16_swap_b32_e32 v138, v140
	v_permlane16_swap_b32_e32 v139, v141
	global_store_dwordx4 v[118:119], v[138:141], off
	s_nop 1
	v_mov_b32_e32 v138, v90
	v_mov_b32_e32 v139, v91
	v_mov_b32_e32 v142, v82
	v_mov_b32_e32 v143, v83
	v_mov_b32_e32 v146, v74
	v_mov_b32_e32 v147, v75
	v_mov_b32_e32 v130, v66
	v_mov_b32_e32 v131, v67
	s_nop 1
	v_permlane16_swap_b32_e32 v130, v132
	v_permlane16_swap_b32_e32 v131, v133
	global_store_dwordx4 v[118:119], v[130:133], off offset:64
	v_mov_b32_e32 v140, v58
	v_mov_b32_e32 v141, v59
	s_nop 1
	v_permlane16_swap_b32_e32 v138, v140
	v_permlane16_swap_b32_e32 v139, v141
	global_store_dwordx4 v[98:99], v[138:141], off offset:64
	v_mov_b32_e32 v144, v50
	v_mov_b32_e32 v145, v51
	s_nop 1
	v_permlane16_swap_b32_e32 v142, v144
	v_permlane16_swap_b32_e32 v143, v145
	global_store_dwordx4 v[100:101], v[142:145], off offset:64
	v_mov_b32_e32 v148, v42
	v_mov_b32_e32 v149, v43
	s_nop 1
	v_permlane16_swap_b32_e32 v146, v148
	v_permlane16_swap_b32_e32 v147, v149
	global_store_dwordx4 v[122:123], v[146:149], off offset:64
	v_mov_b32_e32 v172, v34
	v_mov_b32_e32 v173, v35
	s_nop 1
	v_permlane16_swap_b32_e32 v170, v172
	v_permlane16_swap_b32_e32 v171, v173
	global_store_dwordx4 v[118:119], v[170:173], off offset:128
	v_mov_b32_e32 v130, v30
	v_mov_b32_e32 v131, v31
	v_mov_b32_e32 v138, v26
	v_mov_b32_e32 v139, v27
	v_mov_b32_e32 v142, v22
	v_mov_b32_e32 v143, v23
	v_mov_b32_e32 v146, v18
	v_mov_b32_e32 v147, v19
	v_mov_b32_e32 v132, v14
	v_mov_b32_e32 v133, v15
	s_nop 1
	v_permlane16_swap_b32_e32 v130, v132
	v_permlane16_swap_b32_e32 v131, v133
	global_store_dwordx4 v[98:99], v[130:133], off offset:192
	v_mov_b32_e32 v140, v10
	v_mov_b32_e32 v141, v11
	s_nop 1
	v_permlane16_swap_b32_e32 v138, v140
	v_permlane16_swap_b32_e32 v139, v141
	global_store_dwordx4 v[100:101], v[138:141], off offset:192
	v_mov_b32_e32 v144, v6
	v_mov_b32_e32 v145, v7
	s_nop 1
	v_permlane16_swap_b32_e32 v142, v144
	v_permlane16_swap_b32_e32 v143, v145
	global_store_dwordx4 v[122:123], v[142:145], off offset:192
	v_mov_b32_e32 v148, v2
	v_mov_b32_e32 v149, v3
	s_nop 1
	v_permlane16_swap_b32_e32 v146, v148
	v_permlane16_swap_b32_e32 v147, v149
	global_store_dwordx4 v[118:119], v[146:149], off offset:192
	s_branch .LBB0_285

; DI int get_bid() { int b = blockIdx.x; asm volatile("" : "+s"(b)); return b; }
; template <int BM, class Epi>
; DI void gemm_dma(const u16* __restrict__ X, long ldx, const u16* __restrict__ W, long ldw, int K, char* smem,
;                  int m0, int n0, const Epi& epi) {
;     ...
;   const int wu = __builtin_amdgcn_readfirstlane(wave);
;   const unsigned sbase = (unsigned)__builtin_amdgcn_readfirstlane((int)(unsigned)(size_t)smem);
;   const int r16 = lane >> 2, chunk = (lane & 3) ^ ((4 - (r16 >> 2)) & 3);
;   const u16* xs = X + (long)(wu * XD * 16 + r16) * ldx + (chunk << 3);
;   const u16* ws = W + (long)(wu * 32 + r16) * ldw + (chunk << 3);
;   const long ldx16 = 16 * ldx, ldw16 = 16 * ldw;
;   const unsigned xdst = sbase + wu * XD * 1024, wdst = sbase + BM * 64 + wu * 2048;
;     ...
;   const int nk = K >> 5;
;   __syncthreads();
; #pragma unroll
;   for (int s = 0; s < D - 1; ++s) GD_ISSUE(s)
; DI void phase_odd(const Params& p, int o, int sub, char* smem) {
;     ...
;     for (int t = get_bid(); t < 1088 + 832; t += gridDim.x) {
;       if (t < 1088) {
;         int b, tm, tn; long kv0, ld; u16* C;
;         if (t < 512) { b = t >> 8; const int r = t & 255; tm = r >> 6; tn = r & 63; kv0 = (long)b * 8192; ld = 8192; C = vtb + (size_t)b * 1024 * 8192; }
;         else { const int u = t - 512; b = u / 36; const int r = u % 36; tm = r / 9; tn = r % 9; kv0 = (long)M_PROMPT + (long)b * KSTR_S; ld = KSTR_S;
;                C = vtb + (size_t)2 * 1024 * 8192 + (size_t)b * 1024 * KSTR_S; }
;         EpiVT ev{C, ld};
;         gemm_dma<256>(W + WO_KV + (size_t)(1024 + tm * 256) * 256, 256, ckvb + (size_t)(kv0 + tn * 128) * 256, 256, 256, smem, tm * 256, tn * 128, ev);
;       } else {
;         knope_tile(p, 256 + (t - 1088), smem);
.LBB0_966:
	s_cmpk_gt_i32 s4, 0x77f
	s_cbranch_scc1 .LBB0_974
	s_cmpk_gt_i32 s4, 0x43f
	s_mov_b64 s[38:39], -1
	s_cbranch_scc0 .LBB0_969
	s_add_i32 s5, s4, 0xfffffcc0
	s_bfe_u32 s98, s5, 0x30003
	s_and_b32 s99, s5, 7
	s_lshl_b32 s99, s99, 3
	s_andn2_b32 s5, s5, 63
	s_or_b32 s5, s5, s99
	s_or_b32 s5, s5, s98
	s_lshr_b32 s6, s5, 3
	s_and_b32 s5, s5, 7
	s_lshl_b32 s7, s6, 17
	s_add_u32 s8, s0, s7
	s_addc_u32 s9, s1, 0
	s_lshl_b32 s7, s5, 16
	v_mov_b32_e32 v9, v185
	s_add_u32 s10, s87, s7
	s_addc_u32 s11, s90, 0
	v_readfirstlane_b32 s7, v9
	v_lshrrev_b32_e32 v4, 4, v9
	s_ashr_i32 s12, s7, 6
	v_bfe_u32 v6, v9, 2, 4
	v_sub_u32_e32 v4, 0, v4
	s_andn2_b32 s7, s7, 63
	v_lshrrev_b32_e32 v1, 2, v9
	v_xor_b32_e32 v7, v9, v4
	v_or_b32_e32 v4, s7, v6
	v_and_b32_e32 v89, 15, v9
	v_bfe_u32 v88, v9, 4, 2
	v_sub_u32_e32 v1, 0, v1
	v_ashrrev_i32_e32 v5, 31, v4
	v_lshlrev_b32_e32 v0, 6, v89
	v_bitop3_b32 v1, v88, v1, 3 bitop3:0x78
	v_lshlrev_b64 v[4:5], 9, v[4:5]
	v_lshlrev_b32_e32 v7, 4, v7
	v_lshl_or_b32 v6, s12, 5, v6
	v_lshl_or_b32 v8, v1, 4, v0
	v_mov_b32_e32 v0, v183
	v_lshl_add_u64 v[4:5], s[8:9], 0, v[4:5]
	v_and_b32_e32 v182, 48, v7
	v_ashrrev_i32_e32 v7, 31, v6
	v_lshl_add_u64 v[4:5], v[4:5], 0, v[182:183]
	v_lshlrev_b64 v[6:7], 9, v[6:7]
	s_lshl_b32 s14, s12, 12
	s_waitcnt lgkmcnt(0)
	s_barrier
	s_mov_b32 m0, s14
	s_nop 0
	global_load_lds_dwordx4 v[4:5], off
	s_mov_b64 s[8:9], 0x2000
	v_lshl_add_u64 v[6:7], s[10:11], 0, v[6:7]
	v_lshl_add_u64 v[10:11], v[4:5], 0, s[8:9]
	s_or_b32 s15, s14, 0x400
	s_mov_b32 m0, s15
	s_nop 0
	global_load_lds_dwordx4 v[10:11], off
	s_mov_b64 s[10:11], 0x4000
	v_lshl_add_u64 v[10:11], v[4:5], 0, s[10:11]
	s_or_b32 s16, s14, 0x800
	s_mov_b32 m0, s16
	s_nop 0
	global_load_lds_dwordx4 v[10:11], off
	s_mov_b64 s[10:11], 0x6000
	s_lshl_b32 s41, s12, 11
	v_lshl_add_u64 v[10:11], v[4:5], 0, s[10:11]
	s_or_b32 s17, s14, 0xc00
	s_mov_b32 m0, s17
	s_nop 0
	global_load_lds_dwordx4 v[10:11], off
	v_lshl_add_u64 v[6:7], v[6:7], 0, v[182:183]
	s_add_i32 s13, s41, 0x4000
	s_mov_b32 m0, s13
	s_nop 0
	global_load_lds_dwordx4 v[6:7], off
	v_lshl_add_u64 v[10:11], v[6:7], 0, s[8:9]
	s_add_i32 s18, s41, 0x4400
	s_mov_b32 m0, s18
	s_nop 0
	global_load_lds_dwordx4 v[10:11], off
	v_lshl_add_u64 v[10:11], v[4:5], 0, 64
	s_add_i32 s7, s14, 0x6000
	s_mov_b32 m0, s7
	s_nop 0
	global_load_lds_dwordx4 v[10:11], off
	s_mov_b64 s[20:21], 0x2040
	v_lshl_add_u64 v[10:11], v[4:5], 0, s[20:21]
	s_add_i32 s8, s14, 0x6400
	s_mov_b32 m0, s8
	s_nop 0
	global_load_lds_dwordx4 v[10:11], off
	s_mov_b64 s[10:11], 0x4040
	v_lshl_add_u64 v[10:11], v[4:5], 0, s[10:11]
	s_add_i32 s9, s14, 0x6800
	s_mov_b32 m0, s9
	s_nop 0
	global_load_lds_dwordx4 v[10:11], off
	s_mov_b64 s[10:11], 0x6040
	v_lshl_add_u64 v[10:11], v[4:5], 0, s[10:11]
	s_add_i32 s10, s14, 0x6c00
	s_mov_b32 m0, s10
	s_nop 0
	global_load_lds_dwordx4 v[10:11], off
	v_lshl_add_u64 v[12:13], v[6:7], 0, 64
	s_add_i32 s11, s41, 0xa000
	s_mov_b32 m0, s11
	s_nop 0
	global_load_lds_dwordx4 v[12:13], off
	v_lshl_add_u64 v[10:11], v[6:7], 0, s[20:21]
	s_add_i32 s12, s41, 0xa400
	s_mov_b32 m0, s12
	s_nop 0
	global_load_lds_dwordx4 v[10:11], off
	s_waitcnt vmcnt(6)
	s_barrier
	v_lshl_add_u64 v[12:13], v[4:5], 0, s[28:29]
	s_add_i32 s19, s14, 0xc000
	s_mov_b32 m0, s19
	s_nop 0
	global_load_lds_dwordx4 v[12:13], off
	s_mov_b64 s[20:21], 0x2080
	v_lshl_add_u64 v[12:13], v[4:5], 0, s[20:21]
	s_add_i32 s34, s14, 0xc400
	s_mov_b32 m0, s34
	s_nop 0
	global_load_lds_dwordx4 v[12:13], off
	v_lshl_add_u64 v[12:13], v[4:5], 0, s[94:95]
	s_add_i32 s38, s14, 0xc800
	s_mov_b32 m0, s38
	s_nop 0
	global_load_lds_dwordx4 v[12:13], off
	s_mov_b64 s[22:23], 0x6080
	v_lshl_add_u64 v[12:13], v[4:5], 0, s[22:23]
	s_add_i32 s39, s14, 0xcc00
	s_mov_b32 m0, s39
	s_nop 0
	global_load_lds_dwordx4 v[12:13], off
	v_and_b32_e32 v90, 0xffffffc0, v9
	v_lshl_add_u64 v[10:11], v[6:7], 0, s[28:29]
	s_add_i32 s40, s41, 0x10000
	s_mov_b32 m0, s40
	s_nop 0
	global_load_lds_dwordx4 v[10:11], off
	v_lshl_add_u64 v[10:11], v[6:7], 0, s[20:21]
	s_add_i32 s41, s41, 0x10400
	s_mov_b32 m0, s41
	s_nop 0
	global_load_lds_dwordx4 v[10:11], off
	v_lshl_or_b32 v9, v90, 6, v8
	ds_read_b128 v[10:13], v9
	ds_read_b128 v[14:17], v9 offset:1024
	ds_read_b128 v[18:21], v9 offset:2048
	ds_read_b128 v[22:25], v9 offset:3072
	ds_read_b128 v[26:29], v8 offset:16384
	ds_read_b128 v[30:33], v8 offset:17408
	ds_read_b128 v[34:37], v8 offset:18432
	ds_read_b128 v[38:41], v8 offset:19456
	ds_read_b128 v[96:99], v8 offset:20480
	ds_read_b128 v[100:103], v8 offset:21504
	ds_read_b128 v[104:107], v8 offset:22528
	ds_read_b128 v[108:111], v8 offset:23552
	s_mov_b64 s[20:21], 0xc0
	v_mov_b32_e32 v1, v0
	v_mov_b32_e32 v2, v0
	v_mov_b32_e32 v3, v0
	v_lshl_add_u64 v[86:87], v[4:5], 0, s[20:21]
	v_lshl_add_u64 v[148:149], v[6:7], 0, s[20:21]
	s_waitcnt vmcnt(6)
	s_waitcnt lgkmcnt(0)
	s_barrier
; template <int N> DI void wait_vm() { asm volatile("s_waitcnt vmcnt(%0)" ::"n"(N) : "memory"); }
; template <int BM, class Epi>
; DI void gemm_dma(const u16* __restrict__ X, long ldx, const u16* __restrict__ W, long ldw, int K, char* smem,
;                  int m0, int n0, const Epi& epi) {
;     ...
;   do {
;     if (kt + D - 2 < nk) wait_vm<PW * (D - 2)>(); else wait_vm<0>();
;     __syncthreads();
;     if (kt + D - 1 < nk) GD_ISSUE(nxt)
;     nxt = (nxt + 1 == D) ? 0 : nxt + 1;
;     const char* base = smem + cur * STG;
;     cur = (cur + 1 == D) ? 0 : cur + 1;
;     bf16x8 xf[MT];
; #pragma unroll
;     for (int i = 0; i < MT; ++i) xf[i] = *(const bf16x8*)(base + (xrow0 + i * 16) * 64 + rd);
; #pragma unroll
;     for (int nh = 0; nh < NT / 4; ++nh) {
;       bf16x8 wf[4];
; #pragma unroll
;       for (int i = 0; i < 4; ++i) wf[i] = *(const bf16x8*)(base + BM * 64 + (wrow0 + (nh * 4 + i) * 16) * 64 + rd);
; #pragma unroll
;       for (int i = 0; i < 4; ++i)
; #pragma unroll
;         for (int mt = 0; mt < MT; ++mt)
;           acc[nh * 4 + i][mt] = __builtin_amdgcn_mfma_f32_16x16x32_bf16(wf[i], xf[mt], acc[nh * 4 + i][mt], 0, 0, 0);
;     }
;   } while (++kt < nk);
	s_mov_b32 m0, s14
	s_nop 0
	global_load_lds_dwordx4 v[86:87], off
	s_mov_b64 s[20:21], 0x20c0
	v_mfma_f32_16x16x32_bf16 v[42:45], v[26:29], v[10:13], v[0:3]
	s_mov_b64 s[22:23], 0x40c0
	v_or_b32_e32 v91, 0x10000, v8
	v_or_b32_e32 v174, 0x10400, v8
	v_mfma_f32_16x16x32_bf16 v[46:49], v[26:29], v[14:17], v[0:3]
	v_or_b32_e32 v175, 0x10800, v8
	v_or_b32_e32 v176, 0x10c00, v8
	v_or_b32_e32 v177, 0x11000, v8
	v_mfma_f32_16x16x32_bf16 v[50:53], v[26:29], v[18:21], v[0:3]
	v_or_b32_e32 v178, 0x11400, v8
	v_or_b32_e32 v179, 0x11800, v8
	v_or_b32_e32 v180, 0x11c00, v8
	v_mfma_f32_16x16x32_bf16 v[26:29], v[26:29], v[22:25], v[0:3]
	v_lshl_add_u32 v90, s6, 8, v90
	s_lshl_b32 s5, s5, 8
	v_lshl_or_b32 v182, v88, 3, s5
	v_mfma_f32_16x16x32_bf16 v[54:57], v[30:33], v[10:13], v[0:3]
	v_mfma_f32_16x16x32_bf16 v[58:61], v[30:33], v[14:17], v[0:3]
	v_mfma_f32_16x16x32_bf16 v[62:65], v[30:33], v[18:21], v[0:3]
	v_mfma_f32_16x16x32_bf16 v[30:33], v[30:33], v[22:25], v[0:3]
	v_mfma_f32_16x16x32_bf16 v[66:69], v[34:37], v[10:13], v[0:3]
	v_mfma_f32_16x16x32_bf16 v[70:73], v[34:37], v[14:17], v[0:3]
	v_mfma_f32_16x16x32_bf16 v[74:77], v[34:37], v[18:21], v[0:3]
	v_mfma_f32_16x16x32_bf16 v[34:37], v[34:37], v[22:25], v[0:3]
	v_mfma_f32_16x16x32_bf16 v[78:81], v[38:41], v[10:13], v[0:3]
	v_mfma_f32_16x16x32_bf16 v[82:85], v[38:41], v[14:17], v[0:3]
	v_mfma_f32_16x16x32_bf16 v[92:95], v[38:41], v[18:21], v[0:3]
	v_mfma_f32_16x16x32_bf16 v[38:41], v[38:41], v[22:25], v[0:3]
	v_mfma_f32_16x16x32_bf16 v[112:115], v[96:99], v[10:13], v[0:3]
	v_mfma_f32_16x16x32_bf16 v[116:119], v[96:99], v[14:17], v[0:3]
	v_mfma_f32_16x16x32_bf16 v[120:123], v[96:99], v[18:21], v[0:3]
	v_mfma_f32_16x16x32_bf16 v[96:99], v[96:99], v[22:25], v[0:3]
	v_mfma_f32_16x16x32_bf16 v[124:127], v[100:103], v[10:13], v[0:3]
	v_mfma_f32_16x16x32_bf16 v[128:131], v[100:103], v[14:17], v[0:3]
	v_mfma_f32_16x16x32_bf16 v[132:135], v[100:103], v[18:21], v[0:3]
	v_mfma_f32_16x16x32_bf16 v[100:103], v[100:103], v[22:25], v[0:3]
	v_mfma_f32_16x16x32_bf16 v[136:139], v[104:107], v[10:13], v[0:3]
	v_mfma_f32_16x16x32_bf16 v[140:143], v[104:107], v[14:17], v[0:3]
	v_mfma_f32_16x16x32_bf16 v[144:147], v[104:107], v[18:21], v[0:3]
	v_mfma_f32_16x16x32_bf16 v[104:107], v[104:107], v[22:25], v[0:3]
	v_mfma_f32_16x16x32_bf16 v[10:13], v[108:111], v[10:13], v[0:3]
	v_mfma_f32_16x16x32_bf16 v[14:17], v[108:111], v[14:17], v[0:3]
	v_mfma_f32_16x16x32_bf16 v[18:21], v[108:111], v[18:21], v[0:3]
	v_mfma_f32_16x16x32_bf16 v[0:3], v[108:111], v[22:25], v[0:3]
	v_lshl_add_u64 v[22:23], v[4:5], 0, s[20:21]
	s_mov_b32 m0, s15
	s_nop 0
	global_load_lds_dwordx4 v[22:23], off
	v_lshl_add_u64 v[22:23], v[4:5], 0, s[22:23]
	s_mov_b32 m0, s16
	s_nop 0
	global_load_lds_dwordx4 v[22:23], off
	s_mov_b64 s[22:23], 0x60c0
	v_lshl_add_u64 v[22:23], v[4:5], 0, s[22:23]
	s_mov_b32 m0, s17
	s_nop 0
	global_load_lds_dwordx4 v[22:23], off
	v_lshl_add_u64 v[22:23], v[6:7], 0, s[20:21]
	s_mov_b32 m0, s13
	s_nop 0
	global_load_lds_dwordx4 v[148:149], off
	s_mov_b64 s[20:21], 0x100
	s_mov_b32 m0, s18
	s_nop 0
	global_load_lds_dwordx4 v[22:23], off
	ds_read_b128 v[22:25], v9 offset:24576
	ds_read_b128 v[108:111], v9 offset:25600
	ds_read_b128 v[148:151], v9 offset:26624
	ds_read_b128 v[152:155], v9 offset:27648
	ds_read_b128 v[156:159], v8 offset:40960
	ds_read_b128 v[160:163], v8 offset:41984
	ds_read_b128 v[164:167], v8 offset:43008
	ds_read_b128 v[168:171], v8 offset:44032
	s_waitcnt lgkmcnt(3)
	v_mfma_f32_16x16x32_bf16 v[42:45], v[156:159], v[22:25], v[42:45]
	v_lshl_add_u64 v[86:87], v[4:5], 0, s[20:21]
	v_lshl_add_u64 v[172:173], v[6:7], 0, s[20:21]
	s_mov_b64 s[20:21], 0x2100
	v_mfma_f32_16x16x32_bf16 v[46:49], v[156:159], v[108:111], v[46:49]
	s_mov_b64 s[22:23], 0x4100
	v_mfma_f32_16x16x32_bf16 v[50:53], v[156:159], v[148:151], v[50:53]
	v_mfma_f32_16x16x32_bf16 v[26:29], v[156:159], v[152:155], v[26:29]
	s_waitcnt lgkmcnt(2)
	v_mfma_f32_16x16x32_bf16 v[54:57], v[160:163], v[22:25], v[54:57]
	v_mfma_f32_16x16x32_bf16 v[58:61], v[160:163], v[108:111], v[58:61]
	v_mfma_f32_16x16x32_bf16 v[62:65], v[160:163], v[148:151], v[62:65]
	v_mfma_f32_16x16x32_bf16 v[30:33], v[160:163], v[152:155], v[30:33]
	s_waitcnt lgkmcnt(1)
	v_mfma_f32_16x16x32_bf16 v[66:69], v[164:167], v[22:25], v[66:69]
	v_mfma_f32_16x16x32_bf16 v[70:73], v[164:167], v[108:111], v[70:73]
	v_mfma_f32_16x16x32_bf16 v[74:77], v[164:167], v[148:151], v[74:77]
	v_mfma_f32_16x16x32_bf16 v[34:37], v[164:167], v[152:155], v[34:37]
	s_waitcnt lgkmcnt(0)
	v_mfma_f32_16x16x32_bf16 v[78:81], v[168:171], v[22:25], v[78:81]
	v_mfma_f32_16x16x32_bf16 v[82:85], v[168:171], v[108:111], v[82:85]
	v_mfma_f32_16x16x32_bf16 v[92:95], v[168:171], v[148:151], v[92:95]
	v_mfma_f32_16x16x32_bf16 v[38:41], v[168:171], v[152:155], v[38:41]
	ds_read_b128 v[156:159], v8 offset:45056
	ds_read_b128 v[160:163], v8 offset:46080
	ds_read_b128 v[164:167], v8 offset:47104
	ds_read_b128 v[168:171], v8 offset:48128
	s_waitcnt vmcnt(6)
	s_waitcnt lgkmcnt(0)
	s_barrier
; template <int N> DI void wait_vm() { asm volatile("s_waitcnt vmcnt(%0)" ::"n"(N) : "memory"); }
; template <int BM, class Epi>
; DI void gemm_dma(const u16* __restrict__ X, long ldx, const u16* __restrict__ W, long ldw, int K, char* smem,
;                  int m0, int n0, const Epi& epi) {
;     ...
;   do {
;     if (kt + D - 2 < nk) wait_vm<PW * (D - 2)>(); else wait_vm<0>();
;     __syncthreads();
;     if (kt + D - 1 < nk) GD_ISSUE(nxt)
;     nxt = (nxt + 1 == D) ? 0 : nxt + 1;
;     const char* base = smem + cur * STG;
;     cur = (cur + 1 == D) ? 0 : cur + 1;
;     bf16x8 xf[MT];
; #pragma unroll
;     for (int i = 0; i < MT; ++i) xf[i] = *(const bf16x8*)(base + (xrow0 + i * 16) * 64 + rd);
; #pragma unroll
;     for (int nh = 0; nh < NT / 4; ++nh) {
;       bf16x8 wf[4];
; #pragma unroll
;       for (int i = 0; i < 4; ++i) wf[i] = *(const bf16x8*)(base + BM * 64 + (wrow0 + (nh * 4 + i) * 16) * 64 + rd);
; #pragma unroll
;       for (int i = 0; i < 4; ++i)
; #pragma unroll
;         for (int mt = 0; mt < MT; ++mt)
;           acc[nh * 4 + i][mt] = __builtin_amdgcn_mfma_f32_16x16x32_bf16(wf[i], xf[mt], acc[nh * 4 + i][mt], 0, 0, 0);
;     }
;   } while (++kt < nk);
	s_mov_b32 m0, s7
	s_nop 0
	global_load_lds_dwordx4 v[86:87], off
	v_mfma_f32_16x16x32_bf16 v[112:115], v[156:159], v[22:25], v[112:115]
	v_mfma_f32_16x16x32_bf16 v[124:127], v[160:163], v[22:25], v[124:127]
	v_mfma_f32_16x16x32_bf16 v[136:139], v[164:167], v[22:25], v[136:139]
	v_mfma_f32_16x16x32_bf16 v[10:13], v[168:171], v[22:25], v[10:13]
	v_lshl_add_u64 v[22:23], v[4:5], 0, s[20:21]
	s_mov_b32 m0, s8
	s_nop 0
	global_load_lds_dwordx4 v[22:23], off
	v_lshl_add_u64 v[22:23], v[4:5], 0, s[22:23]
	s_mov_b32 m0, s9
	s_nop 0
	global_load_lds_dwordx4 v[22:23], off
	s_mov_b64 s[22:23], 0x6100
	v_lshl_add_u64 v[22:23], v[4:5], 0, s[22:23]
	s_mov_b32 m0, s10
	s_nop 0
	global_load_lds_dwordx4 v[22:23], off
	v_lshl_add_u64 v[22:23], v[6:7], 0, s[20:21]
	s_mov_b32 m0, s11
	s_nop 0
	global_load_lds_dwordx4 v[172:173], off
	v_mfma_f32_16x16x32_bf16 v[116:119], v[156:159], v[108:111], v[116:119]
	s_mov_b32 m0, s12
	s_nop 0
	global_load_lds_dwordx4 v[22:23], off
	s_mov_b64 s[20:21], 0x140
	v_lshl_add_u64 v[86:87], v[4:5], 0, s[20:21]
	v_mfma_f32_16x16x32_bf16 v[120:123], v[156:159], v[148:151], v[120:123]
	v_lshl_add_u64 v[172:173], v[6:7], 0, s[20:21]
	s_mov_b64 s[20:21], 0x2140
	s_mov_b64 s[22:23], 0x4140
	v_mfma_f32_16x16x32_bf16 v[96:99], v[156:159], v[152:155], v[96:99]
	v_mfma_f32_16x16x32_bf16 v[128:131], v[160:163], v[108:111], v[128:131]
	v_mfma_f32_16x16x32_bf16 v[132:135], v[160:163], v[148:151], v[132:135]
	v_mfma_f32_16x16x32_bf16 v[100:103], v[160:163], v[152:155], v[100:103]
	v_mfma_f32_16x16x32_bf16 v[140:143], v[164:167], v[108:111], v[140:143]
	v_mfma_f32_16x16x32_bf16 v[144:147], v[164:167], v[148:151], v[144:147]
	v_mfma_f32_16x16x32_bf16 v[104:107], v[164:167], v[152:155], v[104:107]
	v_mfma_f32_16x16x32_bf16 v[14:17], v[168:171], v[108:111], v[14:17]
	v_mfma_f32_16x16x32_bf16 v[18:21], v[168:171], v[148:151], v[18:21]
	v_mfma_f32_16x16x32_bf16 v[0:3], v[168:171], v[152:155], v[0:3]
	ds_read_b128 v[22:25], v9 offset:49152
	ds_read_b128 v[108:111], v9 offset:50176
	ds_read_b128 v[148:151], v9 offset:51200
	ds_read_b128 v[152:155], v9 offset:52224
	ds_read_b128 v[156:159], v91
	ds_read_b128 v[160:163], v174
	ds_read_b128 v[164:167], v175
	ds_read_b128 v[168:171], v176
	s_waitcnt lgkmcnt(3)
	v_mfma_f32_16x16x32_bf16 v[42:45], v[156:159], v[22:25], v[42:45]
	v_mfma_f32_16x16x32_bf16 v[46:49], v[156:159], v[108:111], v[46:49]
	v_mfma_f32_16x16x32_bf16 v[50:53], v[156:159], v[148:151], v[50:53]
	v_mfma_f32_16x16x32_bf16 v[26:29], v[156:159], v[152:155], v[26:29]
	ds_read_b128 v[156:159], v177
	s_waitcnt lgkmcnt(3)
	v_mfma_f32_16x16x32_bf16 v[54:57], v[160:163], v[22:25], v[54:57]
	v_mfma_f32_16x16x32_bf16 v[58:61], v[160:163], v[108:111], v[58:61]
	v_mfma_f32_16x16x32_bf16 v[62:65], v[160:163], v[148:151], v[62:65]
	v_mfma_f32_16x16x32_bf16 v[30:33], v[160:163], v[152:155], v[30:33]
	ds_read_b128 v[160:163], v178
	s_waitcnt lgkmcnt(3)
	v_mfma_f32_16x16x32_bf16 v[66:69], v[164:167], v[22:25], v[66:69]
	v_mfma_f32_16x16x32_bf16 v[70:73], v[164:167], v[108:111], v[70:73]
	v_mfma_f32_16x16x32_bf16 v[74:77], v[164:167], v[148:151], v[74:77]
	v_mfma_f32_16x16x32_bf16 v[34:37], v[164:167], v[152:155], v[34:37]
	ds_read_b128 v[164:167], v179
	s_waitcnt lgkmcnt(3)
	v_mfma_f32_16x16x32_bf16 v[78:81], v[168:171], v[22:25], v[78:81]
	v_mfma_f32_16x16x32_bf16 v[82:85], v[168:171], v[108:111], v[82:85]
	v_mfma_f32_16x16x32_bf16 v[92:95], v[168:171], v[148:151], v[92:95]
	v_mfma_f32_16x16x32_bf16 v[38:41], v[168:171], v[152:155], v[38:41]
	ds_read_b128 v[168:171], v180
	s_waitcnt vmcnt(6)
	s_waitcnt lgkmcnt(0)
	s_barrier
	s_mov_b32 m0, s19
	s_nop 0
	global_load_lds_dwordx4 v[86:87], off
	v_mfma_f32_16x16x32_bf16 v[112:115], v[156:159], v[22:25], v[112:115]
	v_mfma_f32_16x16x32_bf16 v[124:127], v[160:163], v[22:25], v[124:127]
	v_mfma_f32_16x16x32_bf16 v[136:139], v[164:167], v[22:25], v[136:139]
	v_mfma_f32_16x16x32_bf16 v[10:13], v[168:171], v[22:25], v[10:13]
	v_lshl_add_u64 v[22:23], v[4:5], 0, s[20:21]
	s_mov_b32 m0, s34
	s_nop 0
	global_load_lds_dwordx4 v[22:23], off
	v_lshl_add_u64 v[22:23], v[4:5], 0, s[22:23]
	s_mov_b32 m0, s38
	s_nop 0
	global_load_lds_dwordx4 v[22:23], off
	s_mov_b64 s[22:23], 0x6140
	v_lshl_add_u64 v[22:23], v[4:5], 0, s[22:23]
	s_mov_b32 m0, s39
	s_nop 0
	global_load_lds_dwordx4 v[22:23], off
	v_lshl_add_u64 v[22:23], v[6:7], 0, s[20:21]
	s_mov_b32 m0, s40
	s_nop 0
	global_load_lds_dwordx4 v[172:173], off
	v_mfma_f32_16x16x32_bf16 v[116:119], v[156:159], v[108:111], v[116:119]
	s_mov_b32 m0, s41
	s_nop 0
	global_load_lds_dwordx4 v[22:23], off
	s_mov_b64 s[20:21], 0x180
	v_lshl_add_u64 v[86:87], v[4:5], 0, s[20:21]
	v_mfma_f32_16x16x32_bf16 v[120:123], v[156:159], v[148:151], v[120:123]
	v_lshl_add_u64 v[172:173], v[6:7], 0, s[20:21]
	s_mov_b64 s[20:21], 0x2180
	s_mov_b64 s[38:39], 0
	v_mfma_f32_16x16x32_bf16 v[96:99], v[156:159], v[152:155], v[96:99]
	v_mfma_f32_16x16x32_bf16 v[128:131], v[160:163], v[108:111], v[128:131]
	v_mfma_f32_16x16x32_bf16 v[132:135], v[160:163], v[148:151], v[132:135]
	v_mfma_f32_16x16x32_bf16 v[100:103], v[160:163], v[152:155], v[100:103]
	v_mfma_f32_16x16x32_bf16 v[140:143], v[164:167], v[108:111], v[140:143]
	v_mfma_f32_16x16x32_bf16 v[144:147], v[164:167], v[148:151], v[144:147]
	v_mfma_f32_16x16x32_bf16 v[104:107], v[164:167], v[152:155], v[104:107]
	v_mfma_f32_16x16x32_bf16 v[14:17], v[168:171], v[108:111], v[14:17]
	v_mfma_f32_16x16x32_bf16 v[18:21], v[168:171], v[148:151], v[18:21]
	v_mfma_f32_16x16x32_bf16 v[0:3], v[168:171], v[152:155], v[0:3]
	ds_read_b128 v[22:25], v9
	ds_read_b128 v[108:111], v9 offset:1024
	ds_read_b128 v[148:151], v9 offset:2048
	ds_read_b128 v[152:155], v9 offset:3072
	ds_read_b128 v[156:159], v8 offset:16384
	ds_read_b128 v[160:163], v8 offset:17408
	ds_read_b128 v[164:167], v8 offset:18432
	ds_read_b128 v[168:171], v8 offset:19456
	s_waitcnt lgkmcnt(3)
; template <int N> DI void wait_vm() { asm volatile("s_waitcnt vmcnt(%0)" ::"n"(N) : "memory"); }
; template <int BM, class Epi>
; DI void gemm_dma(const u16* __restrict__ X, long ldx, const u16* __restrict__ W, long ldw, int K, char* smem,
;                  int m0, int n0, const Epi& epi) {
;     ...
;   do {
;     if (kt + D - 2 < nk) wait_vm<PW * (D - 2)>(); else wait_vm<0>();
;     __syncthreads();
;     if (kt + D - 1 < nk) GD_ISSUE(nxt)
;     nxt = (nxt + 1 == D) ? 0 : nxt + 1;
;     const char* base = smem + cur * STG;
;     cur = (cur + 1 == D) ? 0 : cur + 1;
;     bf16x8 xf[MT];
; #pragma unroll
;     for (int i = 0; i < MT; ++i) xf[i] = *(const bf16x8*)(base + (xrow0 + i * 16) * 64 + rd);
; #pragma unroll
;     for (int nh = 0; nh < NT / 4; ++nh) {
;       bf16x8 wf[4];
; #pragma unroll
;       for (int i = 0; i < 4; ++i) wf[i] = *(const bf16x8*)(base + BM * 64 + (wrow0 + (nh * 4 + i) * 16) * 64 + rd);
; #pragma unroll
;       for (int i = 0; i < 4; ++i)
; #pragma unroll
;         for (int mt = 0; mt < MT; ++mt)
;           acc[nh * 4 + i][mt] = __builtin_amdgcn_mfma_f32_16x16x32_bf16(wf[i], xf[mt], acc[nh * 4 + i][mt], 0, 0, 0);
;     }
;   } while (++kt < nk);
	v_mfma_f32_16x16x32_bf16 v[42:45], v[156:159], v[22:25], v[42:45]
	v_mfma_f32_16x16x32_bf16 v[46:49], v[156:159], v[108:111], v[46:49]
	v_mfma_f32_16x16x32_bf16 v[50:53], v[156:159], v[148:151], v[50:53]
	v_mfma_f32_16x16x32_bf16 v[26:29], v[156:159], v[152:155], v[26:29]
	s_waitcnt lgkmcnt(2)
	v_mfma_f32_16x16x32_bf16 v[54:57], v[160:163], v[22:25], v[54:57]
	v_mfma_f32_16x16x32_bf16 v[58:61], v[160:163], v[108:111], v[58:61]
	v_mfma_f32_16x16x32_bf16 v[62:65], v[160:163], v[148:151], v[62:65]
	v_mfma_f32_16x16x32_bf16 v[30:33], v[160:163], v[152:155], v[30:33]
	s_waitcnt lgkmcnt(1)
	v_mfma_f32_16x16x32_bf16 v[66:69], v[164:167], v[22:25], v[66:69]
	v_mfma_f32_16x16x32_bf16 v[70:73], v[164:167], v[108:111], v[70:73]
	v_mfma_f32_16x16x32_bf16 v[74:77], v[164:167], v[148:151], v[74:77]
	v_mfma_f32_16x16x32_bf16 v[34:37], v[164:167], v[152:155], v[34:37]
	s_waitcnt lgkmcnt(0)
	v_mfma_f32_16x16x32_bf16 v[78:81], v[168:171], v[22:25], v[78:81]
	v_mfma_f32_16x16x32_bf16 v[82:85], v[168:171], v[108:111], v[82:85]
	v_mfma_f32_16x16x32_bf16 v[92:95], v[168:171], v[148:151], v[92:95]
	v_mfma_f32_16x16x32_bf16 v[38:41], v[168:171], v[152:155], v[38:41]
	ds_read_b128 v[156:159], v8 offset:20480
	ds_read_b128 v[160:163], v8 offset:21504
	ds_read_b128 v[164:167], v8 offset:22528
	ds_read_b128 v[168:171], v8 offset:23552
	s_waitcnt vmcnt(6)
	s_waitcnt lgkmcnt(0)
	s_barrier
	s_mov_b32 m0, s14
	s_nop 0
	global_load_lds_dwordx4 v[86:87], off
	v_mfma_f32_16x16x32_bf16 v[112:115], v[156:159], v[22:25], v[112:115]
	v_mfma_f32_16x16x32_bf16 v[124:127], v[160:163], v[22:25], v[124:127]
	v_mfma_f32_16x16x32_bf16 v[136:139], v[164:167], v[22:25], v[136:139]
	v_mfma_f32_16x16x32_bf16 v[10:13], v[168:171], v[22:25], v[10:13]
	v_lshl_add_u64 v[22:23], v[4:5], 0, s[20:21]
	s_mov_b32 m0, s15
	s_nop 0
	global_load_lds_dwordx4 v[22:23], off
	s_mov_b64 s[14:15], 0x4180
	v_lshl_add_u64 v[22:23], v[4:5], 0, s[14:15]
	s_mov_b32 m0, s16
	s_nop 0
	global_load_lds_dwordx4 v[22:23], off
	s_mov_b64 s[14:15], 0x6180
	v_lshl_add_u64 v[22:23], v[4:5], 0, s[14:15]
	s_mov_b32 m0, s17
	s_nop 0
	global_load_lds_dwordx4 v[22:23], off
	v_lshl_add_u64 v[22:23], v[6:7], 0, s[20:21]
	s_mov_b32 m0, s13
	s_nop 0
	global_load_lds_dwordx4 v[172:173], off
	s_mov_b32 m0, s18
	s_nop 0
	global_load_lds_dwordx4 v[22:23], off
	v_mfma_f32_16x16x32_bf16 v[116:119], v[156:159], v[108:111], v[116:119]
	s_mov_b64 s[14:15], 0x1c0
	v_lshl_add_u64 v[86:87], v[4:5], 0, s[14:15]
	v_lshl_add_u64 v[172:173], v[6:7], 0, s[14:15]
	v_mfma_f32_16x16x32_bf16 v[120:123], v[156:159], v[148:151], v[120:123]
	s_mov_b64 s[14:15], 0x21c0
	s_mov_b64 s[16:17], 0x41c0
	v_mfma_f32_16x16x32_bf16 v[96:99], v[156:159], v[152:155], v[96:99]
	v_mfma_f32_16x16x32_bf16 v[128:131], v[160:163], v[108:111], v[128:131]
	v_mfma_f32_16x16x32_bf16 v[132:135], v[160:163], v[148:151], v[132:135]
	v_mfma_f32_16x16x32_bf16 v[100:103], v[160:163], v[152:155], v[100:103]
	v_mfma_f32_16x16x32_bf16 v[140:143], v[164:167], v[108:111], v[140:143]
	v_mfma_f32_16x16x32_bf16 v[144:147], v[164:167], v[148:151], v[144:147]
	v_mfma_f32_16x16x32_bf16 v[104:107], v[164:167], v[152:155], v[104:107]
	v_mfma_f32_16x16x32_bf16 v[14:17], v[168:171], v[108:111], v[14:17]
	v_mfma_f32_16x16x32_bf16 v[18:21], v[168:171], v[148:151], v[18:21]
	v_mfma_f32_16x16x32_bf16 v[0:3], v[168:171], v[152:155], v[0:3]
	ds_read_b128 v[22:25], v9 offset:24576
	ds_read_b128 v[108:111], v9 offset:25600
	ds_read_b128 v[148:151], v9 offset:26624
	ds_read_b128 v[152:155], v9 offset:27648
	ds_read_b128 v[156:159], v8 offset:40960
	ds_read_b128 v[160:163], v8 offset:41984
	ds_read_b128 v[164:167], v8 offset:43008
	ds_read_b128 v[168:171], v8 offset:44032
	s_waitcnt lgkmcnt(3)
	v_mfma_f32_16x16x32_bf16 v[42:45], v[156:159], v[22:25], v[42:45]
	v_mfma_f32_16x16x32_bf16 v[46:49], v[156:159], v[108:111], v[46:49]
	v_mfma_f32_16x16x32_bf16 v[50:53], v[156:159], v[148:151], v[50:53]
	v_mfma_f32_16x16x32_bf16 v[26:29], v[156:159], v[152:155], v[26:29]
	s_waitcnt lgkmcnt(2)
	v_mfma_f32_16x16x32_bf16 v[54:57], v[160:163], v[22:25], v[54:57]
	v_mfma_f32_16x16x32_bf16 v[58:61], v[160:163], v[108:111], v[58:61]
	v_mfma_f32_16x16x32_bf16 v[62:65], v[160:163], v[148:151], v[62:65]
	v_mfma_f32_16x16x32_bf16 v[30:33], v[160:163], v[152:155], v[30:33]
	s_waitcnt lgkmcnt(1)
	v_mfma_f32_16x16x32_bf16 v[66:69], v[164:167], v[22:25], v[66:69]
	v_mfma_f32_16x16x32_bf16 v[70:73], v[164:167], v[108:111], v[70:73]
	v_mfma_f32_16x16x32_bf16 v[74:77], v[164:167], v[148:151], v[74:77]
	v_mfma_f32_16x16x32_bf16 v[34:37], v[164:167], v[152:155], v[34:37]
	s_waitcnt lgkmcnt(0)
	v_mfma_f32_16x16x32_bf16 v[78:81], v[168:171], v[22:25], v[78:81]
	v_mfma_f32_16x16x32_bf16 v[82:85], v[168:171], v[108:111], v[82:85]
	v_mfma_f32_16x16x32_bf16 v[92:95], v[168:171], v[148:151], v[92:95]
	v_mfma_f32_16x16x32_bf16 v[38:41], v[168:171], v[152:155], v[38:41]
	ds_read_b128 v[156:159], v8 offset:45056
	ds_read_b128 v[160:163], v8 offset:46080
	ds_read_b128 v[164:167], v8 offset:47104
	ds_read_b128 v[168:171], v8 offset:48128
	s_waitcnt vmcnt(6)
	s_waitcnt lgkmcnt(0)
	s_barrier
; template <int N> DI void wait_vm() { asm volatile("s_waitcnt vmcnt(%0)" ::"n"(N) : "memory"); }
; template <int BM, class Epi>
; DI void gemm_dma(const u16* __restrict__ X, long ldx, const u16* __restrict__ W, long ldw, int K, char* smem,
;                  int m0, int n0, const Epi& epi) {
;     ...
;   do {
;     if (kt + D - 2 < nk) wait_vm<PW * (D - 2)>(); else wait_vm<0>();
;     __syncthreads();
;     if (kt + D - 1 < nk) GD_ISSUE(nxt)
;     nxt = (nxt + 1 == D) ? 0 : nxt + 1;
;     const char* base = smem + cur * STG;
;     cur = (cur + 1 == D) ? 0 : cur + 1;
;     bf16x8 xf[MT];
; #pragma unroll
;     for (int i = 0; i < MT; ++i) xf[i] = *(const bf16x8*)(base + (xrow0 + i * 16) * 64 + rd);
; #pragma unroll
;     for (int nh = 0; nh < NT / 4; ++nh) {
;       bf16x8 wf[4];
; #pragma unroll
;       for (int i = 0; i < 4; ++i) wf[i] = *(const bf16x8*)(base + BM * 64 + (wrow0 + (nh * 4 + i) * 16) * 64 + rd);
; #pragma unroll
;       for (int i = 0; i < 4; ++i)
; #pragma unroll
;         for (int mt = 0; mt < MT; ++mt)
;           acc[nh * 4 + i][mt] = __builtin_amdgcn_mfma_f32_16x16x32_bf16(wf[i], xf[mt], acc[nh * 4 + i][mt], 0, 0, 0);
;     }
;   } while (++kt < nk);
	s_mov_b32 m0, s7
	s_nop 0
	global_load_lds_dwordx4 v[86:87], off
	v_mfma_f32_16x16x32_bf16 v[112:115], v[156:159], v[22:25], v[112:115]
	v_mfma_f32_16x16x32_bf16 v[124:127], v[160:163], v[22:25], v[124:127]
	v_mfma_f32_16x16x32_bf16 v[136:139], v[164:167], v[22:25], v[136:139]
	v_mfma_f32_16x16x32_bf16 v[10:13], v[168:171], v[22:25], v[10:13]
	v_lshl_add_u64 v[22:23], v[4:5], 0, s[14:15]
	s_mov_b32 m0, s8
	s_nop 0
	global_load_lds_dwordx4 v[22:23], off
	v_lshl_add_u64 v[22:23], v[4:5], 0, s[16:17]
	s_mov_b32 m0, s9
	s_nop 0
	global_load_lds_dwordx4 v[22:23], off
	s_mov_b64 s[8:9], 0x61c0
	v_lshl_add_u64 v[4:5], v[4:5], 0, s[8:9]
	s_mov_b32 m0, s10
	s_nop 0
	global_load_lds_dwordx4 v[4:5], off
	v_lshl_add_u64 v[4:5], v[6:7], 0, s[14:15]
	s_mov_b32 m0, s11
	s_nop 0
	global_load_lds_dwordx4 v[172:173], off
	v_mfma_f32_16x16x32_bf16 v[116:119], v[156:159], v[108:111], v[116:119]
	s_mov_b32 m0, s12
	s_nop 0
	global_load_lds_dwordx4 v[4:5], off
	v_mfma_f32_16x16x32_bf16 v[120:123], v[156:159], v[148:151], v[120:123]
	v_mfma_f32_16x16x32_bf16 v[96:99], v[156:159], v[152:155], v[96:99]
	v_mfma_f32_16x16x32_bf16 v[128:131], v[160:163], v[108:111], v[128:131]
	v_mfma_f32_16x16x32_bf16 v[132:135], v[160:163], v[148:151], v[132:135]
	v_mfma_f32_16x16x32_bf16 v[100:103], v[160:163], v[152:155], v[100:103]
	v_mfma_f32_16x16x32_bf16 v[140:143], v[164:167], v[108:111], v[140:143]
	v_mfma_f32_16x16x32_bf16 v[144:147], v[164:167], v[148:151], v[144:147]
	v_mfma_f32_16x16x32_bf16 v[104:107], v[164:167], v[152:155], v[104:107]
	v_mfma_f32_16x16x32_bf16 v[14:17], v[168:171], v[108:111], v[14:17]
	v_mfma_f32_16x16x32_bf16 v[18:21], v[168:171], v[148:151], v[18:21]
	v_mfma_f32_16x16x32_bf16 v[0:3], v[168:171], v[152:155], v[0:3]
	ds_read_b128 v[4:7], v9 offset:49152
	ds_read_b128 v[22:25], v9 offset:50176
	ds_read_b128 v[108:111], v9 offset:51200
	ds_read_b128 v[148:151], v9 offset:52224
	ds_read_b128 v[152:155], v91
	ds_read_b128 v[156:159], v174
	ds_read_b128 v[160:163], v175
	ds_read_b128 v[164:167], v176
	s_waitcnt lgkmcnt(3)
	v_mfma_f32_16x16x32_bf16 v[42:45], v[152:155], v[4:7], v[42:45]
	v_mfma_f32_16x16x32_bf16 v[46:49], v[152:155], v[22:25], v[46:49]
	v_mfma_f32_16x16x32_bf16 v[50:53], v[152:155], v[108:111], v[50:53]
	v_mfma_f32_16x16x32_bf16 v[26:29], v[152:155], v[148:151], v[26:29]
	s_waitcnt lgkmcnt(2)
	v_mfma_f32_16x16x32_bf16 v[54:57], v[156:159], v[4:7], v[54:57]
	v_mfma_f32_16x16x32_bf16 v[58:61], v[156:159], v[22:25], v[58:61]
	v_mfma_f32_16x16x32_bf16 v[62:65], v[156:159], v[108:111], v[62:65]
	v_mfma_f32_16x16x32_bf16 v[30:33], v[156:159], v[148:151], v[30:33]
	s_waitcnt lgkmcnt(1)
	v_mfma_f32_16x16x32_bf16 v[66:69], v[160:163], v[4:7], v[66:69]
	v_mfma_f32_16x16x32_bf16 v[70:73], v[160:163], v[22:25], v[70:73]
	v_mfma_f32_16x16x32_bf16 v[74:77], v[160:163], v[108:111], v[74:77]
	v_mfma_f32_16x16x32_bf16 v[34:37], v[160:163], v[148:151], v[34:37]
	s_waitcnt lgkmcnt(0)
	v_mfma_f32_16x16x32_bf16 v[78:81], v[164:167], v[4:7], v[78:81]
	v_mfma_f32_16x16x32_bf16 v[82:85], v[164:167], v[22:25], v[82:85]
	v_mfma_f32_16x16x32_bf16 v[92:95], v[164:167], v[108:111], v[92:95]
	v_mfma_f32_16x16x32_bf16 v[38:41], v[164:167], v[148:151], v[38:41]
	ds_read_b128 v[152:155], v177
	ds_read_b128 v[156:159], v178
	ds_read_b128 v[160:163], v179
	ds_read_b128 v[164:167], v180
	s_waitcnt vmcnt(6)
	s_waitcnt lgkmcnt(0)
	v_mfma_f32_16x16x32_bf16 v[112:115], v[152:155], v[4:7], v[112:115]
	s_barrier
	v_mfma_f32_16x16x32_bf16 v[116:119], v[152:155], v[22:25], v[116:119]
	v_mfma_f32_16x16x32_bf16 v[120:123], v[152:155], v[108:111], v[120:123]
	v_mfma_f32_16x16x32_bf16 v[96:99], v[152:155], v[148:151], v[96:99]
	v_mfma_f32_16x16x32_bf16 v[124:127], v[156:159], v[4:7], v[124:127]
	v_mfma_f32_16x16x32_bf16 v[128:131], v[156:159], v[22:25], v[128:131]
	v_mfma_f32_16x16x32_bf16 v[132:135], v[156:159], v[108:111], v[132:135]
	v_mfma_f32_16x16x32_bf16 v[100:103], v[156:159], v[148:151], v[100:103]
	v_mfma_f32_16x16x32_bf16 v[136:139], v[160:163], v[4:7], v[136:139]
	v_mfma_f32_16x16x32_bf16 v[140:143], v[160:163], v[22:25], v[140:143]
	v_mfma_f32_16x16x32_bf16 v[144:147], v[160:163], v[108:111], v[144:147]
	v_mfma_f32_16x16x32_bf16 v[104:107], v[160:163], v[148:151], v[104:107]
	v_mfma_f32_16x16x32_bf16 v[4:7], v[164:167], v[4:7], v[10:13]
	v_mfma_f32_16x16x32_bf16 v[10:13], v[164:167], v[22:25], v[14:17]
	v_mfma_f32_16x16x32_bf16 v[14:17], v[164:167], v[108:111], v[18:21]
	v_mfma_f32_16x16x32_bf16 v[0:3], v[164:167], v[148:151], v[0:3]
	s_nop 1
	ds_read_b128 v[18:21], v8 offset:23552
	ds_read_b128 v[22:25], v8 offset:22528
	ds_read_b128 v[108:111], v8 offset:21504
	ds_read_b128 v[148:151], v8 offset:20480
	ds_read_b128 v[152:155], v8 offset:19456
	ds_read_b128 v[156:159], v8 offset:18432
	ds_read_b128 v[160:163], v8 offset:17408
	ds_read_b128 v[164:167], v8 offset:16384
	ds_read_b128 v[168:171], v9 offset:3072
	ds_read_b128 v[172:175], v9 offset:2048
	ds_read_b128 v[176:179], v9 offset:1024
	ds_read_b128 v[186:189], v9
	s_waitcnt vmcnt(0)
	s_waitcnt lgkmcnt(0)
	v_mfma_f32_16x16x32_bf16 v[42:45], v[164:167], v[186:189], v[42:45]
	s_barrier
; DI void st_bf4(u16* p, float a, float b, float c, float d) { *(uint2*)p = make_uint2(pk2(a, b), pk2(c, d)); }
; template <int BM, class Epi>
; DI void gemm_dma(const u16* __restrict__ X, long ldx, const u16* __restrict__ W, long ldw, int K, char* smem,
;                  int m0, int n0, const Epi& epi) {
;     ...
;     for (int nh = 0; nh < NT / 4; ++nh) {
;       bf16x8 wf[4];
; #pragma unroll
;       for (int i = 0; i < 4; ++i) wf[i] = *(const bf16x8*)(base + BM * 64 + (wrow0 + (nh * 4 + i) * 16) * 64 + rd);
; #pragma unroll
;       for (int i = 0; i < 4; ++i)
; #pragma unroll
;         for (int mt = 0; mt < MT; ++mt)
;           acc[nh * 4 + i][mt] = __builtin_amdgcn_mfma_f32_16x16x32_bf16(wf[i], xf[mt], acc[nh * 4 + i][mt], 0, 0, 0);
;     }
;   } while (++kt < nk);
;   template <int NT, int MT> DI void run(f32x4 (&acc)[NT][MT], int mb, int nb) const {
; #pragma unroll
;     for (int nt = 0; nt < NT; ++nt)
; #pragma unroll
;       for (int mt = 0; mt < MT; ++mt) {
;         f32x4 v = acc[nt][mt];
;         st_bf4(C + (size_t)(mb + mt * 16) * ldc + nb + nt * 16, v[0], v[1], v[2], v[3]);
;       }
	v_mfma_f32_16x16x32_bf16 v[46:49], v[164:167], v[176:179], v[46:49]
	v_mfma_f32_16x16x32_bf16 v[50:53], v[164:167], v[172:175], v[50:53]
	v_mfma_f32_16x16x32_bf16 v[26:29], v[164:167], v[168:171], v[26:29]
	v_mfma_f32_16x16x32_bf16 v[54:57], v[160:163], v[186:189], v[54:57]
	v_mfma_f32_16x16x32_bf16 v[58:61], v[160:163], v[176:179], v[58:61]
	v_mfma_f32_16x16x32_bf16 v[62:65], v[160:163], v[172:175], v[62:65]
	v_mfma_f32_16x16x32_bf16 v[30:33], v[160:163], v[168:171], v[30:33]
	v_mfma_f32_16x16x32_bf16 v[66:69], v[156:159], v[186:189], v[66:69]
	v_mfma_f32_16x16x32_bf16 v[70:73], v[156:159], v[176:179], v[70:73]
	v_mfma_f32_16x16x32_bf16 v[74:77], v[156:159], v[172:175], v[74:77]
	v_mfma_f32_16x16x32_bf16 v[34:37], v[156:159], v[168:171], v[34:37]
	v_mfma_f32_16x16x32_bf16 v[156:159], v[152:155], v[186:189], v[78:81]
	v_mfma_f32_16x16x32_bf16 v[84:87], v[152:155], v[176:179], v[82:85]
	v_mfma_f32_16x16x32_bf16 v[92:95], v[152:155], v[172:175], v[92:95]
	v_mfma_f32_16x16x32_bf16 v[152:155], v[152:155], v[168:171], v[38:41]
	v_mfma_f32_16x16x32_bf16 v[112:115], v[148:151], v[186:189], v[112:115]
	v_mfma_f32_16x16x32_bf16 v[116:119], v[148:151], v[176:179], v[116:119]
	v_mfma_f32_16x16x32_bf16 v[120:123], v[148:151], v[172:175], v[120:123]
	v_mfma_f32_16x16x32_bf16 v[96:99], v[148:151], v[168:171], v[96:99]
	v_mfma_f32_16x16x32_bf16 v[124:127], v[108:111], v[186:189], v[124:127]
	v_mfma_f32_16x16x32_bf16 v[128:131], v[108:111], v[176:179], v[128:131]
	v_mfma_f32_16x16x32_bf16 v[132:135], v[108:111], v[172:175], v[132:135]
	v_mfma_f32_16x16x32_bf16 v[100:103], v[108:111], v[168:171], v[100:103]
	v_mfma_f32_16x16x32_bf16 v[108:111], v[22:25], v[186:189], v[136:139]
	v_mfma_f32_16x16x32_bf16 v[136:139], v[22:25], v[176:179], v[140:143]
	v_mfma_f32_16x16x32_bf16 v[140:143], v[22:25], v[172:175], v[144:147]
	v_mfma_f32_16x16x32_bf16 v[104:107], v[22:25], v[168:171], v[104:107]
	v_mfma_f32_16x16x32_bf16 v[4:7], v[18:21], v[186:189], v[4:7]
	v_mfma_f32_16x16x32_bf16 v[144:147], v[18:21], v[176:179], v[10:13]
	v_mfma_f32_16x16x32_bf16 v[148:151], v[18:21], v[172:175], v[14:17]
	v_mfma_f32_16x16x32_bf16 v[0:3], v[18:21], v[168:171], v[0:3]
	s_nop 0
	ds_read_b128 v[10:13], v9 offset:24576
	ds_read_b128 v[160:163], v9 offset:25600
	ds_read_b128 v[164:167], v9 offset:26624
	ds_read_b128 v[168:171], v9 offset:27648
	ds_read_b128 v[14:17], v8 offset:40960
	ds_read_b128 v[18:21], v8 offset:41984
	ds_read_b128 v[22:25], v8 offset:43008
	ds_read_b128 v[172:175], v8 offset:44032
	s_waitcnt lgkmcnt(3)
	v_mfma_f32_16x16x32_bf16 v[176:179], v[14:17], v[10:13], v[42:45]
	v_mfma_f32_16x16x32_bf16 v[186:189], v[14:17], v[160:163], v[46:49]
	v_mfma_f32_16x16x32_bf16 v[190:193], v[14:17], v[164:167], v[50:53]
	v_mfma_f32_16x16x32_bf16 v[194:197], v[14:17], v[168:171], v[26:29]
	s_waitcnt lgkmcnt(2)
	v_mfma_f32_16x16x32_bf16 v[224:227], v[18:21], v[10:13], v[54:57]
	v_mfma_f32_16x16x32_bf16 v[228:231], v[18:21], v[160:163], v[58:61]
	v_mfma_f32_16x16x32_bf16 v[232:235], v[18:21], v[164:167], v[62:65]
	v_mfma_f32_16x16x32_bf16 v[236:239], v[18:21], v[168:171], v[30:33]
	s_waitcnt lgkmcnt(1)
	v_mfma_f32_16x16x32_bf16 v[240:243], v[22:25], v[10:13], v[66:69]
	v_mfma_f32_16x16x32_bf16 v[64:67], v[22:25], v[168:171], v[34:37]
	s_waitcnt lgkmcnt(0)
	v_mfma_f32_16x16x32_bf16 v[40:43], v[172:175], v[164:167], v[92:95]
	v_mfma_f32_16x16x32_bf16 v[32:35], v[172:175], v[168:171], v[152:155]
	ds_read_b128 v[14:17], v8 offset:45056
	ds_read_b128 v[18:21], v8 offset:46080
	ds_read_b128 v[92:95], v8 offset:47104
	ds_read_b128 v[152:155], v8 offset:48128
	s_nop 0
	v_cvt_pk_bf16_f32 v64, v64, v65
	v_cvt_pk_bf16_f32 v65, v66, v67
	v_mfma_f32_16x16x32_bf16 v[80:83], v[22:25], v[160:163], v[70:73]
	v_cvt_pk_bf16_f32 v32, v32, v33
	v_cvt_pk_bf16_f32 v33, v34, v35
	v_cvt_pk_bf16_f32 v40, v40, v41
	v_mfma_f32_16x16x32_bf16 v[72:75], v[22:25], v[164:167], v[74:77]
	v_cvt_pk_bf16_f32 v41, v42, v43
	s_nop 2
	v_cvt_pk_bf16_f32 v80, v80, v81
	v_cvt_pk_bf16_f32 v81, v82, v83
	v_mfma_f32_16x16x32_bf16 v[48:51], v[172:175], v[160:163], v[84:87]
	s_waitcnt lgkmcnt(3)
	v_mfma_f32_16x16x32_bf16 v[112:115], v[14:17], v[10:13], v[112:115]
	v_cvt_pk_bf16_f32 v72, v72, v73
	v_cvt_pk_bf16_f32 v73, v74, v75
	s_nop 3
	v_cvt_pk_bf16_f32 v48, v48, v49
	v_mfma_f32_16x16x32_bf16 v[84:87], v[14:17], v[160:163], v[116:119]
	v_cvt_pk_bf16_f32 v49, v50, v51
	v_mfma_f32_16x16x32_bf16 v[76:79], v[14:17], v[164:167], v[120:123]
	v_mfma_f32_16x16x32_bf16 v[68:71], v[14:17], v[168:171], v[96:99]
	s_waitcnt lgkmcnt(2)
	v_mfma_f32_16x16x32_bf16 v[60:63], v[18:21], v[10:13], v[124:127]
	s_nop 0
	v_cvt_pk_bf16_f32 v96, v190, v191
	v_cvt_pk_bf16_f32 v97, v192, v193
	v_mfma_f32_16x16x32_bf16 v[52:55], v[18:21], v[160:163], v[128:131]
	v_mfma_f32_16x16x32_bf16 v[44:47], v[18:21], v[164:167], v[132:135]
	v_mfma_f32_16x16x32_bf16 v[36:39], v[18:21], v[168:171], v[100:103]
	s_waitcnt lgkmcnt(1)
; DI void st_bf4(u16* p, float a, float b, float c, float d) { *(uint2*)p = make_uint2(pk2(a, b), pk2(c, d)); }
; template <int BM, class Epi>
; DI void gemm_dma(const u16* __restrict__ X, long ldx, const u16* __restrict__ W, long ldw, int K, char* smem,
;                  int m0, int n0, const Epi& epi) {
;     ...
;     for (int nh = 0; nh < NT / 4; ++nh) {
;       bf16x8 wf[4];
; #pragma unroll
;       for (int i = 0; i < 4; ++i) wf[i] = *(const bf16x8*)(base + BM * 64 + (wrow0 + (nh * 4 + i) * 16) * 64 + rd);
; #pragma unroll
;       for (int i = 0; i < 4; ++i)
; #pragma unroll
;         for (int mt = 0; mt < MT; ++mt)
;           acc[nh * 4 + i][mt] = __builtin_amdgcn_mfma_f32_16x16x32_bf16(wf[i], xf[mt], acc[nh * 4 + i][mt], 0, 0, 0);
;     }
;   } while (++kt < nk);
;     ...
;   epi.run(acc, m0 + xrow0 + lr, n0 + wrow0 + 4 * g);
;   template <int NT, int MT> DI void run(f32x4 (&acc)[NT][MT], int mb, int nb) const {
; #pragma unroll
;     for (int nt = 0; nt < NT; ++nt)
; #pragma unroll
;       for (int mt = 0; mt < MT; ++mt) {
;         f32x4 v = acc[nt][mt];
;         st_bf4(C + (size_t)(mb + mt * 16) * ldc + nb + nt * 16, v[0], v[1], v[2], v[3]);
;       }
	v_mfma_f32_16x16x32_bf16 v[28:31], v[92:95], v[10:13], v[108:111]
	v_mfma_f32_16x16x32_bf16 v[24:27], v[92:95], v[160:163], v[136:139]
	v_mfma_f32_16x16x32_bf16 v[20:23], v[92:95], v[164:167], v[140:143]
	s_nop 5
	v_cvt_pk_bf16_f32 v28, v28, v29
	v_cvt_pk_bf16_f32 v29, v30, v31
	v_cvt_pk_bf16_f32 v24, v24, v25
	v_mfma_f32_16x16x32_bf16 v[16:19], v[92:95], v[168:171], v[104:107]
	v_or_b32_e32 v92, v90, v89
	v_ashrrev_i32_e32 v93, 31, v92
	v_lshlrev_b64 v[90:91], 11, v[92:93]
	v_lshl_add_u64 v[90:91], s[92:93], 0, v[90:91]
	v_bfe_u32 v34, v185, 4, 1
	v_mad_u32_u24 v182, v34, 24, v182
	v_lshl_add_u64 v[88:89], v[90:91], 0, v[182:183]
	v_cvt_pk_bf16_f32 v90, v176, v177
	v_cvt_pk_bf16_f32 v91, v178, v179
	v_mov_b32_e32 v98, v90
	v_mov_b32_e32 v99, v91
	v_or_b32_e32 v90, 16, v92
	v_ashrrev_i32_e32 v91, 31, v90
	v_lshlrev_b64 v[90:91], 11, v[90:91]
	v_lshl_add_u64 v[90:91], s[92:93], 0, v[90:91]
	v_lshl_add_u64 v[90:91], v[90:91], 0, v[182:183]
	v_cvt_pk_bf16_f32 v94, v186, v187
	v_cvt_pk_bf16_f32 v95, v188, v189
	v_mov_b32_e32 v102, v94
	v_mov_b32_e32 v103, v95
	v_or_b32_e32 v94, 32, v92
	v_or_b32_e32 v92, 48, v92
	v_ashrrev_i32_e32 v93, 31, v92
	v_lshlrev_b64 v[92:93], 11, v[92:93]
	v_ashrrev_i32_e32 v95, 31, v94
	v_lshl_add_u64 v[92:93], s[92:93], 0, v[92:93]
	v_lshlrev_b64 v[94:95], 11, v[94:95]
	v_lshl_add_u64 v[92:93], v[92:93], 0, v[182:183]
	v_lshl_add_u64 v[94:95], s[92:93], 0, v[94:95]
	v_mov_b32_e32 v108, v32
	v_mov_b32_e32 v109, v33
	v_cvt_pk_bf16_f32 v32, v112, v113
	v_cvt_pk_bf16_f32 v33, v114, v115
	v_lshl_add_u64 v[94:95], v[94:95], 0, v[182:183]
	v_mov_b32_e32 v116, v32
	v_mov_b32_e32 v117, v33
	v_cvt_pk_bf16_f32 v32, v84, v85
	v_cvt_pk_bf16_f32 v33, v86, v87
	v_mov_b32_e32 v120, v96
	v_mov_b32_e32 v121, v97
	v_cvt_pk_bf16_f32 v96, v194, v195
	v_cvt_pk_bf16_f32 v97, v196, v197
	v_mov_b32_e32 v124, v32
	v_mov_b32_e32 v125, v33
	v_cvt_pk_bf16_f32 v32, v76, v77
	v_cvt_pk_bf16_f32 v33, v78, v79
	v_mfma_f32_16x16x32_bf16 v[56:59], v[172:175], v[10:13], v[156:159]
	v_mov_b32_e32 v110, v96
	v_mov_b32_e32 v111, v97
	v_cvt_pk_bf16_f32 v96, v224, v225
	v_cvt_pk_bf16_f32 v97, v226, v227
	s_waitcnt lgkmcnt(0)
	v_mfma_f32_16x16x32_bf16 v[12:15], v[152:155], v[10:13], v[4:7]
	v_mov_b32_e32 v82, v32
	v_mov_b32_e32 v83, v33
	v_cvt_pk_bf16_f32 v32, v68, v69
	v_cvt_pk_bf16_f32 v33, v70, v71
	v_mfma_f32_16x16x32_bf16 v[8:11], v[152:155], v[160:163], v[144:147]
	v_mov_b32_e32 v100, v96
	v_mov_b32_e32 v101, v97
	s_nop 1
	v_permlane16_swap_b32_e32 v98, v100
	v_permlane16_swap_b32_e32 v99, v101
	global_store_dwordx4 v[88:89], v[98:101], off
	v_cvt_pk_bf16_f32 v96, v228, v229
	v_cvt_pk_bf16_f32 v97, v230, v231
	v_mfma_f32_16x16x32_bf16 v[4:7], v[152:155], v[164:167], v[148:151]
	v_mov_b32_e32 v74, v32
	v_mov_b32_e32 v75, v33
	v_cvt_pk_bf16_f32 v32, v60, v61
	v_cvt_pk_bf16_f32 v33, v62, v63
	v_mfma_f32_16x16x32_bf16 v[0:3], v[152:155], v[168:171], v[0:3]
	v_mov_b32_e32 v104, v96
	v_mov_b32_e32 v105, v97
	s_nop 1
	v_permlane16_swap_b32_e32 v102, v104
	v_permlane16_swap_b32_e32 v103, v105
	global_store_dwordx4 v[90:91], v[102:105], off
	v_cvt_pk_bf16_f32 v96, v232, v233
	v_cvt_pk_bf16_f32 v97, v234, v235
	v_mov_b32_e32 v118, v32
	v_mov_b32_e32 v119, v33
	s_nop 1
	v_permlane16_swap_b32_e32 v116, v118
	v_permlane16_swap_b32_e32 v117, v119
	global_store_dwordx4 v[88:89], v[116:119], off offset:128
	v_cvt_pk_bf16_f32 v32, v52, v53
	v_cvt_pk_bf16_f32 v33, v54, v55
	v_mov_b32_e32 v122, v96
	v_mov_b32_e32 v123, v97
	s_nop 1
	v_permlane16_swap_b32_e32 v120, v122
	v_permlane16_swap_b32_e32 v121, v123
	global_store_dwordx4 v[94:95], v[120:123], off
	v_cvt_pk_bf16_f32 v96, v236, v237
	v_cvt_pk_bf16_f32 v97, v238, v239
	v_mov_b32_e32 v126, v32
	v_mov_b32_e32 v127, v33
	s_nop 1
	v_permlane16_swap_b32_e32 v124, v126
	v_permlane16_swap_b32_e32 v125, v127
	global_store_dwordx4 v[90:91], v[124:127], off offset:128
	v_cvt_pk_bf16_f32 v32, v44, v45
	v_cvt_pk_bf16_f32 v33, v46, v47
	v_mov_b32_e32 v112, v96
	v_mov_b32_e32 v113, v97
	s_nop 1
	v_permlane16_swap_b32_e32 v110, v112
	v_permlane16_swap_b32_e32 v111, v113
	global_store_dwordx4 v[92:93], v[110:113], off
	v_cvt_pk_bf16_f32 v96, v240, v241
	v_cvt_pk_bf16_f32 v97, v242, v243
	v_cvt_pk_bf16_f32 v56, v56, v57
	v_cvt_pk_bf16_f32 v57, v58, v59
	v_mov_b32_e32 v84, v32
	v_mov_b32_e32 v85, v33
	s_nop 1
	v_permlane16_swap_b32_e32 v82, v84
	v_permlane16_swap_b32_e32 v83, v85
	global_store_dwordx4 v[94:95], v[82:85], off offset:128
	v_cvt_pk_bf16_f32 v32, v36, v37
	v_cvt_pk_bf16_f32 v33, v38, v39
	v_cvt_pk_bf16_f32 v25, v26, v27
	v_cvt_pk_bf16_f32 v20, v20, v21
	v_cvt_pk_bf16_f32 v21, v22, v23
	v_cvt_pk_bf16_f32 v16, v16, v17
	v_cvt_pk_bf16_f32 v17, v18, v19
	v_cvt_pk_bf16_f32 v12, v12, v13
	v_cvt_pk_bf16_f32 v13, v14, v15
	v_cvt_pk_bf16_f32 v8, v8, v9
	v_cvt_pk_bf16_f32 v9, v10, v11
	v_cvt_pk_bf16_f32 v4, v4, v5
	v_cvt_pk_bf16_f32 v5, v6, v7
	v_cvt_pk_bf16_f32 v0, v0, v1
	v_cvt_pk_bf16_f32 v1, v2, v3
	v_mov_b32_e32 v34, v96
	v_mov_b32_e32 v35, v97
	v_mov_b32_e32 v42, v80
	v_mov_b32_e32 v43, v81
	v_mov_b32_e32 v50, v72
	v_mov_b32_e32 v51, v73
	v_mov_b32_e32 v106, v64
	v_mov_b32_e32 v107, v65
	s_nop 1
	v_permlane16_swap_b32_e32 v106, v108
	v_permlane16_swap_b32_e32 v107, v109
	global_store_dwordx4 v[92:93], v[106:109], off offset:64
	v_mov_b32_e32 v36, v56
	v_mov_b32_e32 v37, v57
	s_nop 1
	v_permlane16_swap_b32_e32 v34, v36
	v_permlane16_swap_b32_e32 v35, v37
	global_store_dwordx4 v[88:89], v[34:37], off offset:64
	v_mov_b32_e32 v44, v48
	v_mov_b32_e32 v45, v49
	s_nop 1
	v_permlane16_swap_b32_e32 v42, v44
	v_permlane16_swap_b32_e32 v43, v45
	global_store_dwordx4 v[90:91], v[42:45], off offset:64
	v_mov_b32_e32 v52, v40
	v_mov_b32_e32 v53, v41
	s_nop 1
	v_permlane16_swap_b32_e32 v50, v52
	v_permlane16_swap_b32_e32 v51, v53
	global_store_dwordx4 v[94:95], v[50:53], off offset:64
	v_mov_b32_e32 v76, v32
	v_mov_b32_e32 v77, v33
	s_nop 1
	v_permlane16_swap_b32_e32 v74, v76
	v_permlane16_swap_b32_e32 v75, v77
	global_store_dwordx4 v[92:93], v[74:77], off offset:128
	v_mov_b32_e32 v34, v28
	v_mov_b32_e32 v35, v29
	v_mov_b32_e32 v42, v24
	v_mov_b32_e32 v43, v25
	v_mov_b32_e32 v50, v20
	v_mov_b32_e32 v51, v21
	v_mov_b32_e32 v58, v16
	v_mov_b32_e32 v59, v17
	v_mov_b32_e32 v36, v12
	v_mov_b32_e32 v37, v13
	s_nop 1
	v_permlane16_swap_b32_e32 v34, v36
	v_permlane16_swap_b32_e32 v35, v37
	global_store_dwordx4 v[88:89], v[34:37], off offset:192
	v_mov_b32_e32 v44, v8
	v_mov_b32_e32 v45, v9
	s_nop 1
	v_permlane16_swap_b32_e32 v42, v44
	v_permlane16_swap_b32_e32 v43, v45
	global_store_dwordx4 v[90:91], v[42:45], off offset:192
	v_mov_b32_e32 v52, v4
	v_mov_b32_e32 v53, v5
	s_nop 1
	v_permlane16_swap_b32_e32 v50, v52
	v_permlane16_swap_b32_e32 v51, v53
	global_store_dwordx4 v[94:95], v[50:53], off offset:192
	v_mov_b32_e32 v60, v0
	v_mov_b32_e32 v61, v1
	s_nop 1
	v_permlane16_swap_b32_e32 v58, v60
	v_permlane16_swap_b32_e32 v59, v61
	global_store_dwordx4 v[92:93], v[58:61], off offset:192

; DI int get_bid() { int b = blockIdx.x; asm volatile("" : "+s"(b)); return b; }
; template <int N> DI void wait_vm() { asm volatile("s_waitcnt vmcnt(%0)" ::"n"(N) : "memory"); }
; template <int BM, class Epi>
; DI void gemm_dma(const u16* __restrict__ X, long ldx, const u16* __restrict__ W, long ldw, int K, char* smem,
;                  int m0, int n0, const Epi& epi) {
;     ...
;   const int wu = __builtin_amdgcn_readfirstlane(wave);
;   const unsigned sbase = (unsigned)__builtin_amdgcn_readfirstlane((int)(unsigned)(size_t)smem);
;   const int r16 = lane >> 2, chunk = (lane & 3) ^ ((4 - (r16 >> 2)) & 3);
;   const u16* xs = X + (long)(wu * XD * 16 + r16) * ldx + (chunk << 3);
;   const u16* ws = W + (long)(wu * 32 + r16) * ldw + (chunk << 3);
;   const long ldx16 = 16 * ldx, ldw16 = 16 * ldw;
;   const unsigned xdst = sbase + wu * XD * 1024, wdst = sbase + BM * 64 + wu * 2048;
;     ...
;   const int nk = K >> 5;
;   __syncthreads();
; #pragma unroll
;   for (int s = 0; s < D - 1; ++s) GD_ISSUE(s)
;   int cur = 0, nxt = D - 1, kt = 0;
;   do {
;     if (kt + D - 2 < nk) wait_vm<PW * (D - 2)>(); else wait_vm<0>();
;     __syncthreads();
;     if (kt + D - 1 < nk) GD_ISSUE(nxt)
; DI void phase_odd(const Params& p, int o, int sub, char* smem) {
;     ...
;     for (int t = get_bid(); t < 1584 + 256; t += gridDim.x) {
;       if (t < 1584) {
;         const int tm = t / 12, tn = t % 12;
;         const int t2 = t + gridDim.x, tm2 = t2 / 12, tn2 = t2 % 12;
;         const bool nx = t2 < 1584;
;         gemm_tile<4>(qn + (size_t)tm * 128 * 384, 384, W + WO_Q + (size_t)tn * 128 * 384, 384, 384, smem, tm * 128, tn * 128, eq, pre,
;                      nx ? qn + (size_t)tm2 * 128 * 384 : nullptr, W + WO_Q + (size_t)tn2 * 128 * 384);
;         pre = nx;
;       } else {
;         knope_tile(p, t - 1584, smem);
.LBB0_981:
	s_cmpk_gt_i32 s5, 0x62f
	s_mov_b64 s[38:39], -1
	s_cbranch_scc0 .LBB0_983
	s_add_i32 s4, s5, 0xfffff9d0
	s_bfe_u32 s98, s4, 0x30003
	s_and_b32 s99, s4, 7
	s_lshl_b32 s99, s99, 3
	s_andn2_b32 s4, s4, 63
	s_or_b32 s4, s4, s99
	s_or_b32 s4, s4, s98
	s_lshr_b32 s6, s4, 3
	s_and_b32 s4, s4, 7
	s_lshl_b32 s7, s6, 17
	s_add_u32 s8, s0, s7
	s_addc_u32 s9, s1, 0
	s_lshl_b32 s7, s4, 16
	v_mov_b32_e32 v9, v185
	s_add_u32 s10, s87, s7
	s_addc_u32 s11, s90, 0
	v_readfirstlane_b32 s7, v9
	v_lshrrev_b32_e32 v4, 4, v9
	s_ashr_i32 s12, s7, 6
	v_bfe_u32 v6, v9, 2, 4
	v_sub_u32_e32 v4, 0, v4
	s_andn2_b32 s7, s7, 63
	v_lshrrev_b32_e32 v1, 2, v9
	v_xor_b32_e32 v7, v9, v4
	v_or_b32_e32 v4, s7, v6
	v_and_b32_e32 v89, 15, v9
	v_bfe_u32 v88, v9, 4, 2
	v_sub_u32_e32 v1, 0, v1
	v_ashrrev_i32_e32 v5, 31, v4
	v_lshlrev_b32_e32 v0, 6, v89
	v_bitop3_b32 v1, v88, v1, 3 bitop3:0x78
	v_lshlrev_b64 v[4:5], 9, v[4:5]
	v_lshlrev_b32_e32 v7, 4, v7
	v_lshl_or_b32 v6, s12, 5, v6
	v_lshl_or_b32 v8, v1, 4, v0
	v_mov_b32_e32 v0, v183
	v_lshl_add_u64 v[4:5], s[8:9], 0, v[4:5]
	v_and_b32_e32 v182, 48, v7
	v_ashrrev_i32_e32 v7, 31, v6
	v_lshl_add_u64 v[4:5], v[4:5], 0, v[182:183]
	v_lshlrev_b64 v[6:7], 9, v[6:7]
	s_lshl_b32 s14, s12, 12
	s_waitcnt lgkmcnt(0)
	s_barrier
	s_mov_b32 m0, s14
	s_nop 0
	global_load_lds_dwordx4 v[4:5], off
	s_mov_b64 s[8:9], 0x2000
	v_lshl_add_u64 v[6:7], s[10:11], 0, v[6:7]
	v_lshl_add_u64 v[10:11], v[4:5], 0, s[8:9]
	s_or_b32 s15, s14, 0x400
	s_mov_b32 m0, s15
	s_nop 0
	global_load_lds_dwordx4 v[10:11], off
	s_mov_b64 s[10:11], 0x4000
	v_lshl_add_u64 v[10:11], v[4:5], 0, s[10:11]
	s_or_b32 s16, s14, 0x800
	s_mov_b32 m0, s16
	s_nop 0
	global_load_lds_dwordx4 v[10:11], off
	s_mov_b64 s[10:11], 0x6000
	s_lshl_b32 s42, s12, 11
	v_lshl_add_u64 v[10:11], v[4:5], 0, s[10:11]
	s_or_b32 s17, s14, 0xc00
	s_mov_b32 m0, s17
	s_nop 0
	global_load_lds_dwordx4 v[10:11], off
	v_lshl_add_u64 v[6:7], v[6:7], 0, v[182:183]
	s_add_i32 s13, s42, 0x4000
	s_mov_b32 m0, s13
	s_nop 0
	global_load_lds_dwordx4 v[6:7], off
	v_lshl_add_u64 v[10:11], v[6:7], 0, s[8:9]
	s_add_i32 s18, s42, 0x4400
	s_mov_b32 m0, s18
	s_nop 0
	global_load_lds_dwordx4 v[10:11], off
	v_lshl_add_u64 v[10:11], v[4:5], 0, 64
	s_add_i32 s7, s14, 0x6000
	s_mov_b32 m0, s7
	s_nop 0
	global_load_lds_dwordx4 v[10:11], off
	s_mov_b64 s[20:21], 0x2040
	v_lshl_add_u64 v[10:11], v[4:5], 0, s[20:21]
	s_add_i32 s8, s14, 0x6400
	s_mov_b32 m0, s8
	s_nop 0
	global_load_lds_dwordx4 v[10:11], off
	s_mov_b64 s[10:11], 0x4040
	v_lshl_add_u64 v[10:11], v[4:5], 0, s[10:11]
	s_add_i32 s9, s14, 0x6800
	s_mov_b32 m0, s9
	s_nop 0
	global_load_lds_dwordx4 v[10:11], off
	s_mov_b64 s[10:11], 0x6040
	v_lshl_add_u64 v[10:11], v[4:5], 0, s[10:11]
	s_add_i32 s10, s14, 0x6c00
	s_mov_b32 m0, s10
	s_nop 0
	global_load_lds_dwordx4 v[10:11], off
	v_lshl_add_u64 v[12:13], v[6:7], 0, 64
	s_add_i32 s11, s42, 0xa000
	s_mov_b32 m0, s11
	s_nop 0
	global_load_lds_dwordx4 v[12:13], off
	v_lshl_add_u64 v[10:11], v[6:7], 0, s[20:21]
	s_add_i32 s12, s42, 0xa400
	s_mov_b32 m0, s12
	s_nop 0
	global_load_lds_dwordx4 v[10:11], off
	s_waitcnt vmcnt(6)
	s_barrier
	v_lshl_add_u64 v[12:13], v[4:5], 0, s[28:29]
	s_add_i32 s19, s14, 0xc000
	s_mov_b32 m0, s19
	s_nop 0
	global_load_lds_dwordx4 v[12:13], off
	s_mov_b64 s[20:21], 0x2080
	v_lshl_add_u64 v[12:13], v[4:5], 0, s[20:21]
	s_add_i32 s34, s14, 0xc400
	s_mov_b32 m0, s34
	s_nop 0
	global_load_lds_dwordx4 v[12:13], off
	v_lshl_add_u64 v[12:13], v[4:5], 0, s[94:95]
	s_add_i32 s38, s14, 0xc800
	s_mov_b32 m0, s38
	s_nop 0
	global_load_lds_dwordx4 v[12:13], off
	s_mov_b64 s[22:23], 0x6080
	v_lshl_add_u64 v[12:13], v[4:5], 0, s[22:23]
	s_add_i32 s43, s14, 0xcc00
	s_mov_b32 m0, s43
	s_nop 0
	global_load_lds_dwordx4 v[12:13], off
	v_and_b32_e32 v90, 0xffffffc0, v9
	v_lshl_add_u64 v[10:11], v[6:7], 0, s[28:29]
	s_add_i32 s39, s42, 0x10000
	s_mov_b32 m0, s39
	s_nop 0
	global_load_lds_dwordx4 v[10:11], off
	v_lshl_add_u64 v[10:11], v[6:7], 0, s[20:21]
	s_add_i32 s42, s42, 0x10400
	s_mov_b32 m0, s42
	s_nop 0
	global_load_lds_dwordx4 v[10:11], off
	v_lshl_or_b32 v9, v90, 6, v8
	ds_read_b128 v[10:13], v9
	s_waitcnt vmcnt(7)
	ds_read_b128 v[14:17], v9 offset:1024
	s_waitcnt vmcnt(5)
	ds_read_b128 v[18:21], v9 offset:2048
	s_waitcnt vmcnt(5)
	ds_read_b128 v[22:25], v9 offset:3072
	s_waitcnt vmcnt(4)
	ds_read_b128 v[26:29], v8 offset:16384
	s_waitcnt vmcnt(4)
	ds_read_b128 v[30:33], v8 offset:17408
	ds_read_b128 v[34:37], v8 offset:18432
	ds_read_b128 v[38:41], v8 offset:19456
	s_waitcnt vmcnt(0)
	ds_read_b128 v[96:99], v8 offset:20480
	ds_read_b128 v[100:103], v8 offset:21504
	ds_read_b128 v[104:107], v8 offset:22528
	ds_read_b128 v[108:111], v8 offset:23552
	s_mov_b64 s[20:21], 0xc0
	v_mov_b32_e32 v1, v0
	v_mov_b32_e32 v2, v0
	v_mov_b32_e32 v3, v0
	v_lshl_add_u64 v[86:87], v[4:5], 0, s[20:21]
	v_lshl_add_u64 v[148:149], v[6:7], 0, s[20:21]
	s_waitcnt vmcnt(6)
	s_waitcnt lgkmcnt(0)
	s_barrier
; template <int N> DI void wait_vm() { asm volatile("s_waitcnt vmcnt(%0)" ::"n"(N) : "memory"); }
; template <int BM, class Epi>
; DI void gemm_dma(const u16* __restrict__ X, long ldx, const u16* __restrict__ W, long ldw, int K, char* smem,
;                  int m0, int n0, const Epi& epi) {
;     ...
;   do {
;     if (kt + D - 2 < nk) wait_vm<PW * (D - 2)>(); else wait_vm<0>();
;     __syncthreads();
;     if (kt + D - 1 < nk) GD_ISSUE(nxt)
;     nxt = (nxt + 1 == D) ? 0 : nxt + 1;
;     const char* base = smem + cur * STG;
;     cur = (cur + 1 == D) ? 0 : cur + 1;
;     bf16x8 xf[MT];
; #pragma unroll
;     for (int i = 0; i < MT; ++i) xf[i] = *(const bf16x8*)(base + (xrow0 + i * 16) * 64 + rd);
; #pragma unroll
;     for (int nh = 0; nh < NT / 4; ++nh) {
;       bf16x8 wf[4];
; #pragma unroll
;       for (int i = 0; i < 4; ++i) wf[i] = *(const bf16x8*)(base + BM * 64 + (wrow0 + (nh * 4 + i) * 16) * 64 + rd);
; #pragma unroll
;       for (int i = 0; i < 4; ++i)
; #pragma unroll
;         for (int mt = 0; mt < MT; ++mt)
;           acc[nh * 4 + i][mt] = __builtin_amdgcn_mfma_f32_16x16x32_bf16(wf[i], xf[mt], acc[nh * 4 + i][mt], 0, 0, 0);
;     }
;   } while (++kt < nk);
	s_mov_b32 m0, s14
	s_nop 0
	global_load_lds_dwordx4 v[86:87], off
	s_mov_b64 s[20:21], 0x20c0
	v_mfma_f32_16x16x32_bf16 v[42:45], v[26:29], v[10:13], v[0:3]
	s_mov_b64 s[22:23], 0x40c0
	v_or_b32_e32 v91, 0x10000, v8
	v_or_b32_e32 v174, 0x10400, v8
	v_mfma_f32_16x16x32_bf16 v[46:49], v[26:29], v[14:17], v[0:3]
	v_or_b32_e32 v175, 0x10800, v8
	v_or_b32_e32 v176, 0x10c00, v8
	v_or_b32_e32 v177, 0x11000, v8
	v_mfma_f32_16x16x32_bf16 v[50:53], v[26:29], v[18:21], v[0:3]
	v_or_b32_e32 v178, 0x11400, v8
	v_or_b32_e32 v179, 0x11800, v8
	v_or_b32_e32 v180, 0x11c00, v8
	v_mfma_f32_16x16x32_bf16 v[26:29], v[26:29], v[22:25], v[0:3]
	v_lshl_add_u32 v90, s6, 8, v90
	s_lshl_b32 s4, s4, 8
	v_lshl_or_b32 v182, v88, 3, s4
	v_mfma_f32_16x16x32_bf16 v[54:57], v[30:33], v[10:13], v[0:3]
	v_mfma_f32_16x16x32_bf16 v[58:61], v[30:33], v[14:17], v[0:3]
	v_mfma_f32_16x16x32_bf16 v[62:65], v[30:33], v[18:21], v[0:3]
	v_mfma_f32_16x16x32_bf16 v[30:33], v[30:33], v[22:25], v[0:3]
	v_mfma_f32_16x16x32_bf16 v[66:69], v[34:37], v[10:13], v[0:3]
	v_mfma_f32_16x16x32_bf16 v[70:73], v[34:37], v[14:17], v[0:3]
	v_mfma_f32_16x16x32_bf16 v[74:77], v[34:37], v[18:21], v[0:3]
	v_mfma_f32_16x16x32_bf16 v[34:37], v[34:37], v[22:25], v[0:3]
	v_mfma_f32_16x16x32_bf16 v[78:81], v[38:41], v[10:13], v[0:3]
	v_mfma_f32_16x16x32_bf16 v[82:85], v[38:41], v[14:17], v[0:3]
	v_mfma_f32_16x16x32_bf16 v[92:95], v[38:41], v[18:21], v[0:3]
	v_mfma_f32_16x16x32_bf16 v[38:41], v[38:41], v[22:25], v[0:3]
	v_mfma_f32_16x16x32_bf16 v[112:115], v[96:99], v[10:13], v[0:3]
	v_mfma_f32_16x16x32_bf16 v[116:119], v[96:99], v[14:17], v[0:3]
	v_mfma_f32_16x16x32_bf16 v[120:123], v[96:99], v[18:21], v[0:3]
	v_mfma_f32_16x16x32_bf16 v[96:99], v[96:99], v[22:25], v[0:3]
	v_mfma_f32_16x16x32_bf16 v[124:127], v[100:103], v[10:13], v[0:3]
	v_mfma_f32_16x16x32_bf16 v[128:131], v[100:103], v[14:17], v[0:3]
	v_mfma_f32_16x16x32_bf16 v[132:135], v[100:103], v[18:21], v[0:3]
	v_mfma_f32_16x16x32_bf16 v[100:103], v[100:103], v[22:25], v[0:3]
	v_mfma_f32_16x16x32_bf16 v[136:139], v[104:107], v[10:13], v[0:3]
	v_mfma_f32_16x16x32_bf16 v[140:143], v[104:107], v[14:17], v[0:3]
	v_mfma_f32_16x16x32_bf16 v[144:147], v[104:107], v[18:21], v[0:3]
	v_mfma_f32_16x16x32_bf16 v[104:107], v[104:107], v[22:25], v[0:3]
	v_mfma_f32_16x16x32_bf16 v[10:13], v[108:111], v[10:13], v[0:3]
	v_mfma_f32_16x16x32_bf16 v[14:17], v[108:111], v[14:17], v[0:3]
	v_mfma_f32_16x16x32_bf16 v[18:21], v[108:111], v[18:21], v[0:3]
	v_mfma_f32_16x16x32_bf16 v[0:3], v[108:111], v[22:25], v[0:3]
	v_lshl_add_u64 v[22:23], v[4:5], 0, s[20:21]
	s_mov_b32 m0, s15
	s_nop 0
	global_load_lds_dwordx4 v[22:23], off
	v_lshl_add_u64 v[22:23], v[4:5], 0, s[22:23]
	s_mov_b32 m0, s16
	s_nop 0
	global_load_lds_dwordx4 v[22:23], off
	s_mov_b64 s[22:23], 0x60c0
	v_lshl_add_u64 v[22:23], v[4:5], 0, s[22:23]
	s_mov_b32 m0, s17
	s_nop 0
	global_load_lds_dwordx4 v[22:23], off
	v_lshl_add_u64 v[22:23], v[6:7], 0, s[20:21]
	s_mov_b32 m0, s13
	s_nop 0
	global_load_lds_dwordx4 v[148:149], off
	s_mov_b64 s[20:21], 0x100
	s_mov_b32 m0, s18
	s_nop 0
	global_load_lds_dwordx4 v[22:23], off
	ds_read_b128 v[22:25], v9 offset:24576
	ds_read_b128 v[108:111], v9 offset:25600
	ds_read_b128 v[148:151], v9 offset:26624
	ds_read_b128 v[152:155], v9 offset:27648
	ds_read_b128 v[156:159], v8 offset:40960
	ds_read_b128 v[160:163], v8 offset:41984
	ds_read_b128 v[164:167], v8 offset:43008
	ds_read_b128 v[168:171], v8 offset:44032
	s_waitcnt lgkmcnt(3)
	v_mfma_f32_16x16x32_bf16 v[42:45], v[156:159], v[22:25], v[42:45]
	v_lshl_add_u64 v[86:87], v[4:5], 0, s[20:21]
	v_lshl_add_u64 v[172:173], v[6:7], 0, s[20:21]
	s_mov_b64 s[20:21], 0x2100
	v_mfma_f32_16x16x32_bf16 v[46:49], v[156:159], v[108:111], v[46:49]
	s_mov_b64 s[22:23], 0x4100
	v_mfma_f32_16x16x32_bf16 v[50:53], v[156:159], v[148:151], v[50:53]
	v_mfma_f32_16x16x32_bf16 v[26:29], v[156:159], v[152:155], v[26:29]
	s_waitcnt lgkmcnt(2)
	v_mfma_f32_16x16x32_bf16 v[54:57], v[160:163], v[22:25], v[54:57]
	v_mfma_f32_16x16x32_bf16 v[58:61], v[160:163], v[108:111], v[58:61]
	v_mfma_f32_16x16x32_bf16 v[62:65], v[160:163], v[148:151], v[62:65]
	v_mfma_f32_16x16x32_bf16 v[30:33], v[160:163], v[152:155], v[30:33]
	s_waitcnt lgkmcnt(1)
	v_mfma_f32_16x16x32_bf16 v[66:69], v[164:167], v[22:25], v[66:69]
	v_mfma_f32_16x16x32_bf16 v[70:73], v[164:167], v[108:111], v[70:73]
	v_mfma_f32_16x16x32_bf16 v[74:77], v[164:167], v[148:151], v[74:77]
	v_mfma_f32_16x16x32_bf16 v[34:37], v[164:167], v[152:155], v[34:37]
	s_waitcnt lgkmcnt(0)
	v_mfma_f32_16x16x32_bf16 v[78:81], v[168:171], v[22:25], v[78:81]
	v_mfma_f32_16x16x32_bf16 v[82:85], v[168:171], v[108:111], v[82:85]
	v_mfma_f32_16x16x32_bf16 v[92:95], v[168:171], v[148:151], v[92:95]
	v_mfma_f32_16x16x32_bf16 v[38:41], v[168:171], v[152:155], v[38:41]
	ds_read_b128 v[156:159], v8 offset:45056
	ds_read_b128 v[160:163], v8 offset:46080
	ds_read_b128 v[164:167], v8 offset:47104
	ds_read_b128 v[168:171], v8 offset:48128
	s_waitcnt vmcnt(6)
	s_waitcnt lgkmcnt(0)
	s_barrier
; template <int N> DI void wait_vm() { asm volatile("s_waitcnt vmcnt(%0)" ::"n"(N) : "memory"); }
; template <int BM, class Epi>
; DI void gemm_dma(const u16* __restrict__ X, long ldx, const u16* __restrict__ W, long ldw, int K, char* smem,
;                  int m0, int n0, const Epi& epi) {
;     ...
;   do {
;     if (kt + D - 2 < nk) wait_vm<PW * (D - 2)>(); else wait_vm<0>();
;     __syncthreads();
;     if (kt + D - 1 < nk) GD_ISSUE(nxt)
;     nxt = (nxt + 1 == D) ? 0 : nxt + 1;
;     const char* base = smem + cur * STG;
;     cur = (cur + 1 == D) ? 0 : cur + 1;
;     bf16x8 xf[MT];
; #pragma unroll
;     for (int i = 0; i < MT; ++i) xf[i] = *(const bf16x8*)(base + (xrow0 + i * 16) * 64 + rd);
; #pragma unroll
;     for (int nh = 0; nh < NT / 4; ++nh) {
;       bf16x8 wf[4];
; #pragma unroll
;       for (int i = 0; i < 4; ++i) wf[i] = *(const bf16x8*)(base + BM * 64 + (wrow0 + (nh * 4 + i) * 16) * 64 + rd);
; #pragma unroll
;       for (int i = 0; i < 4; ++i)
; #pragma unroll
;         for (int mt = 0; mt < MT; ++mt)
;           acc[nh * 4 + i][mt] = __builtin_amdgcn_mfma_f32_16x16x32_bf16(wf[i], xf[mt], acc[nh * 4 + i][mt], 0, 0, 0);
;     }
;   } while (++kt < nk);
	s_mov_b32 m0, s7
	s_nop 0
	global_load_lds_dwordx4 v[86:87], off
	v_mfma_f32_16x16x32_bf16 v[112:115], v[156:159], v[22:25], v[112:115]
	v_mfma_f32_16x16x32_bf16 v[124:127], v[160:163], v[22:25], v[124:127]
	v_mfma_f32_16x16x32_bf16 v[136:139], v[164:167], v[22:25], v[136:139]
	v_mfma_f32_16x16x32_bf16 v[10:13], v[168:171], v[22:25], v[10:13]
	v_lshl_add_u64 v[22:23], v[4:5], 0, s[20:21]
	s_mov_b32 m0, s8
	s_nop 0
	global_load_lds_dwordx4 v[22:23], off
	v_lshl_add_u64 v[22:23], v[4:5], 0, s[22:23]
	s_mov_b32 m0, s9
	s_nop 0
	global_load_lds_dwordx4 v[22:23], off
	s_mov_b64 s[22:23], 0x6100
	v_lshl_add_u64 v[22:23], v[4:5], 0, s[22:23]
	s_mov_b32 m0, s10
	s_nop 0
	global_load_lds_dwordx4 v[22:23], off
	v_lshl_add_u64 v[22:23], v[6:7], 0, s[20:21]
	s_mov_b32 m0, s11
	s_nop 0
	global_load_lds_dwordx4 v[172:173], off
	v_mfma_f32_16x16x32_bf16 v[116:119], v[156:159], v[108:111], v[116:119]
	s_mov_b32 m0, s12
	s_nop 0
	global_load_lds_dwordx4 v[22:23], off
	s_mov_b64 s[20:21], 0x140
	v_lshl_add_u64 v[86:87], v[4:5], 0, s[20:21]
	v_mfma_f32_16x16x32_bf16 v[120:123], v[156:159], v[148:151], v[120:123]
	v_lshl_add_u64 v[172:173], v[6:7], 0, s[20:21]
	s_mov_b64 s[20:21], 0x2140
	s_mov_b64 s[22:23], 0x4140
	v_mfma_f32_16x16x32_bf16 v[96:99], v[156:159], v[152:155], v[96:99]
	v_mfma_f32_16x16x32_bf16 v[128:131], v[160:163], v[108:111], v[128:131]
	v_mfma_f32_16x16x32_bf16 v[132:135], v[160:163], v[148:151], v[132:135]
	v_mfma_f32_16x16x32_bf16 v[100:103], v[160:163], v[152:155], v[100:103]
	v_mfma_f32_16x16x32_bf16 v[140:143], v[164:167], v[108:111], v[140:143]
	v_mfma_f32_16x16x32_bf16 v[144:147], v[164:167], v[148:151], v[144:147]
	v_mfma_f32_16x16x32_bf16 v[104:107], v[164:167], v[152:155], v[104:107]
	v_mfma_f32_16x16x32_bf16 v[14:17], v[168:171], v[108:111], v[14:17]
	v_mfma_f32_16x16x32_bf16 v[18:21], v[168:171], v[148:151], v[18:21]
	v_mfma_f32_16x16x32_bf16 v[0:3], v[168:171], v[152:155], v[0:3]
	ds_read_b128 v[22:25], v9 offset:49152
	ds_read_b128 v[108:111], v9 offset:50176
	ds_read_b128 v[148:151], v9 offset:51200
	ds_read_b128 v[152:155], v9 offset:52224
	ds_read_b128 v[156:159], v91
	ds_read_b128 v[160:163], v174
	ds_read_b128 v[164:167], v175
	ds_read_b128 v[168:171], v176
	s_waitcnt lgkmcnt(3)
	v_mfma_f32_16x16x32_bf16 v[42:45], v[156:159], v[22:25], v[42:45]
	v_mfma_f32_16x16x32_bf16 v[46:49], v[156:159], v[108:111], v[46:49]
	v_mfma_f32_16x16x32_bf16 v[50:53], v[156:159], v[148:151], v[50:53]
	v_mfma_f32_16x16x32_bf16 v[26:29], v[156:159], v[152:155], v[26:29]
	ds_read_b128 v[156:159], v177
	s_waitcnt lgkmcnt(3)
	v_mfma_f32_16x16x32_bf16 v[54:57], v[160:163], v[22:25], v[54:57]
	v_mfma_f32_16x16x32_bf16 v[58:61], v[160:163], v[108:111], v[58:61]
	v_mfma_f32_16x16x32_bf16 v[62:65], v[160:163], v[148:151], v[62:65]
	v_mfma_f32_16x16x32_bf16 v[30:33], v[160:163], v[152:155], v[30:33]
	ds_read_b128 v[160:163], v178
	s_waitcnt lgkmcnt(3)
	v_mfma_f32_16x16x32_bf16 v[66:69], v[164:167], v[22:25], v[66:69]
	v_mfma_f32_16x16x32_bf16 v[70:73], v[164:167], v[108:111], v[70:73]
	v_mfma_f32_16x16x32_bf16 v[74:77], v[164:167], v[148:151], v[74:77]
	v_mfma_f32_16x16x32_bf16 v[34:37], v[164:167], v[152:155], v[34:37]
	ds_read_b128 v[164:167], v179
	s_waitcnt lgkmcnt(3)
	v_mfma_f32_16x16x32_bf16 v[78:81], v[168:171], v[22:25], v[78:81]
	v_mfma_f32_16x16x32_bf16 v[82:85], v[168:171], v[108:111], v[82:85]
	v_mfma_f32_16x16x32_bf16 v[92:95], v[168:171], v[148:151], v[92:95]
	v_mfma_f32_16x16x32_bf16 v[38:41], v[168:171], v[152:155], v[38:41]
	ds_read_b128 v[168:171], v180
	s_waitcnt vmcnt(6)
	s_waitcnt lgkmcnt(0)
	s_barrier
	s_mov_b32 m0, s19
	s_nop 0
	global_load_lds_dwordx4 v[86:87], off
	v_mfma_f32_16x16x32_bf16 v[112:115], v[156:159], v[22:25], v[112:115]
	v_mfma_f32_16x16x32_bf16 v[124:127], v[160:163], v[22:25], v[124:127]
	v_mfma_f32_16x16x32_bf16 v[136:139], v[164:167], v[22:25], v[136:139]
	v_mfma_f32_16x16x32_bf16 v[10:13], v[168:171], v[22:25], v[10:13]
	v_lshl_add_u64 v[22:23], v[4:5], 0, s[20:21]
	s_mov_b32 m0, s34
	s_nop 0
	global_load_lds_dwordx4 v[22:23], off
	v_lshl_add_u64 v[22:23], v[4:5], 0, s[22:23]
	s_mov_b32 m0, s38
	s_nop 0
	global_load_lds_dwordx4 v[22:23], off
	s_mov_b64 s[22:23], 0x6140
	v_lshl_add_u64 v[22:23], v[4:5], 0, s[22:23]
	s_mov_b32 m0, s43
	s_nop 0
	global_load_lds_dwordx4 v[22:23], off
	v_lshl_add_u64 v[22:23], v[6:7], 0, s[20:21]
	s_mov_b32 m0, s39
	s_nop 0
	global_load_lds_dwordx4 v[172:173], off
	v_mfma_f32_16x16x32_bf16 v[116:119], v[156:159], v[108:111], v[116:119]
	s_mov_b32 m0, s42
	s_nop 0
	global_load_lds_dwordx4 v[22:23], off
	s_mov_b64 s[20:21], 0x180
	v_lshl_add_u64 v[86:87], v[4:5], 0, s[20:21]
	v_mfma_f32_16x16x32_bf16 v[120:123], v[156:159], v[148:151], v[120:123]
	v_lshl_add_u64 v[172:173], v[6:7], 0, s[20:21]
	s_mov_b64 s[20:21], 0x2180
	s_mov_b64 s[38:39], 0
	v_mfma_f32_16x16x32_bf16 v[96:99], v[156:159], v[152:155], v[96:99]
	v_mfma_f32_16x16x32_bf16 v[128:131], v[160:163], v[108:111], v[128:131]
	v_mfma_f32_16x16x32_bf16 v[132:135], v[160:163], v[148:151], v[132:135]
	v_mfma_f32_16x16x32_bf16 v[100:103], v[160:163], v[152:155], v[100:103]
	v_mfma_f32_16x16x32_bf16 v[140:143], v[164:167], v[108:111], v[140:143]
	v_mfma_f32_16x16x32_bf16 v[144:147], v[164:167], v[148:151], v[144:147]
	v_mfma_f32_16x16x32_bf16 v[104:107], v[164:167], v[152:155], v[104:107]
	v_mfma_f32_16x16x32_bf16 v[14:17], v[168:171], v[108:111], v[14:17]
	v_mfma_f32_16x16x32_bf16 v[18:21], v[168:171], v[148:151], v[18:21]
	v_mfma_f32_16x16x32_bf16 v[0:3], v[168:171], v[152:155], v[0:3]
	ds_read_b128 v[22:25], v9
	ds_read_b128 v[108:111], v9 offset:1024
	ds_read_b128 v[148:151], v9 offset:2048
	ds_read_b128 v[152:155], v9 offset:3072
	ds_read_b128 v[156:159], v8 offset:16384
	ds_read_b128 v[160:163], v8 offset:17408
	ds_read_b128 v[164:167], v8 offset:18432
	ds_read_b128 v[168:171], v8 offset:19456
	s_waitcnt lgkmcnt(3)
; template <int N> DI void wait_vm() { asm volatile("s_waitcnt vmcnt(%0)" ::"n"(N) : "memory"); }
; template <int BM, class Epi>
; DI void gemm_dma(const u16* __restrict__ X, long ldx, const u16* __restrict__ W, long ldw, int K, char* smem,
;                  int m0, int n0, const Epi& epi) {
;     ...
;   do {
;     if (kt + D - 2 < nk) wait_vm<PW * (D - 2)>(); else wait_vm<0>();
;     __syncthreads();
;     if (kt + D - 1 < nk) GD_ISSUE(nxt)
;     nxt = (nxt + 1 == D) ? 0 : nxt + 1;
;     const char* base = smem + cur * STG;
;     cur = (cur + 1 == D) ? 0 : cur + 1;
;     bf16x8 xf[MT];
; #pragma unroll
;     for (int i = 0; i < MT; ++i) xf[i] = *(const bf16x8*)(base + (xrow0 + i * 16) * 64 + rd);
; #pragma unroll
;     for (int nh = 0; nh < NT / 4; ++nh) {
;       bf16x8 wf[4];
; #pragma unroll
;       for (int i = 0; i < 4; ++i) wf[i] = *(const bf16x8*)(base + BM * 64 + (wrow0 + (nh * 4 + i) * 16) * 64 + rd);
; #pragma unroll
;       for (int i = 0; i < 4; ++i)
; #pragma unroll
;         for (int mt = 0; mt < MT; ++mt)
;           acc[nh * 4 + i][mt] = __builtin_amdgcn_mfma_f32_16x16x32_bf16(wf[i], xf[mt], acc[nh * 4 + i][mt], 0, 0, 0);
;     }
;   } while (++kt < nk);
	v_mfma_f32_16x16x32_bf16 v[42:45], v[156:159], v[22:25], v[42:45]
	v_mfma_f32_16x16x32_bf16 v[46:49], v[156:159], v[108:111], v[46:49]
	v_mfma_f32_16x16x32_bf16 v[50:53], v[156:159], v[148:151], v[50:53]
	v_mfma_f32_16x16x32_bf16 v[26:29], v[156:159], v[152:155], v[26:29]
	s_waitcnt lgkmcnt(2)
	v_mfma_f32_16x16x32_bf16 v[54:57], v[160:163], v[22:25], v[54:57]
	v_mfma_f32_16x16x32_bf16 v[58:61], v[160:163], v[108:111], v[58:61]
	v_mfma_f32_16x16x32_bf16 v[62:65], v[160:163], v[148:151], v[62:65]
	v_mfma_f32_16x16x32_bf16 v[30:33], v[160:163], v[152:155], v[30:33]
	s_waitcnt lgkmcnt(1)
	v_mfma_f32_16x16x32_bf16 v[66:69], v[164:167], v[22:25], v[66:69]
	v_mfma_f32_16x16x32_bf16 v[70:73], v[164:167], v[108:111], v[70:73]
	v_mfma_f32_16x16x32_bf16 v[74:77], v[164:167], v[148:151], v[74:77]
	v_mfma_f32_16x16x32_bf16 v[34:37], v[164:167], v[152:155], v[34:37]
	s_waitcnt lgkmcnt(0)
	v_mfma_f32_16x16x32_bf16 v[78:81], v[168:171], v[22:25], v[78:81]
	v_mfma_f32_16x16x32_bf16 v[82:85], v[168:171], v[108:111], v[82:85]
	v_mfma_f32_16x16x32_bf16 v[92:95], v[168:171], v[148:151], v[92:95]
	v_mfma_f32_16x16x32_bf16 v[38:41], v[168:171], v[152:155], v[38:41]
	ds_read_b128 v[156:159], v8 offset:20480
	ds_read_b128 v[160:163], v8 offset:21504
	ds_read_b128 v[164:167], v8 offset:22528
	ds_read_b128 v[168:171], v8 offset:23552
	s_waitcnt vmcnt(6)
	s_waitcnt lgkmcnt(0)
	s_barrier
	s_mov_b32 m0, s14
	s_nop 0
	global_load_lds_dwordx4 v[86:87], off
	v_mfma_f32_16x16x32_bf16 v[112:115], v[156:159], v[22:25], v[112:115]
	v_mfma_f32_16x16x32_bf16 v[124:127], v[160:163], v[22:25], v[124:127]
	v_mfma_f32_16x16x32_bf16 v[136:139], v[164:167], v[22:25], v[136:139]
	v_mfma_f32_16x16x32_bf16 v[10:13], v[168:171], v[22:25], v[10:13]
	v_lshl_add_u64 v[22:23], v[4:5], 0, s[20:21]
	s_mov_b32 m0, s15
	s_nop 0
	global_load_lds_dwordx4 v[22:23], off
	s_mov_b64 s[14:15], 0x4180
	v_lshl_add_u64 v[22:23], v[4:5], 0, s[14:15]
	s_mov_b32 m0, s16
	s_nop 0
	global_load_lds_dwordx4 v[22:23], off
	s_mov_b64 s[14:15], 0x6180
	v_lshl_add_u64 v[22:23], v[4:5], 0, s[14:15]
	s_mov_b32 m0, s17
	s_nop 0
	global_load_lds_dwordx4 v[22:23], off
	v_lshl_add_u64 v[22:23], v[6:7], 0, s[20:21]
	s_mov_b32 m0, s13
	s_nop 0
	global_load_lds_dwordx4 v[172:173], off
	s_mov_b32 m0, s18
	s_nop 0
	global_load_lds_dwordx4 v[22:23], off
	v_mfma_f32_16x16x32_bf16 v[116:119], v[156:159], v[108:111], v[116:119]
	s_mov_b64 s[14:15], 0x1c0
	v_lshl_add_u64 v[86:87], v[4:5], 0, s[14:15]
	v_lshl_add_u64 v[172:173], v[6:7], 0, s[14:15]
	v_mfma_f32_16x16x32_bf16 v[120:123], v[156:159], v[148:151], v[120:123]
	s_mov_b64 s[14:15], 0x21c0
	s_mov_b64 s[16:17], 0x41c0
	v_mfma_f32_16x16x32_bf16 v[96:99], v[156:159], v[152:155], v[96:99]
	v_mfma_f32_16x16x32_bf16 v[128:131], v[160:163], v[108:111], v[128:131]
	v_mfma_f32_16x16x32_bf16 v[132:135], v[160:163], v[148:151], v[132:135]
	v_mfma_f32_16x16x32_bf16 v[100:103], v[160:163], v[152:155], v[100:103]
	v_mfma_f32_16x16x32_bf16 v[140:143], v[164:167], v[108:111], v[140:143]
	v_mfma_f32_16x16x32_bf16 v[144:147], v[164:167], v[148:151], v[144:147]
	v_mfma_f32_16x16x32_bf16 v[104:107], v[164:167], v[152:155], v[104:107]
	v_mfma_f32_16x16x32_bf16 v[14:17], v[168:171], v[108:111], v[14:17]
	v_mfma_f32_16x16x32_bf16 v[18:21], v[168:171], v[148:151], v[18:21]
	v_mfma_f32_16x16x32_bf16 v[0:3], v[168:171], v[152:155], v[0:3]
	ds_read_b128 v[22:25], v9 offset:24576
	ds_read_b128 v[108:111], v9 offset:25600
	ds_read_b128 v[148:151], v9 offset:26624
	ds_read_b128 v[152:155], v9 offset:27648
	ds_read_b128 v[156:159], v8 offset:40960
	ds_read_b128 v[160:163], v8 offset:41984
	ds_read_b128 v[164:167], v8 offset:43008
	ds_read_b128 v[168:171], v8 offset:44032
	s_waitcnt lgkmcnt(3)
	v_mfma_f32_16x16x32_bf16 v[42:45], v[156:159], v[22:25], v[42:45]
	v_mfma_f32_16x16x32_bf16 v[46:49], v[156:159], v[108:111], v[46:49]
	v_mfma_f32_16x16x32_bf16 v[50:53], v[156:159], v[148:151], v[50:53]
	v_mfma_f32_16x16x32_bf16 v[26:29], v[156:159], v[152:155], v[26:29]
	s_waitcnt lgkmcnt(2)
	v_mfma_f32_16x16x32_bf16 v[54:57], v[160:163], v[22:25], v[54:57]
	v_mfma_f32_16x16x32_bf16 v[58:61], v[160:163], v[108:111], v[58:61]
	v_mfma_f32_16x16x32_bf16 v[62:65], v[160:163], v[148:151], v[62:65]
	v_mfma_f32_16x16x32_bf16 v[30:33], v[160:163], v[152:155], v[30:33]
	s_waitcnt lgkmcnt(1)
	v_mfma_f32_16x16x32_bf16 v[66:69], v[164:167], v[22:25], v[66:69]
	v_mfma_f32_16x16x32_bf16 v[70:73], v[164:167], v[108:111], v[70:73]
	v_mfma_f32_16x16x32_bf16 v[74:77], v[164:167], v[148:151], v[74:77]
	v_mfma_f32_16x16x32_bf16 v[34:37], v[164:167], v[152:155], v[34:37]
	s_waitcnt lgkmcnt(0)
	v_mfma_f32_16x16x32_bf16 v[78:81], v[168:171], v[22:25], v[78:81]
	v_mfma_f32_16x16x32_bf16 v[82:85], v[168:171], v[108:111], v[82:85]
	v_mfma_f32_16x16x32_bf16 v[92:95], v[168:171], v[148:151], v[92:95]
	v_mfma_f32_16x16x32_bf16 v[38:41], v[168:171], v[152:155], v[38:41]
	ds_read_b128 v[156:159], v8 offset:45056
	ds_read_b128 v[160:163], v8 offset:46080
	ds_read_b128 v[164:167], v8 offset:47104
	ds_read_b128 v[168:171], v8 offset:48128
	s_waitcnt vmcnt(6)
	s_waitcnt lgkmcnt(0)
	s_barrier
; template <int N> DI void wait_vm() { asm volatile("s_waitcnt vmcnt(%0)" ::"n"(N) : "memory"); }
; template <int BM, class Epi>
; DI void gemm_dma(const u16* __restrict__ X, long ldx, const u16* __restrict__ W, long ldw, int K, char* smem,
;                  int m0, int n0, const Epi& epi) {
;     ...
;   do {
;     if (kt + D - 2 < nk) wait_vm<PW * (D - 2)>(); else wait_vm<0>();
;     __syncthreads();
;     if (kt + D - 1 < nk) GD_ISSUE(nxt)
;     nxt = (nxt + 1 == D) ? 0 : nxt + 1;
;     const char* base = smem + cur * STG;
;     cur = (cur + 1 == D) ? 0 : cur + 1;
;     bf16x8 xf[MT];
; #pragma unroll
;     for (int i = 0; i < MT; ++i) xf[i] = *(const bf16x8*)(base + (xrow0 + i * 16) * 64 + rd);
; #pragma unroll
;     for (int nh = 0; nh < NT / 4; ++nh) {
;       bf16x8 wf[4];
; #pragma unroll
;       for (int i = 0; i < 4; ++i) wf[i] = *(const bf16x8*)(base + BM * 64 + (wrow0 + (nh * 4 + i) * 16) * 64 + rd);
; #pragma unroll
;       for (int i = 0; i < 4; ++i)
; #pragma unroll
;         for (int mt = 0; mt < MT; ++mt)
;           acc[nh * 4 + i][mt] = __builtin_amdgcn_mfma_f32_16x16x32_bf16(wf[i], xf[mt], acc[nh * 4 + i][mt], 0, 0, 0);
;     }
;   } while (++kt < nk);
	s_mov_b32 m0, s7
	s_nop 0
	global_load_lds_dwordx4 v[86:87], off
	v_mfma_f32_16x16x32_bf16 v[112:115], v[156:159], v[22:25], v[112:115]
	v_mfma_f32_16x16x32_bf16 v[124:127], v[160:163], v[22:25], v[124:127]
	v_mfma_f32_16x16x32_bf16 v[136:139], v[164:167], v[22:25], v[136:139]
	v_mfma_f32_16x16x32_bf16 v[10:13], v[168:171], v[22:25], v[10:13]
	v_lshl_add_u64 v[22:23], v[4:5], 0, s[14:15]
	s_mov_b32 m0, s8
	s_nop 0
	global_load_lds_dwordx4 v[22:23], off
	v_lshl_add_u64 v[22:23], v[4:5], 0, s[16:17]
	s_mov_b32 m0, s9
	s_nop 0
	global_load_lds_dwordx4 v[22:23], off
	s_mov_b64 s[8:9], 0x61c0
	v_lshl_add_u64 v[4:5], v[4:5], 0, s[8:9]
	s_mov_b32 m0, s10
	s_nop 0
	global_load_lds_dwordx4 v[4:5], off
	v_lshl_add_u64 v[4:5], v[6:7], 0, s[14:15]
	s_mov_b32 m0, s11
	s_nop 0
	global_load_lds_dwordx4 v[172:173], off
	v_mfma_f32_16x16x32_bf16 v[116:119], v[156:159], v[108:111], v[116:119]
	s_mov_b32 m0, s12
	s_nop 0
	global_load_lds_dwordx4 v[4:5], off
	v_readlane_b32 s8, v255, 5
	v_readlane_b32 s14, v255, 11
	v_mfma_f32_16x16x32_bf16 v[120:123], v[156:159], v[148:151], v[120:123]
	v_readlane_b32 s9, v255, 6
	v_readlane_b32 s10, v255, 7
	v_readlane_b32 s11, v255, 8
	v_mfma_f32_16x16x32_bf16 v[96:99], v[156:159], v[152:155], v[96:99]
	v_readlane_b32 s12, v255, 9
	v_readlane_b32 s13, v255, 10
	v_readlane_b32 s15, v255, 12
	v_mfma_f32_16x16x32_bf16 v[128:131], v[160:163], v[108:111], v[128:131]
	s_add_i32 s4, s5, s14
	v_mfma_f32_16x16x32_bf16 v[132:135], v[160:163], v[148:151], v[132:135]
	v_mfma_f32_16x16x32_bf16 v[100:103], v[160:163], v[152:155], v[100:103]
	v_mfma_f32_16x16x32_bf16 v[140:143], v[164:167], v[108:111], v[140:143]
	v_mfma_f32_16x16x32_bf16 v[144:147], v[164:167], v[148:151], v[144:147]
	v_mfma_f32_16x16x32_bf16 v[104:107], v[164:167], v[152:155], v[104:107]
	v_mfma_f32_16x16x32_bf16 v[14:17], v[168:171], v[108:111], v[14:17]
	v_mfma_f32_16x16x32_bf16 v[18:21], v[168:171], v[148:151], v[18:21]
	v_mfma_f32_16x16x32_bf16 v[0:3], v[168:171], v[152:155], v[0:3]
	ds_read_b128 v[4:7], v9 offset:49152
	ds_read_b128 v[22:25], v9 offset:50176
	ds_read_b128 v[108:111], v9 offset:51200
	ds_read_b128 v[148:151], v9 offset:52224
	ds_read_b128 v[152:155], v91
	ds_read_b128 v[156:159], v174
	ds_read_b128 v[160:163], v175
	ds_read_b128 v[164:167], v176
	s_waitcnt lgkmcnt(3)
	v_mfma_f32_16x16x32_bf16 v[42:45], v[152:155], v[4:7], v[42:45]
	v_mfma_f32_16x16x32_bf16 v[46:49], v[152:155], v[22:25], v[46:49]
	v_mfma_f32_16x16x32_bf16 v[50:53], v[152:155], v[108:111], v[50:53]
	v_mfma_f32_16x16x32_bf16 v[26:29], v[152:155], v[148:151], v[26:29]
	s_waitcnt lgkmcnt(2)
	v_mfma_f32_16x16x32_bf16 v[54:57], v[156:159], v[4:7], v[54:57]
	v_mfma_f32_16x16x32_bf16 v[58:61], v[156:159], v[22:25], v[58:61]
	v_mfma_f32_16x16x32_bf16 v[62:65], v[156:159], v[108:111], v[62:65]
	v_mfma_f32_16x16x32_bf16 v[30:33], v[156:159], v[148:151], v[30:33]
	s_waitcnt lgkmcnt(1)
	v_mfma_f32_16x16x32_bf16 v[66:69], v[160:163], v[4:7], v[66:69]
	v_mfma_f32_16x16x32_bf16 v[70:73], v[160:163], v[22:25], v[70:73]
	v_mfma_f32_16x16x32_bf16 v[74:77], v[160:163], v[108:111], v[74:77]
	v_mfma_f32_16x16x32_bf16 v[34:37], v[160:163], v[148:151], v[34:37]
	s_waitcnt lgkmcnt(0)
	v_mfma_f32_16x16x32_bf16 v[78:81], v[164:167], v[4:7], v[78:81]
	v_mfma_f32_16x16x32_bf16 v[82:85], v[164:167], v[22:25], v[82:85]
	v_mfma_f32_16x16x32_bf16 v[92:95], v[164:167], v[108:111], v[92:95]
	v_mfma_f32_16x16x32_bf16 v[38:41], v[164:167], v[148:151], v[38:41]
	ds_read_b128 v[152:155], v177
	ds_read_b128 v[156:159], v178
	ds_read_b128 v[160:163], v179
	ds_read_b128 v[164:167], v180
	s_waitcnt vmcnt(6)
	s_waitcnt lgkmcnt(0)
	v_mfma_f32_16x16x32_bf16 v[112:115], v[152:155], v[4:7], v[112:115]
	s_barrier
	v_mfma_f32_16x16x32_bf16 v[116:119], v[152:155], v[22:25], v[116:119]
	v_mfma_f32_16x16x32_bf16 v[120:123], v[152:155], v[108:111], v[120:123]
	v_mfma_f32_16x16x32_bf16 v[96:99], v[152:155], v[148:151], v[96:99]
	v_mfma_f32_16x16x32_bf16 v[124:127], v[156:159], v[4:7], v[124:127]
	v_mfma_f32_16x16x32_bf16 v[128:131], v[156:159], v[22:25], v[128:131]
	v_mfma_f32_16x16x32_bf16 v[132:135], v[156:159], v[108:111], v[132:135]
	v_mfma_f32_16x16x32_bf16 v[100:103], v[156:159], v[148:151], v[100:103]
	v_mfma_f32_16x16x32_bf16 v[136:139], v[160:163], v[4:7], v[136:139]
	v_mfma_f32_16x16x32_bf16 v[140:143], v[160:163], v[22:25], v[140:143]
	v_mfma_f32_16x16x32_bf16 v[144:147], v[160:163], v[108:111], v[144:147]
	v_mfma_f32_16x16x32_bf16 v[104:107], v[160:163], v[148:151], v[104:107]
	v_mfma_f32_16x16x32_bf16 v[4:7], v[164:167], v[4:7], v[10:13]
	v_mfma_f32_16x16x32_bf16 v[10:13], v[164:167], v[22:25], v[14:17]
	v_mfma_f32_16x16x32_bf16 v[14:17], v[164:167], v[108:111], v[18:21]
	v_mfma_f32_16x16x32_bf16 v[0:3], v[164:167], v[148:151], v[0:3]
	s_nop 1
	ds_read_b128 v[18:21], v8 offset:23552
	ds_read_b128 v[22:25], v8 offset:22528
	ds_read_b128 v[108:111], v8 offset:21504
	ds_read_b128 v[148:151], v8 offset:20480
	ds_read_b128 v[152:155], v8 offset:19456
	ds_read_b128 v[156:159], v8 offset:18432
	ds_read_b128 v[160:163], v8 offset:17408
	ds_read_b128 v[164:167], v8 offset:16384
	ds_read_b128 v[168:171], v9 offset:3072
	ds_read_b128 v[172:175], v9 offset:2048
	ds_read_b128 v[176:179], v9 offset:1024
	ds_read_b128 v[186:189], v9
	s_waitcnt vmcnt(0)
	s_waitcnt lgkmcnt(0)
	v_mfma_f32_16x16x32_bf16 v[42:45], v[164:167], v[186:189], v[42:45]
	s_barrier
; DI void st_bf4(u16* p, float a, float b, float c, float d) { *(uint2*)p = make_uint2(pk2(a, b), pk2(c, d)); }
; template <int BM, class Epi>
; DI void gemm_dma(const u16* __restrict__ X, long ldx, const u16* __restrict__ W, long ldw, int K, char* smem,
;                  int m0, int n0, const Epi& epi) {
;     ...
;     for (int i = 0; i < MT; ++i) xf[i] = *(const bf16x8*)(base + (xrow0 + i * 16) * 64 + rd);
; #pragma unroll
;     for (int nh = 0; nh < NT / 4; ++nh) {
;       bf16x8 wf[4];
; #pragma unroll
;       for (int i = 0; i < 4; ++i) wf[i] = *(const bf16x8*)(base + BM * 64 + (wrow0 + (nh * 4 + i) * 16) * 64 + rd);
; #pragma unroll
;       for (int i = 0; i < 4; ++i)
; #pragma unroll
;         for (int mt = 0; mt < MT; ++mt)
;           acc[nh * 4 + i][mt] = __builtin_amdgcn_mfma_f32_16x16x32_bf16(wf[i], xf[mt], acc[nh * 4 + i][mt], 0, 0, 0);
;   template <int NT, int MT> DI void run(f32x4 (&acc)[NT][MT], int mb, int nb) const {
; #pragma unroll
;     for (int nt = 0; nt < NT; ++nt)
; #pragma unroll
;       for (int mt = 0; mt < MT; ++mt) {
;         f32x4 v = acc[nt][mt];
;         st_bf4(C + (size_t)(mb + mt * 16) * ldc + nb + nt * 16, v[0], v[1], v[2], v[3]);
;       }
;   }
	v_mfma_f32_16x16x32_bf16 v[46:49], v[164:167], v[176:179], v[46:49]
	v_mfma_f32_16x16x32_bf16 v[50:53], v[164:167], v[172:175], v[50:53]
	v_mfma_f32_16x16x32_bf16 v[26:29], v[164:167], v[168:171], v[26:29]
	v_mfma_f32_16x16x32_bf16 v[54:57], v[160:163], v[186:189], v[54:57]
	v_mfma_f32_16x16x32_bf16 v[58:61], v[160:163], v[176:179], v[58:61]
	v_mfma_f32_16x16x32_bf16 v[62:65], v[160:163], v[172:175], v[62:65]
	v_mfma_f32_16x16x32_bf16 v[30:33], v[160:163], v[168:171], v[30:33]
	v_mfma_f32_16x16x32_bf16 v[66:69], v[156:159], v[186:189], v[66:69]
	v_mfma_f32_16x16x32_bf16 v[70:73], v[156:159], v[176:179], v[70:73]
	v_mfma_f32_16x16x32_bf16 v[74:77], v[156:159], v[172:175], v[74:77]
	v_mfma_f32_16x16x32_bf16 v[34:37], v[156:159], v[168:171], v[34:37]
	v_mfma_f32_16x16x32_bf16 v[156:159], v[152:155], v[186:189], v[78:81]
	v_mfma_f32_16x16x32_bf16 v[84:87], v[152:155], v[176:179], v[82:85]
	v_mfma_f32_16x16x32_bf16 v[92:95], v[152:155], v[172:175], v[92:95]
	v_mfma_f32_16x16x32_bf16 v[152:155], v[152:155], v[168:171], v[38:41]
	v_mfma_f32_16x16x32_bf16 v[112:115], v[148:151], v[186:189], v[112:115]
	v_mfma_f32_16x16x32_bf16 v[116:119], v[148:151], v[176:179], v[116:119]
	v_mfma_f32_16x16x32_bf16 v[120:123], v[148:151], v[172:175], v[120:123]
	v_mfma_f32_16x16x32_bf16 v[96:99], v[148:151], v[168:171], v[96:99]
	v_mfma_f32_16x16x32_bf16 v[124:127], v[108:111], v[186:189], v[124:127]
	v_mfma_f32_16x16x32_bf16 v[128:131], v[108:111], v[176:179], v[128:131]
	v_mfma_f32_16x16x32_bf16 v[132:135], v[108:111], v[172:175], v[132:135]
	v_mfma_f32_16x16x32_bf16 v[100:103], v[108:111], v[168:171], v[100:103]
	v_mfma_f32_16x16x32_bf16 v[108:111], v[22:25], v[186:189], v[136:139]
	v_mfma_f32_16x16x32_bf16 v[136:139], v[22:25], v[176:179], v[140:143]
	v_mfma_f32_16x16x32_bf16 v[140:143], v[22:25], v[172:175], v[144:147]
	v_mfma_f32_16x16x32_bf16 v[104:107], v[22:25], v[168:171], v[104:107]
	v_mfma_f32_16x16x32_bf16 v[4:7], v[18:21], v[186:189], v[4:7]
	v_mfma_f32_16x16x32_bf16 v[144:147], v[18:21], v[176:179], v[10:13]
	v_mfma_f32_16x16x32_bf16 v[148:151], v[18:21], v[172:175], v[14:17]
	v_mfma_f32_16x16x32_bf16 v[0:3], v[18:21], v[168:171], v[0:3]
	s_nop 0
	ds_read_b128 v[10:13], v9 offset:24576
	ds_read_b128 v[160:163], v9 offset:25600
	ds_read_b128 v[164:167], v9 offset:26624
	ds_read_b128 v[168:171], v9 offset:27648
	ds_read_b128 v[14:17], v8 offset:40960
	ds_read_b128 v[18:21], v8 offset:41984
	ds_read_b128 v[22:25], v8 offset:43008
	ds_read_b128 v[172:175], v8 offset:44032
	s_waitcnt lgkmcnt(3)
	v_mfma_f32_16x16x32_bf16 v[176:179], v[14:17], v[10:13], v[42:45]
	v_mfma_f32_16x16x32_bf16 v[186:189], v[14:17], v[160:163], v[46:49]
	v_mfma_f32_16x16x32_bf16 v[190:193], v[14:17], v[164:167], v[50:53]
	v_mfma_f32_16x16x32_bf16 v[194:197], v[14:17], v[168:171], v[26:29]
	s_waitcnt lgkmcnt(2)
	v_mfma_f32_16x16x32_bf16 v[224:227], v[18:21], v[10:13], v[54:57]
	v_mfma_f32_16x16x32_bf16 v[228:231], v[18:21], v[160:163], v[58:61]
	v_mfma_f32_16x16x32_bf16 v[232:235], v[18:21], v[164:167], v[62:65]
	v_mfma_f32_16x16x32_bf16 v[236:239], v[18:21], v[168:171], v[30:33]
	s_waitcnt lgkmcnt(1)
	v_mfma_f32_16x16x32_bf16 v[240:243], v[22:25], v[10:13], v[66:69]
	v_mfma_f32_16x16x32_bf16 v[64:67], v[22:25], v[168:171], v[34:37]
	s_waitcnt lgkmcnt(0)
	v_mfma_f32_16x16x32_bf16 v[40:43], v[172:175], v[164:167], v[92:95]
	v_mfma_f32_16x16x32_bf16 v[32:35], v[172:175], v[168:171], v[152:155]
	ds_read_b128 v[14:17], v8 offset:45056
	ds_read_b128 v[18:21], v8 offset:46080
	ds_read_b128 v[92:95], v8 offset:47104
	ds_read_b128 v[152:155], v8 offset:48128
	s_nop 0
	v_cvt_pk_bf16_f32 v64, v64, v65
	v_cvt_pk_bf16_f32 v65, v66, v67
	v_mfma_f32_16x16x32_bf16 v[80:83], v[22:25], v[160:163], v[70:73]
	v_cvt_pk_bf16_f32 v32, v32, v33
	v_cvt_pk_bf16_f32 v33, v34, v35
	v_cvt_pk_bf16_f32 v40, v40, v41
	v_mfma_f32_16x16x32_bf16 v[72:75], v[22:25], v[164:167], v[74:77]
	v_cvt_pk_bf16_f32 v41, v42, v43
	s_nop 2
	v_cvt_pk_bf16_f32 v80, v80, v81
	v_cvt_pk_bf16_f32 v81, v82, v83
	v_mfma_f32_16x16x32_bf16 v[48:51], v[172:175], v[160:163], v[84:87]
	s_waitcnt lgkmcnt(3)
	v_mfma_f32_16x16x32_bf16 v[112:115], v[14:17], v[10:13], v[112:115]
	v_cvt_pk_bf16_f32 v72, v72, v73
	v_cvt_pk_bf16_f32 v73, v74, v75
	s_nop 3
	v_cvt_pk_bf16_f32 v48, v48, v49
	v_mfma_f32_16x16x32_bf16 v[84:87], v[14:17], v[160:163], v[116:119]
	v_cvt_pk_bf16_f32 v49, v50, v51
	v_mfma_f32_16x16x32_bf16 v[76:79], v[14:17], v[164:167], v[120:123]
	v_mfma_f32_16x16x32_bf16 v[68:71], v[14:17], v[168:171], v[96:99]
	s_waitcnt lgkmcnt(2)
	v_mfma_f32_16x16x32_bf16 v[60:63], v[18:21], v[10:13], v[124:127]
	s_nop 0
	v_cvt_pk_bf16_f32 v96, v190, v191
	v_cvt_pk_bf16_f32 v97, v192, v193
	v_mfma_f32_16x16x32_bf16 v[52:55], v[18:21], v[160:163], v[128:131]
	v_mfma_f32_16x16x32_bf16 v[44:47], v[18:21], v[164:167], v[132:135]
	v_mfma_f32_16x16x32_bf16 v[36:39], v[18:21], v[168:171], v[100:103]
	s_waitcnt lgkmcnt(1)
; DI void st_bf4(u16* p, float a, float b, float c, float d) { *(uint2*)p = make_uint2(pk2(a, b), pk2(c, d)); }
;   template <int NT, int MT> DI void run(f32x4 (&acc)[NT][MT], int mb, int nb) const {
; #pragma unroll
;     for (int nt = 0; nt < NT; ++nt)
; #pragma unroll
;       for (int mt = 0; mt < MT; ++mt) {
;         f32x4 v = acc[nt][mt];
;         st_bf4(C + (size_t)(mb + mt * 16) * ldc + nb + nt * 16, v[0], v[1], v[2], v[3]);
;       }
;   }
	v_mfma_f32_16x16x32_bf16 v[28:31], v[92:95], v[10:13], v[108:111]
	v_mfma_f32_16x16x32_bf16 v[24:27], v[92:95], v[160:163], v[136:139]
	v_mfma_f32_16x16x32_bf16 v[20:23], v[92:95], v[164:167], v[140:143]
	s_nop 5
	v_cvt_pk_bf16_f32 v28, v28, v29
	v_cvt_pk_bf16_f32 v29, v30, v31
	v_cvt_pk_bf16_f32 v24, v24, v25
	v_mfma_f32_16x16x32_bf16 v[16:19], v[92:95], v[168:171], v[104:107]
	v_or_b32_e32 v92, v90, v89
	v_ashrrev_i32_e32 v93, 31, v92
	v_lshlrev_b64 v[90:91], 11, v[92:93]
	v_lshl_add_u64 v[90:91], s[92:93], 0, v[90:91]
	v_bfe_u32 v34, v185, 4, 1
	v_mad_u32_u24 v182, v34, 24, v182
	v_lshl_add_u64 v[88:89], v[90:91], 0, v[182:183]
	v_cvt_pk_bf16_f32 v90, v176, v177
	v_cvt_pk_bf16_f32 v91, v178, v179
	v_mov_b32_e32 v98, v90
	v_mov_b32_e32 v99, v91
	v_or_b32_e32 v90, 16, v92
	v_ashrrev_i32_e32 v91, 31, v90
	v_lshlrev_b64 v[90:91], 11, v[90:91]
	v_lshl_add_u64 v[90:91], s[92:93], 0, v[90:91]
	v_lshl_add_u64 v[90:91], v[90:91], 0, v[182:183]
	v_cvt_pk_bf16_f32 v94, v186, v187
	v_cvt_pk_bf16_f32 v95, v188, v189
	v_mov_b32_e32 v102, v94
	v_mov_b32_e32 v103, v95
	v_or_b32_e32 v94, 32, v92
	v_or_b32_e32 v92, 48, v92
	v_ashrrev_i32_e32 v93, 31, v92
	v_lshlrev_b64 v[92:93], 11, v[92:93]
	v_ashrrev_i32_e32 v95, 31, v94
	v_lshl_add_u64 v[92:93], s[92:93], 0, v[92:93]
	v_lshlrev_b64 v[94:95], 11, v[94:95]
	v_lshl_add_u64 v[92:93], v[92:93], 0, v[182:183]
	v_lshl_add_u64 v[94:95], s[92:93], 0, v[94:95]
	v_mov_b32_e32 v108, v32
	v_mov_b32_e32 v109, v33
	v_cvt_pk_bf16_f32 v32, v112, v113
	v_cvt_pk_bf16_f32 v33, v114, v115
	v_lshl_add_u64 v[94:95], v[94:95], 0, v[182:183]
	v_mov_b32_e32 v116, v32
	v_mov_b32_e32 v117, v33
	v_cvt_pk_bf16_f32 v32, v84, v85
	v_cvt_pk_bf16_f32 v33, v86, v87
	v_mov_b32_e32 v120, v96
	v_mov_b32_e32 v121, v97
	v_cvt_pk_bf16_f32 v96, v194, v195
	v_cvt_pk_bf16_f32 v97, v196, v197
	v_mov_b32_e32 v124, v32
	v_mov_b32_e32 v125, v33
	v_cvt_pk_bf16_f32 v32, v76, v77
	v_cvt_pk_bf16_f32 v33, v78, v79
	v_mfma_f32_16x16x32_bf16 v[56:59], v[172:175], v[10:13], v[156:159]
	v_mov_b32_e32 v110, v96
	v_mov_b32_e32 v111, v97
	v_cvt_pk_bf16_f32 v96, v224, v225
	v_cvt_pk_bf16_f32 v97, v226, v227
	s_waitcnt lgkmcnt(0)
	v_mfma_f32_16x16x32_bf16 v[12:15], v[152:155], v[10:13], v[4:7]
	v_mov_b32_e32 v82, v32
	v_mov_b32_e32 v83, v33
	v_cvt_pk_bf16_f32 v32, v68, v69
	v_cvt_pk_bf16_f32 v33, v70, v71
	v_mfma_f32_16x16x32_bf16 v[8:11], v[152:155], v[160:163], v[144:147]
	v_mov_b32_e32 v100, v96
	v_mov_b32_e32 v101, v97
	s_nop 1
	v_permlane16_swap_b32_e32 v98, v100
	v_permlane16_swap_b32_e32 v99, v101
	global_store_dwordx4 v[88:89], v[98:101], off
	v_cvt_pk_bf16_f32 v96, v228, v229
	v_cvt_pk_bf16_f32 v97, v230, v231
	v_mfma_f32_16x16x32_bf16 v[4:7], v[152:155], v[164:167], v[148:151]
	v_mov_b32_e32 v74, v32
	v_mov_b32_e32 v75, v33
	v_cvt_pk_bf16_f32 v32, v60, v61
	v_cvt_pk_bf16_f32 v33, v62, v63
	v_mfma_f32_16x16x32_bf16 v[0:3], v[152:155], v[168:171], v[0:3]
	v_mov_b32_e32 v104, v96
	v_mov_b32_e32 v105, v97
	s_nop 1
	v_permlane16_swap_b32_e32 v102, v104
	v_permlane16_swap_b32_e32 v103, v105
	global_store_dwordx4 v[90:91], v[102:105], off
	v_cvt_pk_bf16_f32 v96, v232, v233
	v_cvt_pk_bf16_f32 v97, v234, v235
	v_mov_b32_e32 v118, v32
	v_mov_b32_e32 v119, v33
	s_nop 1
	v_permlane16_swap_b32_e32 v116, v118
	v_permlane16_swap_b32_e32 v117, v119
	global_store_dwordx4 v[88:89], v[116:119], off offset:128
	v_cvt_pk_bf16_f32 v32, v52, v53
	v_cvt_pk_bf16_f32 v33, v54, v55
	v_mov_b32_e32 v122, v96
	v_mov_b32_e32 v123, v97
	s_nop 1
	v_permlane16_swap_b32_e32 v120, v122
	v_permlane16_swap_b32_e32 v121, v123
	global_store_dwordx4 v[94:95], v[120:123], off
	v_cvt_pk_bf16_f32 v96, v236, v237
	v_cvt_pk_bf16_f32 v97, v238, v239
	v_mov_b32_e32 v126, v32
	v_mov_b32_e32 v127, v33
	s_nop 1
	v_permlane16_swap_b32_e32 v124, v126
	v_permlane16_swap_b32_e32 v125, v127
	global_store_dwordx4 v[90:91], v[124:127], off offset:128
	v_cvt_pk_bf16_f32 v32, v44, v45
	v_cvt_pk_bf16_f32 v33, v46, v47
	v_mov_b32_e32 v112, v96
	v_mov_b32_e32 v113, v97
	s_nop 1
	v_permlane16_swap_b32_e32 v110, v112
	v_permlane16_swap_b32_e32 v111, v113
	global_store_dwordx4 v[92:93], v[110:113], off
	v_cvt_pk_bf16_f32 v96, v240, v241
	v_cvt_pk_bf16_f32 v97, v242, v243
	v_cvt_pk_bf16_f32 v56, v56, v57
	v_cvt_pk_bf16_f32 v57, v58, v59
	v_mov_b32_e32 v84, v32
	v_mov_b32_e32 v85, v33
	s_nop 1
	v_permlane16_swap_b32_e32 v82, v84
	v_permlane16_swap_b32_e32 v83, v85
	global_store_dwordx4 v[94:95], v[82:85], off offset:128
	v_cvt_pk_bf16_f32 v32, v36, v37
	v_cvt_pk_bf16_f32 v33, v38, v39
	v_cvt_pk_bf16_f32 v25, v26, v27
	v_cvt_pk_bf16_f32 v20, v20, v21
	v_cvt_pk_bf16_f32 v21, v22, v23
	v_cvt_pk_bf16_f32 v16, v16, v17
	v_cvt_pk_bf16_f32 v17, v18, v19
	v_cvt_pk_bf16_f32 v12, v12, v13
	v_cvt_pk_bf16_f32 v13, v14, v15
	v_cvt_pk_bf16_f32 v8, v8, v9
	v_cvt_pk_bf16_f32 v9, v10, v11
	v_cvt_pk_bf16_f32 v4, v4, v5
	v_cvt_pk_bf16_f32 v5, v6, v7
	v_cvt_pk_bf16_f32 v0, v0, v1
	v_cvt_pk_bf16_f32 v1, v2, v3
	v_mov_b32_e32 v34, v96
	v_mov_b32_e32 v35, v97
	v_mov_b32_e32 v42, v80
	v_mov_b32_e32 v43, v81
	v_mov_b32_e32 v50, v72
	v_mov_b32_e32 v51, v73
	v_mov_b32_e32 v106, v64
	v_mov_b32_e32 v107, v65
	s_nop 1
	v_permlane16_swap_b32_e32 v106, v108
	v_permlane16_swap_b32_e32 v107, v109
	global_store_dwordx4 v[92:93], v[106:109], off offset:64
	v_mov_b32_e32 v36, v56
	v_mov_b32_e32 v37, v57
	s_nop 1
	v_permlane16_swap_b32_e32 v34, v36
	v_permlane16_swap_b32_e32 v35, v37
	global_store_dwordx4 v[88:89], v[34:37], off offset:64
	v_mov_b32_e32 v44, v48
	v_mov_b32_e32 v45, v49
	s_nop 1
	v_permlane16_swap_b32_e32 v42, v44
	v_permlane16_swap_b32_e32 v43, v45
	global_store_dwordx4 v[90:91], v[42:45], off offset:64
	v_mov_b32_e32 v52, v40
	v_mov_b32_e32 v53, v41
	s_nop 1
	v_permlane16_swap_b32_e32 v50, v52
	v_permlane16_swap_b32_e32 v51, v53
	global_store_dwordx4 v[94:95], v[50:53], off offset:64
	v_mov_b32_e32 v76, v32
	v_mov_b32_e32 v77, v33
	s_nop 1
	v_permlane16_swap_b32_e32 v74, v76
	v_permlane16_swap_b32_e32 v75, v77
	global_store_dwordx4 v[92:93], v[74:77], off offset:128
	v_mov_b32_e32 v34, v28
	v_mov_b32_e32 v35, v29
	v_mov_b32_e32 v42, v24
	v_mov_b32_e32 v43, v25
	v_mov_b32_e32 v50, v20
	v_mov_b32_e32 v51, v21
	v_mov_b32_e32 v58, v16
	v_mov_b32_e32 v59, v17
	v_mov_b32_e32 v36, v12
	v_mov_b32_e32 v37, v13
	s_nop 1
	v_permlane16_swap_b32_e32 v34, v36
	v_permlane16_swap_b32_e32 v35, v37
	global_store_dwordx4 v[88:89], v[34:37], off offset:192
	v_mov_b32_e32 v44, v8
	v_mov_b32_e32 v45, v9
	s_nop 1
	v_permlane16_swap_b32_e32 v42, v44
	v_permlane16_swap_b32_e32 v43, v45
	global_store_dwordx4 v[90:91], v[42:45], off offset:192
	v_mov_b32_e32 v52, v4
	v_mov_b32_e32 v53, v5
	s_nop 1
	v_permlane16_swap_b32_e32 v50, v52
	v_permlane16_swap_b32_e32 v51, v53
	global_store_dwordx4 v[94:95], v[50:53], off offset:192
	v_mov_b32_e32 v60, v0
	v_mov_b32_e32 v61, v1
	s_nop 1
	v_permlane16_swap_b32_e32 v58, v60
	v_permlane16_swap_b32_e32 v59, v61
	global_store_dwordx4 v[92:93], v[58:61], off offset:192

; template <int N> DI void wait_vm() { asm volatile("s_waitcnt vmcnt(%0)" ::"n"(N) : "memory"); }
; template <int BM, class Epi>
; DI void gemm_dma(const u16* __restrict__ X, long ldx, const u16* __restrict__ W, long ldw, int K, char* smem,
;                  int m0, int n0, const Epi& epi) {
;     ...
;   do {
;     if (kt + D - 2 < nk) wait_vm<PW * (D - 2)>(); else wait_vm<0>();
;     __syncthreads();
;     if (kt + D - 1 < nk) GD_ISSUE(nxt)
;     nxt = (nxt + 1 == D) ? 0 : nxt + 1;
;     const char* base = smem + cur * STG;
;     cur = (cur + 1 == D) ? 0 : cur + 1;
;     bf16x8 xf[MT];
; #pragma unroll
;     for (int i = 0; i < MT; ++i) xf[i] = *(const bf16x8*)(base + (xrow0 + i * 16) * 64 + rd);
; #pragma unroll
;     for (int nh = 0; nh < NT / 4; ++nh) {
;       bf16x8 wf[4];
; #pragma unroll
;       for (int i = 0; i < 4; ++i) wf[i] = *(const bf16x8*)(base + BM * 64 + (wrow0 + (nh * 4 + i) * 16) * 64 + rd);
; #pragma unroll
;       for (int i = 0; i < 4; ++i)
; #pragma unroll
;         for (int mt = 0; mt < MT; ++mt)
;           acc[nh * 4 + i][mt] = __builtin_amdgcn_mfma_f32_16x16x32_bf16(wf[i], xf[mt], acc[nh * 4 + i][mt], 0, 0, 0);
;     }
;   } while (++kt < nk);
;     ...
;   epi.run(acc, m0 + xrow0 + lr, n0 + wrow0 + 4 * g);
.LBB0_1139:
	s_mul_i32 s12, s10, 0x6000
	v_lshl_add_u64 v[196:197], v[130:131], 0, s[42:43]
	s_waitcnt vmcnt(6)
	s_barrier
	s_mul_i32 s98, s11, 0x6000
	v_or_b32_e32 v137, s98, v134
	v_add_u32_e32 v150, v137, v136
	ds_read_b128 v[138:141], v150
	ds_read_b128 v[142:145], v150 offset:1024
	ds_read_b128 v[146:149], v150 offset:2048
	ds_read_b128 v[150:153], v150 offset:3072
	ds_read_b128 v[154:157], v137 offset:16384
	ds_read_b128 v[158:161], v137 offset:17408
	ds_read_b128 v[162:165], v137 offset:18432
	ds_read_b128 v[166:169], v137 offset:19456
	ds_read_b128 v[226:229], v137 offset:20480
	ds_read_b128 v[230:233], v137 offset:21504
	ds_read_b128 v[234:237], v137 offset:22528
	ds_read_b128 v[238:241], v137 offset:23552
	s_add_i32 s13, s12, s8
	s_mov_b32 m0, s13
	s_nop 0
	global_load_lds_dwordx4 v[196:197], off
	v_lshl_add_u64 v[224:225], v[196:197], 0, s[58:59]
	s_add_i32 s14, s13, 0x400
	s_mov_b32 m0, s14
	s_nop 0
	global_load_lds_dwordx4 v[224:225], off
	v_lshl_add_u64 v[224:225], v[196:197], 0, s[16:17]
	s_add_i32 s14, s13, 0x800
	s_mov_b32 m0, s14
	s_nop 0
	global_load_lds_dwordx4 v[224:225], off
	v_lshl_add_u64 v[196:197], v[196:197], 0, s[18:19]
	s_addk_i32 s13, 0xc00
	s_mov_b32 m0, s13
	s_nop 0
	global_load_lds_dwordx4 v[196:197], off
	s_add_i32 s12, s12, s9
	v_lshl_add_u64 v[194:195], v[128:129], 0, s[42:43]
	s_mov_b32 m0, s12
	s_nop 0
	global_load_lds_dwordx4 v[194:195], off
	s_addk_i32 s12, 0x400
	v_lshl_add_u64 v[194:195], v[194:195], 0, s[58:59]
	s_mov_b32 m0, s12
	s_nop 0
	global_load_lds_dwordx4 v[194:195], off
	s_waitcnt lgkmcnt(7)
	v_mfma_f32_16x16x32_bf16 v[124:127], v[154:157], v[138:141], v[124:127]
	s_add_i32 s10, s10, 1
	s_add_i32 s11, s11, 1
	s_cmp_lg_u32 s10, 3
	v_mfma_f32_16x16x32_bf16 v[120:123], v[154:157], v[142:145], v[120:123]
	s_cselect_b32 s10, s10, 0
	s_cmp_lg_u32 s11, 3
	s_cselect_b32 s11, s11, 0
	v_mfma_f32_16x16x32_bf16 v[116:119], v[154:157], v[146:149], v[116:119]
	s_add_u32 s42, s42, 64
	s_addc_u32 s43, s43, 0
	s_cmpk_lg_i32 s42, 0xf80
	v_mfma_f32_16x16x32_bf16 v[112:115], v[154:157], v[150:153], v[112:115]
	s_waitcnt lgkmcnt(6)
	v_mfma_f32_16x16x32_bf16 v[108:111], v[158:161], v[138:141], v[108:111]
	v_mfma_f32_16x16x32_bf16 v[104:107], v[158:161], v[142:145], v[104:107]
	v_mfma_f32_16x16x32_bf16 v[100:103], v[158:161], v[146:149], v[100:103]
	v_mfma_f32_16x16x32_bf16 v[96:99], v[158:161], v[150:153], v[96:99]
	s_waitcnt lgkmcnt(5)
	v_mfma_f32_16x16x32_bf16 v[92:95], v[162:165], v[138:141], v[92:95]
	v_mfma_f32_16x16x32_bf16 v[88:91], v[162:165], v[142:145], v[88:91]
	v_mfma_f32_16x16x32_bf16 v[84:87], v[162:165], v[146:149], v[84:87]
	v_mfma_f32_16x16x32_bf16 v[80:83], v[162:165], v[150:153], v[80:83]
	s_waitcnt lgkmcnt(4)
	v_mfma_f32_16x16x32_bf16 v[76:79], v[166:169], v[138:141], v[76:79]
	v_mfma_f32_16x16x32_bf16 v[72:75], v[166:169], v[142:145], v[72:75]
	v_mfma_f32_16x16x32_bf16 v[68:71], v[166:169], v[146:149], v[68:71]
	v_mfma_f32_16x16x32_bf16 v[64:67], v[166:169], v[150:153], v[64:67]
	s_waitcnt lgkmcnt(3)
	v_mfma_f32_16x16x32_bf16 v[60:63], v[226:229], v[138:141], v[60:63]
	v_mfma_f32_16x16x32_bf16 v[56:59], v[226:229], v[142:145], v[56:59]
	v_mfma_f32_16x16x32_bf16 v[52:55], v[226:229], v[146:149], v[52:55]
	v_mfma_f32_16x16x32_bf16 v[48:51], v[226:229], v[150:153], v[48:51]
	s_waitcnt lgkmcnt(2)
	v_mfma_f32_16x16x32_bf16 v[44:47], v[230:233], v[138:141], v[44:47]
	v_mfma_f32_16x16x32_bf16 v[40:43], v[230:233], v[142:145], v[40:43]
	v_mfma_f32_16x16x32_bf16 v[36:39], v[230:233], v[146:149], v[36:39]
	v_mfma_f32_16x16x32_bf16 v[32:35], v[230:233], v[150:153], v[32:35]
	s_waitcnt lgkmcnt(1)
	v_mfma_f32_16x16x32_bf16 v[28:31], v[234:237], v[138:141], v[28:31]
	v_mfma_f32_16x16x32_bf16 v[24:27], v[234:237], v[142:145], v[24:27]
	v_mfma_f32_16x16x32_bf16 v[20:23], v[234:237], v[146:149], v[20:23]
	v_mfma_f32_16x16x32_bf16 v[16:19], v[234:237], v[150:153], v[16:19]
	s_waitcnt lgkmcnt(0)
	v_mfma_f32_16x16x32_bf16 v[12:15], v[238:241], v[138:141], v[12:15]
	v_mfma_f32_16x16x32_bf16 v[8:11], v[238:241], v[142:145], v[8:11]
	v_mfma_f32_16x16x32_bf16 v[4:7], v[238:241], v[146:149], v[4:7]
	v_mfma_f32_16x16x32_bf16 v[0:3], v[238:241], v[150:153], v[0:3]
	s_cbranch_scc1 .LBB0_1139
	v_add_u32_e32 v180, v134, v136
	v_or_b32_e32 v148, 0x10000, v134
	v_or_b32_e32 v152, 0x10400, v134
	v_or_b32_e32 v156, 0x10800, v134
	v_or_b32_e32 v160, 0x10c00, v134
	s_waitcnt vmcnt(6)
	s_barrier
	ds_read_b128 v[128:131], v180 offset:49152
	ds_read_b128 v[136:139], v180 offset:50176
	ds_read_b128 v[140:143], v180 offset:51200
	ds_read_b128 v[144:147], v180 offset:52224
	ds_read_b128 v[148:151], v148
	ds_read_b128 v[152:155], v152
	ds_read_b128 v[156:159], v156
	ds_read_b128 v[160:163], v160
	s_waitcnt lgkmcnt(3)
	v_mfma_f32_16x16x32_bf16 v[124:127], v[148:151], v[128:131], v[124:127]
	v_readlane_b32 s8, v252, 33
	v_readlane_b32 s9, v252, 34
	s_lshl_b32 s7, s7, 8
	v_mfma_f32_16x16x32_bf16 v[120:123], v[148:151], v[136:139], v[120:123]
	v_lshl_or_b32 v182, v132, 3, s7
	v_mfma_f32_16x16x32_bf16 v[116:119], v[148:151], v[140:143], v[116:119]
	v_mfma_f32_16x16x32_bf16 v[112:115], v[148:151], v[144:147], v[112:115]
	s_waitcnt lgkmcnt(2)
	v_mfma_f32_16x16x32_bf16 v[108:111], v[152:155], v[128:131], v[108:111]
	v_mfma_f32_16x16x32_bf16 v[104:107], v[152:155], v[136:139], v[104:107]
	v_mfma_f32_16x16x32_bf16 v[100:103], v[152:155], v[140:143], v[100:103]
	v_mfma_f32_16x16x32_bf16 v[96:99], v[152:155], v[144:147], v[96:99]
	s_waitcnt lgkmcnt(1)
	v_mfma_f32_16x16x32_bf16 v[92:95], v[156:159], v[128:131], v[92:95]
	v_mfma_f32_16x16x32_bf16 v[148:151], v[156:159], v[136:139], v[88:91]
	v_mfma_f32_16x16x32_bf16 v[84:87], v[156:159], v[140:143], v[84:87]
	s_nop 1
	v_or_b32_e32 v88, 0x11c00, v134
	ds_read_b128 v[88:91], v88
	v_mfma_f32_16x16x32_bf16 v[152:155], v[156:159], v[144:147], v[80:83]
	s_waitcnt lgkmcnt(1)
	v_mfma_f32_16x16x32_bf16 v[76:79], v[160:163], v[128:131], v[76:79]
	s_nop 0
	v_or_b32_e32 v80, 0x11800, v134
	ds_read_b128 v[80:83], v80
	v_mfma_f32_16x16x32_bf16 v[156:159], v[160:163], v[136:139], v[72:75]
	v_mfma_f32_16x16x32_bf16 v[68:71], v[160:163], v[140:143], v[68:71]
	s_nop 1
	v_or_b32_e32 v72, 0x11400, v134
	ds_read_b128 v[72:75], v72
	v_mfma_f32_16x16x32_bf16 v[160:163], v[160:163], v[144:147], v[64:67]
	s_nop 2
	v_or_b32_e32 v64, 0x11000, v134
	ds_read_b128 v[64:67], v64
	s_waitcnt lgkmcnt(1)
	v_mfma_f32_16x16x32_bf16 v[44:47], v[72:75], v[128:131], v[44:47]
	s_waitcnt vmcnt(0)
	s_waitcnt lgkmcnt(0)
	s_barrier
; DI void st_bf4(u16* p, float a, float b, float c, float d) { *(uint2*)p = make_uint2(pk2(a, b), pk2(c, d)); }
; template <int BM, class Epi>
; DI void gemm_dma(const u16* __restrict__ X, long ldx, const u16* __restrict__ W, long ldw, int K, char* smem,
;                  int m0, int n0, const Epi& epi) {
;     ...
;     for (int i = 0; i < MT; ++i) xf[i] = *(const bf16x8*)(base + (xrow0 + i * 16) * 64 + rd);
; #pragma unroll
;     for (int nh = 0; nh < NT / 4; ++nh) {
;       bf16x8 wf[4];
; #pragma unroll
;       for (int i = 0; i < 4; ++i) wf[i] = *(const bf16x8*)(base + BM * 64 + (wrow0 + (nh * 4 + i) * 16) * 64 + rd);
; #pragma unroll
;       for (int i = 0; i < 4; ++i)
; #pragma unroll
;         for (int mt = 0; mt < MT; ++mt)
;           acc[nh * 4 + i][mt] = __builtin_amdgcn_mfma_f32_16x16x32_bf16(wf[i], xf[mt], acc[nh * 4 + i][mt], 0, 0, 0);
;   template <int NT, int MT> DI void run(f32x4 (&acc)[NT][MT], int mb, int nb) const {
; #pragma unroll
;     for (int nt = 0; nt < NT; ++nt)
; #pragma unroll
;       for (int mt = 0; mt < MT; ++mt) {
;         f32x4 v = acc[nt][mt];
;         st_bf4(C + (size_t)(mb + mt * 16) * ldc + nb + nt * 16, v[0], v[1], v[2], v[3]);
;       }
;   }
	v_mfma_f32_16x16x32_bf16 v[60:63], v[64:67], v[128:131], v[60:63]
	v_mfma_f32_16x16x32_bf16 v[164:167], v[64:67], v[136:139], v[56:59]
	v_mfma_f32_16x16x32_bf16 v[52:55], v[64:67], v[140:143], v[52:55]
	v_mfma_f32_16x16x32_bf16 v[168:171], v[64:67], v[144:147], v[48:51]
	v_mfma_f32_16x16x32_bf16 v[172:175], v[72:75], v[136:139], v[40:43]
	v_mfma_f32_16x16x32_bf16 v[36:39], v[72:75], v[140:143], v[36:39]
	v_mfma_f32_16x16x32_bf16 v[176:179], v[72:75], v[144:147], v[32:35]
	v_mfma_f32_16x16x32_bf16 v[28:31], v[80:83], v[128:131], v[28:31]
	v_mfma_f32_16x16x32_bf16 v[24:27], v[80:83], v[136:139], v[24:27]
	v_mfma_f32_16x16x32_bf16 v[20:23], v[80:83], v[140:143], v[20:23]
	v_mfma_f32_16x16x32_bf16 v[16:19], v[80:83], v[144:147], v[16:19]
	v_mfma_f32_16x16x32_bf16 v[12:15], v[88:91], v[128:131], v[12:15]
	v_mfma_f32_16x16x32_bf16 v[8:11], v[88:91], v[136:139], v[8:11]
	v_mfma_f32_16x16x32_bf16 v[4:7], v[88:91], v[140:143], v[4:7]
	v_mfma_f32_16x16x32_bf16 v[0:3], v[88:91], v[144:147], v[0:3]
	ds_read_b128 v[128:131], v180
	ds_read_b128 v[136:139], v180 offset:1024
	ds_read_b128 v[140:143], v180 offset:2048
	ds_read_b128 v[144:147], v180 offset:3072
	ds_read_b128 v[32:35], v134 offset:16384
	ds_read_b128 v[40:43], v134 offset:17408
	ds_read_b128 v[48:51], v134 offset:18432
	ds_read_b128 v[186:189], v134 offset:19456
	s_waitcnt lgkmcnt(2)
	v_mfma_f32_16x16x32_bf16 v[108:111], v[40:43], v[128:131], v[108:111]
	v_mfma_f32_16x16x32_bf16 v[104:107], v[40:43], v[136:139], v[104:107]
	v_mfma_f32_16x16x32_bf16 v[100:103], v[40:43], v[140:143], v[100:103]
	s_nop 5
	v_cvt_pk_bf16_f32 v108, v108, v109
	v_cvt_pk_bf16_f32 v109, v110, v111
	v_cvt_pk_bf16_f32 v104, v104, v105
	v_mfma_f32_16x16x32_bf16 v[190:193], v[40:43], v[144:147], v[96:99]
	v_cvt_pk_bf16_f32 v105, v106, v107
	v_cvt_pk_bf16_f32 v100, v100, v101
	v_cvt_pk_bf16_f32 v101, v102, v103
	s_waitcnt lgkmcnt(1)
	v_mfma_f32_16x16x32_bf16 v[80:83], v[48:51], v[136:139], v[148:151]
	v_mfma_f32_16x16x32_bf16 v[64:67], v[48:51], v[144:147], v[152:155]
	s_waitcnt lgkmcnt(0)
	v_mfma_f32_16x16x32_bf16 v[40:43], v[186:189], v[140:143], v[68:71]
	s_nop 2
	ds_read_b128 v[68:71], v134 offset:20480
	ds_read_b128 v[96:99], v134 offset:21504
	ds_read_b128 v[148:151], v134 offset:22528
	ds_read_b128 v[152:155], v134 offset:23552
	v_cvt_pk_bf16_f32 v80, v80, v81
	v_cvt_pk_bf16_f32 v81, v82, v83
	v_mfma_f32_16x16x32_bf16 v[88:91], v[48:51], v[128:131], v[92:95]
	v_cvt_pk_bf16_f32 v64, v64, v65
	v_cvt_pk_bf16_f32 v65, v66, v67
	v_cvt_pk_bf16_f32 v40, v40, v41
	v_mfma_f32_16x16x32_bf16 v[56:59], v[186:189], v[128:131], v[76:79]
	v_cvt_pk_bf16_f32 v41, v42, v43
	s_nop 2
	v_cvt_pk_bf16_f32 v88, v88, v89
	v_cvt_pk_bf16_f32 v89, v90, v91
	s_waitcnt lgkmcnt(3)
	v_mfma_f32_16x16x32_bf16 v[92:95], v[68:71], v[128:131], v[60:63]
	v_mfma_f32_16x16x32_bf16 v[76:79], v[68:71], v[140:143], v[52:55]
	v_cvt_pk_bf16_f32 v56, v56, v57
	v_cvt_pk_bf16_f32 v57, v58, v59
	s_waitcnt lgkmcnt(2)
	v_mfma_f32_16x16x32_bf16 v[60:63], v[96:99], v[128:131], v[44:47]
	v_mfma_f32_16x16x32_bf16 v[52:55], v[96:99], v[136:139], v[172:175]
	v_mfma_f32_16x16x32_bf16 v[44:47], v[96:99], v[140:143], v[36:39]
	v_mfma_f32_16x16x32_bf16 v[36:39], v[96:99], v[144:147], v[176:179]
	v_lshl_add_u32 v96, s40, 8, v135
	v_mfma_f32_16x16x32_bf16 v[124:127], v[32:35], v[128:131], v[124:127]
	s_waitcnt lgkmcnt(1)
	v_mfma_f32_16x16x32_bf16 v[28:31], v[148:151], v[128:131], v[28:31]
	s_waitcnt lgkmcnt(0)
	v_mfma_f32_16x16x32_bf16 v[12:15], v[152:155], v[128:131], v[12:15]
	v_or_b32_e32 v128, v96, v133
	v_ashrrev_i32_e32 v129, 31, v128
	v_lshlrev_b64 v[96:97], 11, v[128:129]
	v_lshl_add_u64 v[96:97], s[8:9], 0, v[96:97]
	v_bfe_u32 v172, v185, 4, 1
	v_mad_u32_u24 v182, v172, 24, v182
	v_lshl_add_u64 v[96:97], v[96:97], 0, v[182:183]
	v_cvt_pk_bf16_f32 v98, v124, v125
	v_cvt_pk_bf16_f32 v99, v126, v127
	v_mfma_f32_16x16x32_bf16 v[120:123], v[32:35], v[136:139], v[120:123]
	v_mov_b32_e32 v172, v98
	v_mov_b32_e32 v173, v99
	v_or_b32_e32 v98, 16, v128
	v_ashrrev_i32_e32 v99, 31, v98
	v_lshlrev_b64 v[98:99], 11, v[98:99]
	v_lshl_add_u64 v[98:99], s[8:9], 0, v[98:99]
	v_lshl_add_u64 v[98:99], v[98:99], 0, v[182:183]
	s_nop 1
	v_cvt_pk_bf16_f32 v120, v120, v121
	v_cvt_pk_bf16_f32 v121, v122, v123
	v_mfma_f32_16x16x32_bf16 v[116:119], v[32:35], v[140:143], v[116:119]
	v_mov_b32_e32 v176, v120
	v_mov_b32_e32 v177, v121
	v_or_b32_e32 v120, 32, v128
	v_ashrrev_i32_e32 v121, 31, v120
	v_lshlrev_b64 v[120:121], 11, v[120:121]
	v_lshl_add_u64 v[120:121], s[8:9], 0, v[120:121]
	v_lshl_add_u64 v[120:121], v[120:121], 0, v[182:183]
	s_nop 1
	v_cvt_pk_bf16_f32 v116, v116, v117
	v_cvt_pk_bf16_f32 v117, v118, v119
	v_mfma_f32_16x16x32_bf16 v[112:115], v[32:35], v[144:147], v[112:115]
	v_mov_b32_e32 v194, v116
	v_mov_b32_e32 v195, v117
	v_or_b32_e32 v116, 48, v128
	v_ashrrev_i32_e32 v117, 31, v116
	v_mfma_f32_16x16x32_bf16 v[32:35], v[186:189], v[144:147], v[160:163]
	v_lshlrev_b64 v[116:117], 11, v[116:117]
	v_lshl_add_u64 v[116:117], s[8:9], 0, v[116:117]
	v_lshl_add_u64 v[116:117], v[116:117], 0, v[182:183]
	v_mfma_f32_16x16x32_bf16 v[72:75], v[48:51], v[140:143], v[84:87]
	v_cvt_pk_bf16_f32 v112, v112, v113
	s_nop 2
	v_cvt_pk_bf16_f32 v32, v32, v33
	v_cvt_pk_bf16_f32 v33, v34, v35
	v_mfma_f32_16x16x32_bf16 v[84:87], v[68:71], v[136:139], v[164:167]
	v_mov_b32_e32 v130, v32
	v_mov_b32_e32 v131, v33
	v_cvt_pk_bf16_f32 v32, v92, v93
	v_cvt_pk_bf16_f32 v33, v94, v95
; DI void st_bf4(u16* p, float a, float b, float c, float d) { *(uint2*)p = make_uint2(pk2(a, b), pk2(c, d)); }
;   template <int NT, int MT> DI void run(f32x4 (&acc)[NT][MT], int mb, int nb) const {
; #pragma unroll
;     for (int nt = 0; nt < NT; ++nt)
; #pragma unroll
;       for (int mt = 0; mt < MT; ++mt) {
;         f32x4 v = acc[nt][mt];
;         st_bf4(C + (size_t)(mb + mt * 16) * ldc + nb + nt * 16, v[0], v[1], v[2], v[3]);
;       }
;   }
	v_mfma_f32_16x16x32_bf16 v[68:71], v[68:71], v[144:147], v[168:171]
	v_mov_b32_e32 v160, v32
	v_mov_b32_e32 v161, v33
	s_nop 2
	v_cvt_pk_bf16_f32 v32, v84, v85
	v_cvt_pk_bf16_f32 v33, v86, v87
	v_mov_b32_e32 v224, v32
	v_mov_b32_e32 v225, v33
	v_cvt_pk_bf16_f32 v32, v76, v77
	v_cvt_pk_bf16_f32 v33, v78, v79
	v_mfma_f32_16x16x32_bf16 v[48:51], v[186:189], v[136:139], v[156:159]
	v_mov_b32_e32 v164, v32
	v_mov_b32_e32 v165, v33
	v_cvt_pk_bf16_f32 v32, v68, v69
	v_cvt_pk_bf16_f32 v33, v70, v71
	v_mfma_f32_16x16x32_bf16 v[24:27], v[148:151], v[136:139], v[24:27]
	v_mov_b32_e32 v168, v32
	v_mov_b32_e32 v169, v33
	v_cvt_pk_bf16_f32 v32, v60, v61
	v_cvt_pk_bf16_f32 v33, v62, v63
	v_mfma_f32_16x16x32_bf16 v[20:23], v[148:151], v[140:143], v[20:23]
	v_mov_b32_e32 v162, v32
	v_mov_b32_e32 v163, v33
	s_nop 1
	v_permlane16_swap_b32_e32 v160, v162
	v_permlane16_swap_b32_e32 v161, v163
	global_store_dwordx4 v[96:97], v[160:163], off offset:128
	v_cvt_pk_bf16_f32 v32, v52, v53
	v_cvt_pk_bf16_f32 v33, v54, v55
	v_mfma_f32_16x16x32_bf16 v[16:19], v[148:151], v[144:147], v[16:19]
	v_mov_b32_e32 v226, v32
	v_mov_b32_e32 v227, v33
	s_nop 1
	v_permlane16_swap_b32_e32 v224, v226
	v_permlane16_swap_b32_e32 v225, v227
	global_store_dwordx4 v[98:99], v[224:227], off offset:128
	v_cvt_pk_bf16_f32 v32, v44, v45
	v_cvt_pk_bf16_f32 v33, v46, v47
	v_mfma_f32_16x16x32_bf16 v[8:11], v[152:155], v[136:139], v[8:11]
	v_cvt_pk_bf16_f32 v113, v114, v115
	v_mov_b32_e32 v196, v100
	v_mov_b32_e32 v197, v101
	s_nop 1
	v_permlane16_swap_b32_e32 v194, v196
	v_permlane16_swap_b32_e32 v195, v197
	global_store_dwordx4 v[120:121], v[194:197], off
	v_cvt_pk_bf16_f32 v100, v190, v191
	v_mfma_f32_16x16x32_bf16 v[4:7], v[152:155], v[140:143], v[4:7]
	v_cvt_pk_bf16_f32 v101, v192, v193
	v_cvt_pk_bf16_f32 v72, v72, v73
	v_cvt_pk_bf16_f32 v73, v74, v75
	v_mfma_f32_16x16x32_bf16 v[0:3], v[152:155], v[144:147], v[0:3]
	v_cvt_pk_bf16_f32 v48, v48, v49
	v_cvt_pk_bf16_f32 v49, v50, v51
	v_mov_b32_e32 v166, v32
	v_mov_b32_e32 v167, v33
	s_nop 1
	v_permlane16_swap_b32_e32 v164, v166
	v_permlane16_swap_b32_e32 v165, v167
	global_store_dwordx4 v[120:121], v[164:167], off offset:128
	v_cvt_pk_bf16_f32 v32, v36, v37
	v_cvt_pk_bf16_f32 v33, v38, v39
	v_cvt_pk_bf16_f32 v28, v28, v29
	v_cvt_pk_bf16_f32 v29, v30, v31
	v_cvt_pk_bf16_f32 v24, v24, v25
	v_cvt_pk_bf16_f32 v25, v26, v27
	v_cvt_pk_bf16_f32 v20, v20, v21
	v_cvt_pk_bf16_f32 v21, v22, v23
	v_cvt_pk_bf16_f32 v16, v16, v17
	v_cvt_pk_bf16_f32 v17, v18, v19
	v_cvt_pk_bf16_f32 v12, v12, v13
	v_cvt_pk_bf16_f32 v13, v14, v15
	v_cvt_pk_bf16_f32 v8, v8, v9
	v_cvt_pk_bf16_f32 v9, v10, v11
	v_cvt_pk_bf16_f32 v4, v4, v5
	v_cvt_pk_bf16_f32 v5, v6, v7
	v_cvt_pk_bf16_f32 v0, v0, v1
	v_cvt_pk_bf16_f32 v1, v2, v3
	v_mov_b32_e32 v138, v112
	v_mov_b32_e32 v139, v113
	v_mov_b32_e32 v174, v108
	v_mov_b32_e32 v175, v109
	s_nop 1
	v_permlane16_swap_b32_e32 v172, v174
	v_permlane16_swap_b32_e32 v173, v175
	global_store_dwordx4 v[96:97], v[172:175], off
	v_mov_b32_e32 v178, v104
	v_mov_b32_e32 v179, v105
	s_nop 1
	v_permlane16_swap_b32_e32 v176, v178
	v_permlane16_swap_b32_e32 v177, v179
	global_store_dwordx4 v[98:99], v[176:179], off
	v_mov_b32_e32 v140, v100
	v_mov_b32_e32 v141, v101
	s_nop 1
	v_permlane16_swap_b32_e32 v138, v140
	v_permlane16_swap_b32_e32 v139, v141
	global_store_dwordx4 v[116:117], v[138:141], off
	s_nop 1
	v_mov_b32_e32 v138, v88
	v_mov_b32_e32 v139, v89
	v_mov_b32_e32 v142, v80
	v_mov_b32_e32 v143, v81
	v_mov_b32_e32 v146, v72
	v_mov_b32_e32 v147, v73
	v_mov_b32_e32 v128, v64
	v_mov_b32_e32 v129, v65
	s_nop 1
	v_permlane16_swap_b32_e32 v128, v130
	v_permlane16_swap_b32_e32 v129, v131
	global_store_dwordx4 v[116:117], v[128:131], off offset:64
	v_mov_b32_e32 v140, v56
	v_mov_b32_e32 v141, v57
	s_nop 1
	v_permlane16_swap_b32_e32 v138, v140
	v_permlane16_swap_b32_e32 v139, v141
	global_store_dwordx4 v[96:97], v[138:141], off offset:64
	v_mov_b32_e32 v144, v48
	v_mov_b32_e32 v145, v49
	s_nop 1
	v_permlane16_swap_b32_e32 v142, v144
	v_permlane16_swap_b32_e32 v143, v145
	global_store_dwordx4 v[98:99], v[142:145], off offset:64
	v_mov_b32_e32 v148, v40
	v_mov_b32_e32 v149, v41
	s_nop 1
	v_permlane16_swap_b32_e32 v146, v148
	v_permlane16_swap_b32_e32 v147, v149
	global_store_dwordx4 v[120:121], v[146:149], off offset:64
	v_mov_b32_e32 v170, v32
	v_mov_b32_e32 v171, v33
	s_nop 1
	v_permlane16_swap_b32_e32 v168, v170
	v_permlane16_swap_b32_e32 v169, v171
	global_store_dwordx4 v[116:117], v[168:171], off offset:128
	v_mov_b32_e32 v128, v28
	v_mov_b32_e32 v129, v29
	v_mov_b32_e32 v138, v24
	v_mov_b32_e32 v139, v25
	v_mov_b32_e32 v142, v20
	v_mov_b32_e32 v143, v21
	v_mov_b32_e32 v146, v16
	v_mov_b32_e32 v147, v17
	v_mov_b32_e32 v130, v12
	v_mov_b32_e32 v131, v13
	s_nop 1
	v_permlane16_swap_b32_e32 v128, v130
	v_permlane16_swap_b32_e32 v129, v131
	global_store_dwordx4 v[96:97], v[128:131], off offset:192
	v_mov_b32_e32 v140, v8
	v_mov_b32_e32 v141, v9
	s_nop 1
	v_permlane16_swap_b32_e32 v138, v140
	v_permlane16_swap_b32_e32 v139, v141
	global_store_dwordx4 v[98:99], v[138:141], off offset:192
	v_mov_b32_e32 v144, v4
	v_mov_b32_e32 v145, v5
	s_nop 1
	v_permlane16_swap_b32_e32 v142, v144
	v_permlane16_swap_b32_e32 v143, v145
	global_store_dwordx4 v[120:121], v[142:145], off offset:192
	v_mov_b32_e32 v148, v0
	v_mov_b32_e32 v149, v1
	s_nop 1
	v_permlane16_swap_b32_e32 v146, v148
	v_permlane16_swap_b32_e32 v147, v149
	global_store_dwordx4 v[116:117], v[146:149], off offset:192
	s_branch .LBB0_1132
